# baseline (speedup 1.0000x reference)
; #define PG8_STAGE(bufoff, gbase, voff) do { _Pragma("unroll") for (int _i = 0; _i < 2; ++_i) \
;         __builtin_amdgcn_global_load_lds((const unsigned*)((const char*)(gbase) + (voff)[_i]), (PG8_LAS unsigned*)(lds + (bufoff) + ldsw + _i * 8192), 16, 0, 0); } while (0)
; #define PG8_LDA(dst, b, h) do { _Pragma("unroll") for (int m = 0; m < 4; ++m) _Pragma("unroll") for (int k = 0; k < 2; ++k) dst[m][k] = *(const PG8_LAS bf16x8*)(lds + PG8_SA(b, h) + aoff + m * 2048 + k * 1024); } while (0)
; #define PG8_LDB(dst, b, h) do { _Pragma("unroll") for (int n = 0; n < 2; ++n) _Pragma("unroll") for (int k = 0; k < 2; ++k) dst[n][k] = *(const PG8_LAS bf16x8*)(lds + PG8_SB(b, h) + boff + n * 2048 + k * 1024); } while (0)
; #define PG8_WAIT_V(n) asm volatile("s_waitcnt vmcnt(" #n ")" ::: "memory")
; #define PG8_WAIT_L(n) asm volatile("s_waitcnt lgkmcnt(" #n ")" ::: "memory")
; #define PG8_BAR __builtin_amdgcn_s_barrier()
; #define PG8_SCHED __builtin_amdgcn_sched_barrier(0)
; template <class Epi, class Sched, bool ALIGN_EPI = false, bool SP2 = false>
; __device__ __forceinline__ void gemm_phase(PG8_LAS unsigned char* lds, const Gemm g, const Sched& S, const Epi& E) {
;     ...
;         const char* nA = has_next ? (const char*)g.A + (size_t)nxt.pm * tstep : cA; const char* nB = has_next ? (const char*)g.Bt + (size_t)nxt.pn * tstep : cB;
;         for (int t = 0; t < nt; t += 2) {
;             if constexpr (Epi::MID_HOOK) { if (t == Epi::MID_T) E.mid(acc, cur, wr, wc, fr, fq); }
;             const bool last = (t == nt - 2);
;             const char* a1 = cA + (size_t)(t + 1) * kstep;
;             const char* a2 = last ? nA : cA + (size_t)(t + 2) * kstep; const char* b2 = last ? nB : cB + (size_t)(t + 2) * kstep;
;             const char* a3 = a2 + kstep; const char* b3 = b2 + kstep;
;             if (last && has_next) S.a_ready(nxt);
;             if constexpr (SP2) {
;             PG8_LDB(B0, 0, 0); PG8_LDB(B1, 0, 1); PG8_SCHED; PG8_LDA(At, 0, 0); PG8_STAGE(PG8_SA(1, 1), a1 + hstep, voffA);
;             PG8_WAIT_V(8); PG8_WAIT_L(0); PG8_BAR; PG8_MMA(0, 0, At, B0); PG8_MMA(0, 1, At, B1); PG8_BAR; PG8_SCHED;
;             PG8_LDA(At, 0, 1); PG8_STAGE(PG8_SB(0, 0), b2, voffB); PG8_STAGE(PG8_SB(0, 1), b2 + hstep, voffB); PG8_STAGE(PG8_SA(0, 0), a2, voffA);
;             PG8_WAIT_V(8); PG8_WAIT_L(0); PG8_BAR; PG8_MMA(1, 0, At, B0); PG8_MMA(1, 1, At, B1); PG8_BAR; PG8_SCHED;
.LBB0_128:
	s_ashr_i32 s67, s66, 31
	s_lshl_b64 s[14:15], s[66:67], 20
	s_add_u32 s70, s37, s14
	s_addc_u32 s71, s38, s15
	s_and_b64 s[14:15], s[68:69], exec
	s_cselect_b32 s2, s71, s1
	s_cselect_b32 s11, s70, s0
	s_ashr_i32 s65, s64, 31
	s_lshl_b64 s[14:15], s[64:65], 20
	s_add_u32 s72, s31, s14
	s_addc_u32 s73, s36, s15
	s_and_b64 s[14:15], s[68:69], exec
	s_cselect_b32 s18, s73, s13
	s_cselect_b32 s19, s72, s12
	s_add_u32 s0, s0, 0x80080
	s_addc_u32 s1, s1, 0
	s_add_u32 s34, s12, 0x100
	s_addc_u32 s41, s13, 0
	s_mov_b32 s42, -2
	v_lshl_add_u64 v[194:195], s[0:1], 0, v[144:145]
	s_add_i32 m0, s74, 0xc000
	global_load_lds_dwordx4 v[194:195], off
	s_add_i32 m0, s74, 0xe000
	v_lshl_add_u64 v[194:195], s[0:1], 0, v[146:147]
	global_load_lds_dwordx4 v[194:195], off
	s_add_u32 s12, s0, 0xfff80080
	s_addc_u32 s13, s1, -1
	s_add_i32 s43, 0, 0x10000
	s_cmp_eq_u32 s42, 28
	s_cselect_b32 s15, s2, s13
	s_cselect_b32 s14, s11, s12
	s_cselect_b32 s13, s18, s41
	s_cselect_b32 s12, s19, s34
	s_add_i32 s65, 0, 0x14000
	s_waitcnt vmcnt(8)
	s_waitcnt lgkmcnt(0)
	s_barrier
	s_setprio 1
	s_waitcnt lgkmcnt(0)
	v_mfma_f32_16x16x32_bf16 v[124:127], v[128:131], v[172:175], 0
	v_mfma_f32_16x16x32_bf16 v[120:123], v[148:151], v[172:175], 0
	v_mfma_f32_16x16x32_bf16 v[108:111], v[128:131], v[184:187], 0
	v_mfma_f32_16x16x32_bf16 v[104:107], v[148:151], v[184:187], 0
	v_mfma_f32_16x16x32_bf16 v[92:95], v[128:131], v[206:209], 0
	v_mfma_f32_16x16x32_bf16 v[88:91], v[148:151], v[206:209], 0
	v_mfma_f32_16x16x32_bf16 v[76:79], v[128:131], v[214:217], 0
	v_mfma_f32_16x16x32_bf16 v[72:75], v[148:151], v[214:217], 0
	v_mfma_f32_16x16x32_bf16 v[124:127], v[132:135], v[180:183], v[124:127]
	v_mfma_f32_16x16x32_bf16 v[120:123], v[152:155], v[180:183], v[120:123]
	v_mfma_f32_16x16x32_bf16 v[108:111], v[132:135], v[188:191], v[108:111]
	v_mfma_f32_16x16x32_bf16 v[104:107], v[152:155], v[188:191], v[104:107]
	v_mfma_f32_16x16x32_bf16 v[92:95], v[132:135], v[210:213], v[92:95]
	v_mfma_f32_16x16x32_bf16 v[88:91], v[152:155], v[210:213], v[88:91]
	v_mfma_f32_16x16x32_bf16 v[76:79], v[132:135], v[218:221], v[76:79]
	v_mfma_f32_16x16x32_bf16 v[72:75], v[152:155], v[218:221], v[72:75]
	s_setprio 0
	s_setprio 1
	v_mfma_f32_16x16x32_bf16 v[116:119], v[156:159], v[172:175], 0
	v_mfma_f32_16x16x32_bf16 v[112:115], v[164:167], v[172:175], 0
	v_mfma_f32_16x16x32_bf16 v[100:103], v[156:159], v[184:187], 0
	v_mfma_f32_16x16x32_bf16 v[96:99], v[164:167], v[184:187], 0
	v_mfma_f32_16x16x32_bf16 v[84:87], v[156:159], v[206:209], 0
	v_mfma_f32_16x16x32_bf16 v[80:83], v[164:167], v[206:209], 0
	v_mfma_f32_16x16x32_bf16 v[68:71], v[156:159], v[214:217], 0
	v_mfma_f32_16x16x32_bf16 v[64:67], v[164:167], v[214:217], 0
	v_mfma_f32_16x16x32_bf16 v[116:119], v[160:163], v[180:183], v[116:119]
	v_mfma_f32_16x16x32_bf16 v[112:115], v[168:171], v[180:183], v[112:115]
	v_mfma_f32_16x16x32_bf16 v[100:103], v[160:163], v[188:191], v[100:103]
	v_mfma_f32_16x16x32_bf16 v[96:99], v[168:171], v[188:191], v[96:99]
	v_mfma_f32_16x16x32_bf16 v[84:87], v[160:163], v[210:213], v[84:87]
	v_mfma_f32_16x16x32_bf16 v[80:83], v[168:171], v[210:213], v[80:83]
	v_mfma_f32_16x16x32_bf16 v[68:71], v[160:163], v[218:221], v[68:71]
	v_mfma_f32_16x16x32_bf16 v[64:67], v[168:171], v[218:221], v[64:67]
	s_setprio 0
	s_barrier
	s_add_i32 s43, s43, s39
	v_lshl_add_u64 v[194:195], s[12:13], 0, v[138:139]
	s_mov_b32 m0, s43
	ds_read_b128 v[172:175], v179 offset:16384
	ds_read_b128 v[180:183], v179 offset:17408
	ds_read_b128 v[184:187], v179 offset:18432
	ds_read_b128 v[188:191], v179 offset:19456
	ds_read_b128 v[206:209], v179 offset:20480
	ds_read_b128 v[210:213], v179 offset:21504
	ds_read_b128 v[214:217], v179 offset:22528
	ds_read_b128 v[218:221], v179 offset:23552
	global_load_lds_dwordx4 v[194:195], off
	s_add_i32 m0, s43, 0x2000
	s_add_u32 s86, s12, 0x80000
	v_lshl_add_u64 v[196:197], s[12:13], 0, v[142:143]
	s_addc_u32 s87, s13, 0
	s_add_i32 s43, s65, s39
	global_load_lds_dwordx4 v[196:197], off
	v_lshl_add_u64 v[202:203], s[86:87], 0, v[138:139]
	s_mov_b32 m0, s43
	v_lshl_add_u64 v[204:205], s[14:15], 0, v[140:141]
	global_load_lds_dwordx4 v[202:203], off
	s_add_i32 m0, s43, 0x2000
	v_lshl_add_u64 v[202:203], s[86:87], 0, v[142:143]
	global_load_lds_dwordx4 v[202:203], off
	s_mov_b32 m0, s74
	v_lshl_add_u64 v[202:203], s[14:15], 0, v[136:137]
	global_load_lds_dwordx4 v[202:203], off
	s_mov_b32 m0, s75
	s_nop 0
	global_load_lds_dwordx4 v[204:205], off
	s_waitcnt vmcnt(8)
	s_waitcnt lgkmcnt(0)
	s_barrier
	s_setprio 1
	s_waitcnt lgkmcnt(0)
	v_mfma_f32_16x16x32_bf16 v[60:63], v[128:131], v[172:175], 0
	v_mfma_f32_16x16x32_bf16 v[56:59], v[148:151], v[172:175], 0
	v_mfma_f32_16x16x32_bf16 v[44:47], v[128:131], v[184:187], 0
	v_mfma_f32_16x16x32_bf16 v[40:43], v[148:151], v[184:187], 0
	v_mfma_f32_16x16x32_bf16 v[28:31], v[128:131], v[206:209], 0
	v_mfma_f32_16x16x32_bf16 v[24:27], v[148:151], v[206:209], 0
	v_mfma_f32_16x16x32_bf16 v[12:15], v[128:131], v[214:217], 0
	v_mfma_f32_16x16x32_bf16 v[8:11], v[148:151], v[214:217], 0
	v_mfma_f32_16x16x32_bf16 v[60:63], v[132:135], v[180:183], v[60:63]
	v_mfma_f32_16x16x32_bf16 v[56:59], v[152:155], v[180:183], v[56:59]
	v_mfma_f32_16x16x32_bf16 v[44:47], v[132:135], v[188:191], v[44:47]
	v_mfma_f32_16x16x32_bf16 v[40:43], v[152:155], v[188:191], v[40:43]
	v_mfma_f32_16x16x32_bf16 v[28:31], v[132:135], v[210:213], v[28:31]
	v_mfma_f32_16x16x32_bf16 v[24:27], v[152:155], v[210:213], v[24:27]
	v_mfma_f32_16x16x32_bf16 v[12:15], v[132:135], v[218:221], v[12:15]
	v_mfma_f32_16x16x32_bf16 v[8:11], v[152:155], v[218:221], v[8:11]
	s_setprio 0
	s_setprio 1
	v_mfma_f32_16x16x32_bf16 v[52:55], v[156:159], v[172:175], 0
	v_mfma_f32_16x16x32_bf16 v[48:51], v[164:167], v[172:175], 0
	v_mfma_f32_16x16x32_bf16 v[36:39], v[156:159], v[184:187], 0
	v_mfma_f32_16x16x32_bf16 v[32:35], v[164:167], v[184:187], 0
	v_mfma_f32_16x16x32_bf16 v[20:23], v[156:159], v[206:209], 0
	v_mfma_f32_16x16x32_bf16 v[16:19], v[164:167], v[206:209], 0
	v_mfma_f32_16x16x32_bf16 v[4:7], v[156:159], v[214:217], 0
	v_mfma_f32_16x16x32_bf16 v[0:3], v[164:167], v[214:217], 0
	v_mfma_f32_16x16x32_bf16 v[52:55], v[160:163], v[180:183], v[52:55]
	v_mfma_f32_16x16x32_bf16 v[48:51], v[168:171], v[180:183], v[48:51]
	v_mfma_f32_16x16x32_bf16 v[36:39], v[160:163], v[188:191], v[36:39]
	v_mfma_f32_16x16x32_bf16 v[32:35], v[168:171], v[188:191], v[32:35]
	v_mfma_f32_16x16x32_bf16 v[20:23], v[160:163], v[210:213], v[20:23]
	v_mfma_f32_16x16x32_bf16 v[16:19], v[168:171], v[210:213], v[16:19]
	v_mfma_f32_16x16x32_bf16 v[4:7], v[160:163], v[218:221], v[4:7]
	v_mfma_f32_16x16x32_bf16 v[0:3], v[168:171], v[218:221], v[0:3]
	s_setprio 0
	s_barrier
; #define PG8_STAGE(bufoff, gbase, voff) do { _Pragma("unroll") for (int _i = 0; _i < 2; ++_i) \
;         __builtin_amdgcn_global_load_lds((const unsigned*)((const char*)(gbase) + (voff)[_i]), (PG8_LAS unsigned*)(lds + (bufoff) + ldsw + _i * 8192), 16, 0, 0); } while (0)
; #define PG8_LDA(dst, b, h) do { _Pragma("unroll") for (int m = 0; m < 4; ++m) _Pragma("unroll") for (int k = 0; k < 2; ++k) dst[m][k] = *(const PG8_LAS bf16x8*)(lds + PG8_SA(b, h) + aoff + m * 2048 + k * 1024); } while (0)
; #define PG8_LDB(dst, b, h) do { _Pragma("unroll") for (int n = 0; n < 2; ++n) _Pragma("unroll") for (int k = 0; k < 2; ++k) dst[n][k] = *(const PG8_LAS bf16x8*)(lds + PG8_SB(b, h) + boff + n * 2048 + k * 1024); } while (0)
; #define PG8_MMA(ai, bj, At, Bt) do { __builtin_amdgcn_s_setprio(1); _Pragma("unroll") for (int m = 0; m < 4; ++m) _Pragma("unroll") for (int n = 0; n < 2; ++n) _Pragma("unroll") for (int k = 0; k < 2; ++k) \
;         acc[ai][bj][m][n] = __builtin_amdgcn_mfma_f32_16x16x32_bf16(Bt[n][k], At[m][k], acc[ai][bj][m][n], 0, 0, 0); __builtin_amdgcn_s_setprio(0); } while (0)
; #define PG8_WAIT_V(n) asm volatile("s_waitcnt vmcnt(" #n ")" ::: "memory")
; #define PG8_WAIT_L(n) asm volatile("s_waitcnt lgkmcnt(" #n ")" ::: "memory")
; #define PG8_BAR __builtin_amdgcn_s_barrier()
; #define PG8_SCHED __builtin_amdgcn_sched_barrier(0)
; template <class Epi, class Sched, bool ALIGN_EPI = false, bool SP2 = false>
; __device__ __forceinline__ void gemm_phase(PG8_LAS unsigned char* lds, const Gemm g, const Sched& S, const Epi& E) {
;     ...
;             PG8_LDB(B0, 1, 0); PG8_LDB(B1, 1, 1); PG8_SCHED; PG8_LDA(At, 1, 0); PG8_STAGE(PG8_SA(0, 1), a2 + hstep, voffA);
;             PG8_WAIT_V(8); PG8_WAIT_L(0); PG8_BAR; PG8_MMA(0, 0, At, B0); PG8_MMA(0, 1, At, B1); PG8_BAR; PG8_SCHED;
;             PG8_LDA(At, 1, 1); PG8_STAGE(PG8_SB(1, 0), b3, voffB); PG8_STAGE(PG8_SB(1, 1), b3 + hstep, voffB); PG8_STAGE(PG8_SA(1, 0), a3, voffA);
;             PG8_WAIT_V(8); PG8_WAIT_L(0); PG8_BAR; PG8_MMA(1, 0, At, B0); PG8_MMA(1, 1, At, B1); PG8_BAR; PG8_SCHED;
	s_add_i32 s43, 0, 0x18000
	s_add_i32 s65, 0, 0x1c000
	v_add_u32_e32 v152, 0x18000, v178
	v_add_u32_e32 v168, 0x1c000, v178
	ds_read_b128 v[128:131], v152
	ds_read_b128 v[132:135], v152 offset:1024
	ds_read_b128 v[148:151], v152 offset:2048
	ds_read_b128 v[152:155], v152 offset:3072
	ds_read_b128 v[156:159], v168
	ds_read_b128 v[160:163], v168 offset:1024
	ds_read_b128 v[164:167], v168 offset:2048
	ds_read_b128 v[168:171], v168 offset:3072
	s_add_u32 s14, s14, 0x80000
	s_addc_u32 s15, s15, 0
	s_mov_b32 m0, s76
	v_lshl_add_u64 v[232:233], s[14:15], 0, v[136:137]
	ds_read_b128 v[172:175], v179 offset:32768
	ds_read_b128 v[180:183], v179 offset:33792
	ds_read_b128 v[184:187], v179 offset:34816
	ds_read_b128 v[188:191], v179 offset:35840
	ds_read_b128 v[206:209], v179 offset:36864
	ds_read_b128 v[210:213], v179 offset:37888
	ds_read_b128 v[214:217], v179 offset:38912
	ds_read_b128 v[218:221], v179 offset:39936
	global_load_lds_dwordx4 v[232:233], off
	s_mov_b32 m0, s77
	v_lshl_add_u64 v[232:233], s[14:15], 0, v[140:141]
	global_load_lds_dwordx4 v[232:233], off
	s_waitcnt vmcnt(8)
	s_waitcnt lgkmcnt(0)
	s_barrier
	s_setprio 1
	s_waitcnt lgkmcnt(0)
	v_mfma_f32_16x16x32_bf16 v[124:127], v[128:131], v[172:175], v[124:127]
	v_mfma_f32_16x16x32_bf16 v[120:123], v[148:151], v[172:175], v[120:123]
	v_mfma_f32_16x16x32_bf16 v[108:111], v[128:131], v[184:187], v[108:111]
	v_mfma_f32_16x16x32_bf16 v[104:107], v[148:151], v[184:187], v[104:107]
	v_mfma_f32_16x16x32_bf16 v[92:95], v[128:131], v[206:209], v[92:95]
	v_mfma_f32_16x16x32_bf16 v[88:91], v[148:151], v[206:209], v[88:91]
	v_mfma_f32_16x16x32_bf16 v[76:79], v[128:131], v[214:217], v[76:79]
	v_mfma_f32_16x16x32_bf16 v[72:75], v[148:151], v[214:217], v[72:75]
	v_mfma_f32_16x16x32_bf16 v[124:127], v[132:135], v[180:183], v[124:127]
	v_mfma_f32_16x16x32_bf16 v[120:123], v[152:155], v[180:183], v[120:123]
	v_mfma_f32_16x16x32_bf16 v[108:111], v[132:135], v[188:191], v[108:111]
	v_mfma_f32_16x16x32_bf16 v[104:107], v[152:155], v[188:191], v[104:107]
	v_mfma_f32_16x16x32_bf16 v[92:95], v[132:135], v[210:213], v[92:95]
	v_mfma_f32_16x16x32_bf16 v[88:91], v[152:155], v[210:213], v[88:91]
	v_mfma_f32_16x16x32_bf16 v[76:79], v[132:135], v[218:221], v[76:79]
	v_mfma_f32_16x16x32_bf16 v[72:75], v[152:155], v[218:221], v[72:75]
	s_setprio 0
	s_setprio 1
	v_mfma_f32_16x16x32_bf16 v[116:119], v[156:159], v[172:175], v[116:119]
	v_mfma_f32_16x16x32_bf16 v[112:115], v[164:167], v[172:175], v[112:115]
	v_mfma_f32_16x16x32_bf16 v[100:103], v[156:159], v[184:187], v[100:103]
	v_mfma_f32_16x16x32_bf16 v[96:99], v[164:167], v[184:187], v[96:99]
	v_mfma_f32_16x16x32_bf16 v[84:87], v[156:159], v[206:209], v[84:87]
	v_mfma_f32_16x16x32_bf16 v[80:83], v[164:167], v[206:209], v[80:83]
	v_mfma_f32_16x16x32_bf16 v[68:71], v[156:159], v[214:217], v[68:71]
	v_mfma_f32_16x16x32_bf16 v[64:67], v[164:167], v[214:217], v[64:67]
	v_mfma_f32_16x16x32_bf16 v[116:119], v[160:163], v[180:183], v[116:119]
	v_mfma_f32_16x16x32_bf16 v[112:115], v[168:171], v[180:183], v[112:115]
	v_mfma_f32_16x16x32_bf16 v[100:103], v[160:163], v[188:191], v[100:103]
	v_mfma_f32_16x16x32_bf16 v[96:99], v[168:171], v[188:191], v[96:99]
	v_mfma_f32_16x16x32_bf16 v[84:87], v[160:163], v[210:213], v[84:87]
	v_mfma_f32_16x16x32_bf16 v[80:83], v[168:171], v[210:213], v[80:83]
	v_mfma_f32_16x16x32_bf16 v[68:71], v[160:163], v[218:221], v[68:71]
	v_mfma_f32_16x16x32_bf16 v[64:67], v[168:171], v[218:221], v[64:67]
	s_setprio 0
	s_barrier
	s_add_i32 s14, s43, s39
	v_lshl_add_u64 v[194:195], v[194:195], 0, s[16:17]
	s_mov_b32 m0, s14
	ds_read_b128 v[172:175], v179 offset:49152
	ds_read_b128 v[180:183], v179 offset:50176
	ds_read_b128 v[184:187], v179 offset:51200
	ds_read_b128 v[188:191], v179 offset:52224
	ds_read_b128 v[206:209], v179 offset:53248
	ds_read_b128 v[210:213], v179 offset:54272
	ds_read_b128 v[214:217], v179 offset:55296
	ds_read_b128 v[218:221], v179 offset:56320
	global_load_lds_dwordx4 v[194:195], off
	s_add_i32 m0, s14, 0x2000
	s_add_u32 s12, s12, 0x80080
	v_lshl_add_u64 v[194:195], v[196:197], 0, s[16:17]
	s_addc_u32 s13, s13, 0
	s_add_i32 s14, s65, s39
	global_load_lds_dwordx4 v[194:195], off
	s_mov_b32 m0, s14
	v_lshl_add_u64 v[194:195], s[12:13], 0, v[138:139]
	global_load_lds_dwordx4 v[194:195], off
	s_add_i32 m0, s14, 0x2000
	v_lshl_add_u64 v[194:195], s[12:13], 0, v[142:143]
	global_load_lds_dwordx4 v[194:195], off
	s_mov_b32 m0, s80
	v_lshl_add_u64 v[194:195], v[202:203], 0, s[16:17]
	global_load_lds_dwordx4 v[194:195], off
	s_mov_b32 m0, s81
	v_lshl_add_u64 v[194:195], v[204:205], 0, s[16:17]
	global_load_lds_dwordx4 v[194:195], off
	s_waitcnt vmcnt(8)
	s_waitcnt lgkmcnt(0)
	s_barrier
; #define PG8_STAGE(bufoff, gbase, voff) do { _Pragma("unroll") for (int _i = 0; _i < 2; ++_i) \
;         __builtin_amdgcn_global_load_lds((const unsigned*)((const char*)(gbase) + (voff)[_i]), (PG8_LAS unsigned*)(lds + (bufoff) + ldsw + _i * 8192), 16, 0, 0); } while (0)
; #define PG8_LDA(dst, b, h) do { _Pragma("unroll") for (int m = 0; m < 4; ++m) _Pragma("unroll") for (int k = 0; k < 2; ++k) dst[m][k] = *(const PG8_LAS bf16x8*)(lds + PG8_SA(b, h) + aoff + m * 2048 + k * 1024); } while (0)
; #define PG8_LDB(dst, b, h) do { _Pragma("unroll") for (int n = 0; n < 2; ++n) _Pragma("unroll") for (int k = 0; k < 2; ++k) dst[n][k] = *(const PG8_LAS bf16x8*)(lds + PG8_SB(b, h) + boff + n * 2048 + k * 1024); } while (0)
; #define PG8_MMA(ai, bj, At, Bt) do { __builtin_amdgcn_s_setprio(1); _Pragma("unroll") for (int m = 0; m < 4; ++m) _Pragma("unroll") for (int n = 0; n < 2; ++n) _Pragma("unroll") for (int k = 0; k < 2; ++k) \
;         acc[ai][bj][m][n] = __builtin_amdgcn_mfma_f32_16x16x32_bf16(Bt[n][k], At[m][k], acc[ai][bj][m][n], 0, 0, 0); __builtin_amdgcn_s_setprio(0); } while (0)
; #define PG8_WAIT_V(n) asm volatile("s_waitcnt vmcnt(" #n ")" ::: "memory")
; template <class Epi, class Sched, bool ALIGN_EPI = false, bool SP2 = false>
; __device__ __forceinline__ void gemm_phase(PG8_LAS unsigned char* lds, const Gemm g, const Sched& S, const Epi& E) {
;     ...
;             PG8_LDB(B0, 0, 0); PG8_LDB(B1, 0, 1); PG8_SCHED; PG8_LDA(At, 0, 0); PG8_STAGE(PG8_SA(1, 1), a1 + hstep, voffA);
;             PG8_WAIT_V(8); PG8_WAIT_L(0); PG8_BAR; PG8_MMA(0, 0, At, B0); PG8_MMA(0, 1, At, B1); PG8_BAR; PG8_SCHED;
;             PG8_LDA(At, 0, 1); PG8_STAGE(PG8_SB(0, 0), b2, voffB); PG8_STAGE(PG8_SB(0, 1), b2 + hstep, voffB); PG8_STAGE(PG8_SA(0, 0), a2, voffA);
;             PG8_WAIT_V(8); PG8_WAIT_L(0); PG8_BAR; PG8_MMA(1, 0, At, B0); PG8_MMA(1, 1, At, B1); PG8_BAR; PG8_SCHED;
;             PG8_LDB(B0, 1, 0); PG8_LDB(B1, 1, 1); PG8_SCHED; PG8_LDA(At, 1, 0); PG8_STAGE(PG8_SA(0, 1), a2 + hstep, voffA);
;             PG8_WAIT_V(8); PG8_WAIT_L(0); PG8_BAR; PG8_MMA(0, 0, At, B0); PG8_MMA(0, 1, At, B1); PG8_BAR; PG8_SCHED;
;             PG8_LDA(At, 1, 1); PG8_STAGE(PG8_SB(1, 0), b3, voffB); PG8_STAGE(PG8_SB(1, 1), b3 + hstep, voffB); PG8_STAGE(PG8_SA(1, 0), a3, voffA);
;             PG8_WAIT_V(8); PG8_WAIT_L(0); PG8_BAR; PG8_MMA(1, 0, At, B0); PG8_MMA(1, 1, At, B1); PG8_BAR; PG8_SCHED;
	s_setprio 1
	s_waitcnt lgkmcnt(0)
	v_mfma_f32_16x16x32_bf16 v[60:63], v[128:131], v[172:175], v[60:63]
	v_mfma_f32_16x16x32_bf16 v[56:59], v[148:151], v[172:175], v[56:59]
	v_mfma_f32_16x16x32_bf16 v[44:47], v[128:131], v[184:187], v[44:47]
	v_mfma_f32_16x16x32_bf16 v[40:43], v[148:151], v[184:187], v[40:43]
	v_mfma_f32_16x16x32_bf16 v[28:31], v[128:131], v[206:209], v[28:31]
	v_mfma_f32_16x16x32_bf16 v[24:27], v[148:151], v[206:209], v[24:27]
	v_mfma_f32_16x16x32_bf16 v[12:15], v[128:131], v[214:217], v[12:15]
	v_mfma_f32_16x16x32_bf16 v[8:11], v[148:151], v[214:217], v[8:11]
	v_mfma_f32_16x16x32_bf16 v[60:63], v[132:135], v[180:183], v[60:63]
	v_mfma_f32_16x16x32_bf16 v[56:59], v[152:155], v[180:183], v[56:59]
	v_mfma_f32_16x16x32_bf16 v[44:47], v[132:135], v[188:191], v[44:47]
	v_mfma_f32_16x16x32_bf16 v[40:43], v[152:155], v[188:191], v[40:43]
	v_mfma_f32_16x16x32_bf16 v[28:31], v[132:135], v[210:213], v[28:31]
	v_mfma_f32_16x16x32_bf16 v[24:27], v[152:155], v[210:213], v[24:27]
	v_mfma_f32_16x16x32_bf16 v[12:15], v[132:135], v[218:221], v[12:15]
	v_mfma_f32_16x16x32_bf16 v[8:11], v[152:155], v[218:221], v[8:11]
	s_setprio 0
	s_setprio 1
	v_mfma_f32_16x16x32_bf16 v[52:55], v[156:159], v[172:175], v[52:55]
	v_mfma_f32_16x16x32_bf16 v[48:51], v[164:167], v[172:175], v[48:51]
	v_mfma_f32_16x16x32_bf16 v[36:39], v[156:159], v[184:187], v[36:39]
	v_mfma_f32_16x16x32_bf16 v[32:35], v[164:167], v[184:187], v[32:35]
	v_mfma_f32_16x16x32_bf16 v[20:23], v[156:159], v[206:209], v[20:23]
	v_mfma_f32_16x16x32_bf16 v[16:19], v[164:167], v[206:209], v[16:19]
	v_mfma_f32_16x16x32_bf16 v[4:7], v[156:159], v[214:217], v[4:7]
	v_mfma_f32_16x16x32_bf16 v[0:3], v[164:167], v[214:217], v[0:3]
	v_mfma_f32_16x16x32_bf16 v[52:55], v[160:163], v[180:183], v[52:55]
	v_mfma_f32_16x16x32_bf16 v[48:51], v[168:171], v[180:183], v[48:51]
	v_mfma_f32_16x16x32_bf16 v[36:39], v[160:163], v[188:191], v[36:39]
	v_mfma_f32_16x16x32_bf16 v[32:35], v[168:171], v[188:191], v[32:35]
	v_mfma_f32_16x16x32_bf16 v[20:23], v[160:163], v[210:213], v[20:23]
	v_mfma_f32_16x16x32_bf16 v[16:19], v[168:171], v[210:213], v[16:19]
	v_mfma_f32_16x16x32_bf16 v[4:7], v[160:163], v[218:221], v[4:7]
	v_mfma_f32_16x16x32_bf16 v[0:3], v[168:171], v[218:221], v[0:3]
	s_setprio 0
	s_add_i32 s42, s42, 2
	s_add_u32 s0, s0, 0x100
	s_addc_u32 s1, s1, 0
	s_add_u32 s34, s34, 0x100
	s_addc_u32 s41, s41, 0
	s_cmp_gt_u32 s42, 29
	s_barrier
.LBB0_129:
	v_add_u32_e32 v152, 0x10000, v178
	v_add_u32_e32 v168, 0x14000, v178
	ds_read_b128 v[128:131], v152
	ds_read_b128 v[132:135], v152 offset:1024
	ds_read_b128 v[148:151], v152 offset:2048
	ds_read_b128 v[152:155], v152 offset:3072
	ds_read_b128 v[156:159], v168
	ds_read_b128 v[160:163], v168 offset:1024
	ds_read_b128 v[164:167], v168 offset:2048
	ds_read_b128 v[168:171], v168 offset:3072
	v_lshl_add_u64 v[194:195], s[0:1], 0, v[144:145]
	s_add_i32 m0, s74, 0xc000
	ds_read_b128 v[172:175], v179
	ds_read_b128 v[180:183], v179 offset:1024
	ds_read_b128 v[184:187], v179 offset:2048
	ds_read_b128 v[188:191], v179 offset:3072
	ds_read_b128 v[206:209], v179 offset:4096
	ds_read_b128 v[210:213], v179 offset:5120
	ds_read_b128 v[214:217], v179 offset:6144
	ds_read_b128 v[218:221], v179 offset:7168
	global_load_lds_dwordx4 v[194:195], off
	s_add_i32 m0, s74, 0xe000
	v_lshl_add_u64 v[194:195], s[0:1], 0, v[146:147]
	global_load_lds_dwordx4 v[194:195], off
	s_add_u32 s12, s0, 0xfff80080
	s_addc_u32 s13, s1, -1
	s_add_i32 s43, 0, 0x10000
	s_cmp_eq_u32 s42, 28
	s_cselect_b32 s15, s2, s13
	s_cselect_b32 s14, s11, s12
	s_cselect_b32 s13, s18, s41
	s_cselect_b32 s12, s19, s34
	s_add_i32 s65, 0, 0x14000
	s_waitcnt vmcnt(8)
	s_waitcnt lgkmcnt(0)
	s_barrier
	s_setprio 1
	s_waitcnt lgkmcnt(0)
	v_mfma_f32_16x16x32_bf16 v[124:127], v[128:131], v[172:175], v[124:127]
	v_mfma_f32_16x16x32_bf16 v[120:123], v[148:151], v[172:175], v[120:123]
	v_mfma_f32_16x16x32_bf16 v[108:111], v[128:131], v[184:187], v[108:111]
	v_mfma_f32_16x16x32_bf16 v[104:107], v[148:151], v[184:187], v[104:107]
	v_mfma_f32_16x16x32_bf16 v[92:95], v[128:131], v[206:209], v[92:95]
	v_mfma_f32_16x16x32_bf16 v[88:91], v[148:151], v[206:209], v[88:91]
	v_mfma_f32_16x16x32_bf16 v[76:79], v[128:131], v[214:217], v[76:79]
	v_mfma_f32_16x16x32_bf16 v[72:75], v[148:151], v[214:217], v[72:75]
	v_mfma_f32_16x16x32_bf16 v[124:127], v[132:135], v[180:183], v[124:127]
	v_mfma_f32_16x16x32_bf16 v[120:123], v[152:155], v[180:183], v[120:123]
	v_mfma_f32_16x16x32_bf16 v[108:111], v[132:135], v[188:191], v[108:111]
	v_mfma_f32_16x16x32_bf16 v[104:107], v[152:155], v[188:191], v[104:107]
	v_mfma_f32_16x16x32_bf16 v[92:95], v[132:135], v[210:213], v[92:95]
	v_mfma_f32_16x16x32_bf16 v[88:91], v[152:155], v[210:213], v[88:91]
	v_mfma_f32_16x16x32_bf16 v[76:79], v[132:135], v[218:221], v[76:79]
	v_mfma_f32_16x16x32_bf16 v[72:75], v[152:155], v[218:221], v[72:75]
	s_setprio 0
	s_setprio 1
	v_mfma_f32_16x16x32_bf16 v[116:119], v[156:159], v[172:175], v[116:119]
	v_mfma_f32_16x16x32_bf16 v[112:115], v[164:167], v[172:175], v[112:115]
	v_mfma_f32_16x16x32_bf16 v[100:103], v[156:159], v[184:187], v[100:103]
	v_mfma_f32_16x16x32_bf16 v[96:99], v[164:167], v[184:187], v[96:99]
	v_mfma_f32_16x16x32_bf16 v[84:87], v[156:159], v[206:209], v[84:87]
	v_mfma_f32_16x16x32_bf16 v[80:83], v[164:167], v[206:209], v[80:83]
	v_mfma_f32_16x16x32_bf16 v[68:71], v[156:159], v[214:217], v[68:71]
	v_mfma_f32_16x16x32_bf16 v[64:67], v[164:167], v[214:217], v[64:67]
	v_mfma_f32_16x16x32_bf16 v[116:119], v[160:163], v[180:183], v[116:119]
	v_mfma_f32_16x16x32_bf16 v[112:115], v[168:171], v[180:183], v[112:115]
	v_mfma_f32_16x16x32_bf16 v[100:103], v[160:163], v[188:191], v[100:103]
	v_mfma_f32_16x16x32_bf16 v[96:99], v[168:171], v[188:191], v[96:99]
	v_mfma_f32_16x16x32_bf16 v[84:87], v[160:163], v[210:213], v[84:87]
	v_mfma_f32_16x16x32_bf16 v[80:83], v[168:171], v[210:213], v[80:83]
	v_mfma_f32_16x16x32_bf16 v[68:71], v[160:163], v[218:221], v[68:71]
	v_mfma_f32_16x16x32_bf16 v[64:67], v[168:171], v[218:221], v[64:67]
	s_setprio 0
	s_barrier
; #define PG8_STAGE(bufoff, gbase, voff) do { _Pragma("unroll") for (int _i = 0; _i < 2; ++_i) \
;         __builtin_amdgcn_global_load_lds((const unsigned*)((const char*)(gbase) + (voff)[_i]), (PG8_LAS unsigned*)(lds + (bufoff) + ldsw + _i * 8192), 16, 0, 0); } while (0)
; #define PG8_LDA(dst, b, h) do { _Pragma("unroll") for (int m = 0; m < 4; ++m) _Pragma("unroll") for (int k = 0; k < 2; ++k) dst[m][k] = *(const PG8_LAS bf16x8*)(lds + PG8_SA(b, h) + aoff + m * 2048 + k * 1024); } while (0)
; #define PG8_LDB(dst, b, h) do { _Pragma("unroll") for (int n = 0; n < 2; ++n) _Pragma("unroll") for (int k = 0; k < 2; ++k) dst[n][k] = *(const PG8_LAS bf16x8*)(lds + PG8_SB(b, h) + boff + n * 2048 + k * 1024); } while (0)
; #define PG8_MMA(ai, bj, At, Bt) do { __builtin_amdgcn_s_setprio(1); _Pragma("unroll") for (int m = 0; m < 4; ++m) _Pragma("unroll") for (int n = 0; n < 2; ++n) _Pragma("unroll") for (int k = 0; k < 2; ++k) \
;         acc[ai][bj][m][n] = __builtin_amdgcn_mfma_f32_16x16x32_bf16(Bt[n][k], At[m][k], acc[ai][bj][m][n], 0, 0, 0); __builtin_amdgcn_s_setprio(0); } while (0)
; #define PG8_WAIT_V(n) asm volatile("s_waitcnt vmcnt(" #n ")" ::: "memory")
; #define PG8_WAIT_L(n) asm volatile("s_waitcnt lgkmcnt(" #n ")" ::: "memory")
; #define PG8_BAR __builtin_amdgcn_s_barrier()
; #define PG8_SCHED __builtin_amdgcn_sched_barrier(0)
; template <class Epi, class Sched, bool ALIGN_EPI = false, bool SP2 = false>
; __device__ __forceinline__ void gemm_phase(PG8_LAS unsigned char* lds, const Gemm g, const Sched& S, const Epi& E) {
;     ...
;             PG8_LDA(At, 0, 1); PG8_STAGE(PG8_SB(0, 0), b2, voffB); PG8_STAGE(PG8_SB(0, 1), b2 + hstep, voffB); PG8_STAGE(PG8_SA(0, 0), a2, voffA);
;             PG8_WAIT_V(8); PG8_WAIT_L(0); PG8_BAR; PG8_MMA(1, 0, At, B0); PG8_MMA(1, 1, At, B1); PG8_BAR; PG8_SCHED;
;             PG8_LDB(B0, 1, 0); PG8_LDB(B1, 1, 1); PG8_SCHED; PG8_LDA(At, 1, 0); PG8_STAGE(PG8_SA(0, 1), a2 + hstep, voffA);
;             PG8_WAIT_V(8); PG8_WAIT_L(0); PG8_BAR; PG8_MMA(0, 0, At, B0); PG8_MMA(0, 1, At, B1); PG8_BAR; PG8_SCHED;
	s_add_i32 s43, s43, s39
	v_lshl_add_u64 v[194:195], s[12:13], 0, v[138:139]
	s_mov_b32 m0, s43
	ds_read_b128 v[172:175], v179 offset:16384
	ds_read_b128 v[180:183], v179 offset:17408
	ds_read_b128 v[184:187], v179 offset:18432
	ds_read_b128 v[188:191], v179 offset:19456
	ds_read_b128 v[206:209], v179 offset:20480
	ds_read_b128 v[210:213], v179 offset:21504
	ds_read_b128 v[214:217], v179 offset:22528
	ds_read_b128 v[218:221], v179 offset:23552
	global_load_lds_dwordx4 v[194:195], off
	s_add_i32 m0, s43, 0x2000
	s_add_u32 s86, s12, 0x80000
	v_lshl_add_u64 v[196:197], s[12:13], 0, v[142:143]
	s_addc_u32 s87, s13, 0
	s_add_i32 s43, s65, s39
	global_load_lds_dwordx4 v[196:197], off
	v_lshl_add_u64 v[202:203], s[86:87], 0, v[138:139]
	s_mov_b32 m0, s43
	v_lshl_add_u64 v[204:205], s[14:15], 0, v[140:141]
	global_load_lds_dwordx4 v[202:203], off
	s_add_i32 m0, s43, 0x2000
	v_lshl_add_u64 v[202:203], s[86:87], 0, v[142:143]
	global_load_lds_dwordx4 v[202:203], off
	s_mov_b32 m0, s74
	v_lshl_add_u64 v[202:203], s[14:15], 0, v[136:137]
	global_load_lds_dwordx4 v[202:203], off
	s_mov_b32 m0, s75
	s_nop 0
	global_load_lds_dwordx4 v[204:205], off
	s_waitcnt vmcnt(8)
	s_waitcnt lgkmcnt(0)
	s_barrier
	s_setprio 1
	s_waitcnt lgkmcnt(0)
	v_mfma_f32_16x16x32_bf16 v[60:63], v[128:131], v[172:175], v[60:63]
	v_mfma_f32_16x16x32_bf16 v[56:59], v[148:151], v[172:175], v[56:59]
	v_mfma_f32_16x16x32_bf16 v[44:47], v[128:131], v[184:187], v[44:47]
	v_mfma_f32_16x16x32_bf16 v[40:43], v[148:151], v[184:187], v[40:43]
	v_mfma_f32_16x16x32_bf16 v[28:31], v[128:131], v[206:209], v[28:31]
	v_mfma_f32_16x16x32_bf16 v[24:27], v[148:151], v[206:209], v[24:27]
	v_mfma_f32_16x16x32_bf16 v[12:15], v[128:131], v[214:217], v[12:15]
	v_mfma_f32_16x16x32_bf16 v[8:11], v[148:151], v[214:217], v[8:11]
	v_mfma_f32_16x16x32_bf16 v[60:63], v[132:135], v[180:183], v[60:63]
	v_mfma_f32_16x16x32_bf16 v[56:59], v[152:155], v[180:183], v[56:59]
	v_mfma_f32_16x16x32_bf16 v[44:47], v[132:135], v[188:191], v[44:47]
	v_mfma_f32_16x16x32_bf16 v[40:43], v[152:155], v[188:191], v[40:43]
	v_mfma_f32_16x16x32_bf16 v[28:31], v[132:135], v[210:213], v[28:31]
	v_mfma_f32_16x16x32_bf16 v[24:27], v[152:155], v[210:213], v[24:27]
	v_mfma_f32_16x16x32_bf16 v[12:15], v[132:135], v[218:221], v[12:15]
	v_mfma_f32_16x16x32_bf16 v[8:11], v[152:155], v[218:221], v[8:11]
	s_setprio 0
	s_setprio 1
	v_mfma_f32_16x16x32_bf16 v[52:55], v[156:159], v[172:175], v[52:55]
	v_mfma_f32_16x16x32_bf16 v[48:51], v[164:167], v[172:175], v[48:51]
	v_mfma_f32_16x16x32_bf16 v[36:39], v[156:159], v[184:187], v[36:39]
	v_mfma_f32_16x16x32_bf16 v[32:35], v[164:167], v[184:187], v[32:35]
	v_mfma_f32_16x16x32_bf16 v[20:23], v[156:159], v[206:209], v[20:23]
	v_mfma_f32_16x16x32_bf16 v[16:19], v[164:167], v[206:209], v[16:19]
	v_mfma_f32_16x16x32_bf16 v[4:7], v[156:159], v[214:217], v[4:7]
	v_mfma_f32_16x16x32_bf16 v[0:3], v[164:167], v[214:217], v[0:3]
	v_mfma_f32_16x16x32_bf16 v[52:55], v[160:163], v[180:183], v[52:55]
	v_mfma_f32_16x16x32_bf16 v[48:51], v[168:171], v[180:183], v[48:51]
	v_mfma_f32_16x16x32_bf16 v[36:39], v[160:163], v[188:191], v[36:39]
	v_mfma_f32_16x16x32_bf16 v[32:35], v[168:171], v[188:191], v[32:35]
	v_mfma_f32_16x16x32_bf16 v[20:23], v[160:163], v[210:213], v[20:23]
	v_mfma_f32_16x16x32_bf16 v[16:19], v[168:171], v[210:213], v[16:19]
	v_mfma_f32_16x16x32_bf16 v[4:7], v[160:163], v[218:221], v[4:7]
	v_mfma_f32_16x16x32_bf16 v[0:3], v[168:171], v[218:221], v[0:3]
	s_setprio 0
	s_barrier
	s_add_i32 s43, 0, 0x18000
	s_add_i32 s65, 0, 0x1c000
	v_add_u32_e32 v152, 0x18000, v178
	v_add_u32_e32 v168, 0x1c000, v178
	ds_read_b128 v[128:131], v152
	ds_read_b128 v[132:135], v152 offset:1024
	ds_read_b128 v[148:151], v152 offset:2048
	ds_read_b128 v[152:155], v152 offset:3072
	ds_read_b128 v[156:159], v168
	ds_read_b128 v[160:163], v168 offset:1024
	ds_read_b128 v[164:167], v168 offset:2048
	ds_read_b128 v[168:171], v168 offset:3072
	s_add_u32 s14, s14, 0x80000
	s_addc_u32 s15, s15, 0
	s_mov_b32 m0, s76
	v_lshl_add_u64 v[232:233], s[14:15], 0, v[136:137]
	ds_read_b128 v[172:175], v179 offset:32768
	ds_read_b128 v[180:183], v179 offset:33792
	ds_read_b128 v[184:187], v179 offset:34816
	ds_read_b128 v[188:191], v179 offset:35840
	ds_read_b128 v[206:209], v179 offset:36864
	ds_read_b128 v[210:213], v179 offset:37888
	ds_read_b128 v[214:217], v179 offset:38912
	ds_read_b128 v[218:221], v179 offset:39936
	global_load_lds_dwordx4 v[232:233], off
	s_mov_b32 m0, s77
	v_lshl_add_u64 v[232:233], s[14:15], 0, v[140:141]
	global_load_lds_dwordx4 v[232:233], off
	s_waitcnt vmcnt(8)
	s_waitcnt lgkmcnt(0)
	s_barrier
; #define PG8_STAGE(bufoff, gbase, voff) do { _Pragma("unroll") for (int _i = 0; _i < 2; ++_i) \
;         __builtin_amdgcn_global_load_lds((const unsigned*)((const char*)(gbase) + (voff)[_i]), (PG8_LAS unsigned*)(lds + (bufoff) + ldsw + _i * 8192), 16, 0, 0); } while (0)
; #define PG8_LDA(dst, b, h) do { _Pragma("unroll") for (int m = 0; m < 4; ++m) _Pragma("unroll") for (int k = 0; k < 2; ++k) dst[m][k] = *(const PG8_LAS bf16x8*)(lds + PG8_SA(b, h) + aoff + m * 2048 + k * 1024); } while (0)
; #define PG8_MMA(ai, bj, At, Bt) do { __builtin_amdgcn_s_setprio(1); _Pragma("unroll") for (int m = 0; m < 4; ++m) _Pragma("unroll") for (int n = 0; n < 2; ++n) _Pragma("unroll") for (int k = 0; k < 2; ++k) \
;         acc[ai][bj][m][n] = __builtin_amdgcn_mfma_f32_16x16x32_bf16(Bt[n][k], At[m][k], acc[ai][bj][m][n], 0, 0, 0); __builtin_amdgcn_s_setprio(0); } while (0)
; #define PG8_WAIT_V(n) asm volatile("s_waitcnt vmcnt(" #n ")" ::: "memory")
; #define PG8_WAIT_L(n) asm volatile("s_waitcnt lgkmcnt(" #n ")" ::: "memory")
; #define PG8_BAR __builtin_amdgcn_s_barrier()
; #define PG8_SCHED __builtin_amdgcn_sched_barrier(0)
; template <class Epi, class Sched, bool ALIGN_EPI = false, bool SP2 = false>
; __device__ __forceinline__ void gemm_phase(PG8_LAS unsigned char* lds, const Gemm g, const Sched& S, const Epi& E) {
;     ...
;             PG8_WAIT_V(8); PG8_WAIT_L(0); PG8_BAR; PG8_MMA(0, 0, At, B0); PG8_MMA(0, 1, At, B1); PG8_BAR; PG8_SCHED;
;             PG8_LDA(At, 1, 1); PG8_STAGE(PG8_SB(1, 0), b3, voffB); PG8_STAGE(PG8_SB(1, 1), b3 + hstep, voffB); PG8_STAGE(PG8_SA(1, 0), a3, voffA);
;             PG8_WAIT_V(8); PG8_WAIT_L(0); PG8_BAR; PG8_MMA(1, 0, At, B0); PG8_MMA(1, 1, At, B1); PG8_BAR; PG8_SCHED;
	s_setprio 1
	s_waitcnt lgkmcnt(0)
	v_mfma_f32_16x16x32_bf16 v[124:127], v[128:131], v[172:175], v[124:127]
	v_mfma_f32_16x16x32_bf16 v[120:123], v[148:151], v[172:175], v[120:123]
	v_mfma_f32_16x16x32_bf16 v[108:111], v[128:131], v[184:187], v[108:111]
	v_mfma_f32_16x16x32_bf16 v[104:107], v[148:151], v[184:187], v[104:107]
	v_mfma_f32_16x16x32_bf16 v[92:95], v[128:131], v[206:209], v[92:95]
	v_mfma_f32_16x16x32_bf16 v[88:91], v[148:151], v[206:209], v[88:91]
	v_mfma_f32_16x16x32_bf16 v[76:79], v[128:131], v[214:217], v[76:79]
	v_mfma_f32_16x16x32_bf16 v[72:75], v[148:151], v[214:217], v[72:75]
	v_mfma_f32_16x16x32_bf16 v[124:127], v[132:135], v[180:183], v[124:127]
	v_mfma_f32_16x16x32_bf16 v[120:123], v[152:155], v[180:183], v[120:123]
	v_mfma_f32_16x16x32_bf16 v[108:111], v[132:135], v[188:191], v[108:111]
	v_mfma_f32_16x16x32_bf16 v[104:107], v[152:155], v[188:191], v[104:107]
	v_mfma_f32_16x16x32_bf16 v[92:95], v[132:135], v[210:213], v[92:95]
	v_mfma_f32_16x16x32_bf16 v[88:91], v[152:155], v[210:213], v[88:91]
	v_mfma_f32_16x16x32_bf16 v[76:79], v[132:135], v[218:221], v[76:79]
	v_mfma_f32_16x16x32_bf16 v[72:75], v[152:155], v[218:221], v[72:75]
	s_setprio 0
	s_setprio 1
	v_mfma_f32_16x16x32_bf16 v[116:119], v[156:159], v[172:175], v[116:119]
	v_mfma_f32_16x16x32_bf16 v[112:115], v[164:167], v[172:175], v[112:115]
	v_mfma_f32_16x16x32_bf16 v[100:103], v[156:159], v[184:187], v[100:103]
	v_mfma_f32_16x16x32_bf16 v[96:99], v[164:167], v[184:187], v[96:99]
	v_mfma_f32_16x16x32_bf16 v[84:87], v[156:159], v[206:209], v[84:87]
	v_mfma_f32_16x16x32_bf16 v[80:83], v[164:167], v[206:209], v[80:83]
	v_mfma_f32_16x16x32_bf16 v[68:71], v[156:159], v[214:217], v[68:71]
	v_mfma_f32_16x16x32_bf16 v[64:67], v[164:167], v[214:217], v[64:67]
	v_mfma_f32_16x16x32_bf16 v[116:119], v[160:163], v[180:183], v[116:119]
	v_mfma_f32_16x16x32_bf16 v[112:115], v[168:171], v[180:183], v[112:115]
	v_mfma_f32_16x16x32_bf16 v[100:103], v[160:163], v[188:191], v[100:103]
	v_mfma_f32_16x16x32_bf16 v[96:99], v[168:171], v[188:191], v[96:99]
	v_mfma_f32_16x16x32_bf16 v[84:87], v[160:163], v[210:213], v[84:87]
	v_mfma_f32_16x16x32_bf16 v[80:83], v[168:171], v[210:213], v[80:83]
	v_mfma_f32_16x16x32_bf16 v[68:71], v[160:163], v[218:221], v[68:71]
	v_mfma_f32_16x16x32_bf16 v[64:67], v[168:171], v[218:221], v[64:67]
	s_setprio 0
	s_barrier
	s_add_i32 s14, s43, s39
	v_lshl_add_u64 v[194:195], v[194:195], 0, s[16:17]
	s_mov_b32 m0, s14
	ds_read_b128 v[172:175], v179 offset:49152
	ds_read_b128 v[180:183], v179 offset:50176
	ds_read_b128 v[184:187], v179 offset:51200
	ds_read_b128 v[188:191], v179 offset:52224
	ds_read_b128 v[206:209], v179 offset:53248
	ds_read_b128 v[210:213], v179 offset:54272
	ds_read_b128 v[214:217], v179 offset:55296
	ds_read_b128 v[218:221], v179 offset:56320
	global_load_lds_dwordx4 v[194:195], off
	s_add_i32 m0, s14, 0x2000
	s_add_u32 s12, s12, 0x80080
	v_lshl_add_u64 v[194:195], v[196:197], 0, s[16:17]
	s_addc_u32 s13, s13, 0
	s_add_i32 s14, s65, s39
	global_load_lds_dwordx4 v[194:195], off
	s_mov_b32 m0, s14
	v_lshl_add_u64 v[194:195], s[12:13], 0, v[138:139]
	global_load_lds_dwordx4 v[194:195], off
	s_add_i32 m0, s14, 0x2000
	v_lshl_add_u64 v[194:195], s[12:13], 0, v[142:143]
	global_load_lds_dwordx4 v[194:195], off
	s_mov_b32 m0, s80
	v_lshl_add_u64 v[194:195], v[202:203], 0, s[16:17]
	global_load_lds_dwordx4 v[194:195], off
	s_mov_b32 m0, s81
	v_lshl_add_u64 v[194:195], v[204:205], 0, s[16:17]
	global_load_lds_dwordx4 v[194:195], off
	s_waitcnt vmcnt(8)
	s_waitcnt lgkmcnt(0)
	s_barrier
	s_setprio 1
	s_waitcnt lgkmcnt(0)
	v_mfma_f32_16x16x32_bf16 v[60:63], v[128:131], v[172:175], v[60:63]
	v_mfma_f32_16x16x32_bf16 v[56:59], v[148:151], v[172:175], v[56:59]
	v_mfma_f32_16x16x32_bf16 v[44:47], v[128:131], v[184:187], v[44:47]
	v_mfma_f32_16x16x32_bf16 v[40:43], v[148:151], v[184:187], v[40:43]
	v_mfma_f32_16x16x32_bf16 v[28:31], v[128:131], v[206:209], v[28:31]
	v_mfma_f32_16x16x32_bf16 v[24:27], v[148:151], v[206:209], v[24:27]
	v_mfma_f32_16x16x32_bf16 v[12:15], v[128:131], v[214:217], v[12:15]
	v_mfma_f32_16x16x32_bf16 v[8:11], v[148:151], v[214:217], v[8:11]
	v_mfma_f32_16x16x32_bf16 v[60:63], v[132:135], v[180:183], v[60:63]
	v_mfma_f32_16x16x32_bf16 v[56:59], v[152:155], v[180:183], v[56:59]
	v_mfma_f32_16x16x32_bf16 v[44:47], v[132:135], v[188:191], v[44:47]
	v_mfma_f32_16x16x32_bf16 v[40:43], v[152:155], v[188:191], v[40:43]
	v_mfma_f32_16x16x32_bf16 v[28:31], v[132:135], v[210:213], v[28:31]
	v_mfma_f32_16x16x32_bf16 v[24:27], v[152:155], v[210:213], v[24:27]
	v_mfma_f32_16x16x32_bf16 v[12:15], v[132:135], v[218:221], v[12:15]
	v_mfma_f32_16x16x32_bf16 v[8:11], v[152:155], v[218:221], v[8:11]
	s_setprio 0
	s_setprio 1
	v_mfma_f32_16x16x32_bf16 v[52:55], v[156:159], v[172:175], v[52:55]
	v_mfma_f32_16x16x32_bf16 v[48:51], v[164:167], v[172:175], v[48:51]
	v_mfma_f32_16x16x32_bf16 v[36:39], v[156:159], v[184:187], v[36:39]
	v_mfma_f32_16x16x32_bf16 v[32:35], v[164:167], v[184:187], v[32:35]
	v_mfma_f32_16x16x32_bf16 v[20:23], v[156:159], v[206:209], v[20:23]
	v_mfma_f32_16x16x32_bf16 v[16:19], v[164:167], v[206:209], v[16:19]
	v_mfma_f32_16x16x32_bf16 v[4:7], v[156:159], v[214:217], v[4:7]
	v_mfma_f32_16x16x32_bf16 v[0:3], v[164:167], v[214:217], v[0:3]
	v_mfma_f32_16x16x32_bf16 v[52:55], v[160:163], v[180:183], v[52:55]
	v_mfma_f32_16x16x32_bf16 v[48:51], v[168:171], v[180:183], v[48:51]
	v_mfma_f32_16x16x32_bf16 v[36:39], v[160:163], v[188:191], v[36:39]
	v_mfma_f32_16x16x32_bf16 v[32:35], v[168:171], v[188:191], v[32:35]
	v_mfma_f32_16x16x32_bf16 v[20:23], v[160:163], v[210:213], v[20:23]
	v_mfma_f32_16x16x32_bf16 v[16:19], v[168:171], v[210:213], v[16:19]
	v_mfma_f32_16x16x32_bf16 v[4:7], v[160:163], v[218:221], v[4:7]
	v_mfma_f32_16x16x32_bf16 v[0:3], v[168:171], v[218:221], v[0:3]
	s_setprio 0
	s_add_i32 s42, s42, 2
	s_add_u32 s0, s0, 0x100
	s_addc_u32 s1, s1, 0
	s_add_u32 s34, s34, 0x100
	s_addc_u32 s41, s41, 0
	s_cmp_gt_u32 s42, 29
	s_barrier
	s_cbranch_scc0 .LBB0_129
	s_and_b64 vcc, exec, s[62:63]
	s_cbranch_vccz .LBB0_132
	s_barrier

; #define PG8_STAGE(bufoff, gbase, voff) do { _Pragma("unroll") for (int _i = 0; _i < 2; ++_i) \
;         __builtin_amdgcn_global_load_lds((const unsigned*)((const char*)(gbase) + (voff)[_i]), (PG8_LAS unsigned*)(lds + (bufoff) + ldsw + _i * 8192), 16, 0, 0); } while (0)
; #define PG8_LDA(dst, b, h) do { _Pragma("unroll") for (int m = 0; m < 4; ++m) _Pragma("unroll") for (int k = 0; k < 2; ++k) dst[m][k] = *(const PG8_LAS bf16x8*)(lds + PG8_SA(b, h) + aoff + m * 2048 + k * 1024); } while (0)
; #define PG8_LDB(dst, b, h) do { _Pragma("unroll") for (int n = 0; n < 2; ++n) _Pragma("unroll") for (int k = 0; k < 2; ++k) dst[n][k] = *(const PG8_LAS bf16x8*)(lds + PG8_SB(b, h) + boff + n * 2048 + k * 1024); } while (0)
; #define PG8_WAIT_V(n) asm volatile("s_waitcnt vmcnt(" #n ")" ::: "memory")
; #define PG8_WAIT_L(n) asm volatile("s_waitcnt lgkmcnt(" #n ")" ::: "memory")
; #define PG8_BAR __builtin_amdgcn_s_barrier()
; #define PG8_SCHED __builtin_amdgcn_sched_barrier(0)
; template <class Epi, class Sched, bool ALIGN_EPI = false, bool SP2 = false>
; __device__ __forceinline__ void gemm_phase(PG8_LAS unsigned char* lds, const Gemm g, const Sched& S, const Epi& E) {
;     ...
;         const char* nA = has_next ? (const char*)g.A + (size_t)nxt.pm * tstep : cA; const char* nB = has_next ? (const char*)g.Bt + (size_t)nxt.pn * tstep : cB;
;         for (int t = 0; t < nt; t += 2) {
;             if constexpr (Epi::MID_HOOK) { if (t == Epi::MID_T) E.mid(acc, cur, wr, wc, fr, fq); }
;             const bool last = (t == nt - 2);
;             const char* a1 = cA + (size_t)(t + 1) * kstep;
;             const char* a2 = last ? nA : cA + (size_t)(t + 2) * kstep; const char* b2 = last ? nB : cB + (size_t)(t + 2) * kstep;
;             const char* a3 = a2 + kstep; const char* b3 = b2 + kstep;
;             if (last && has_next) S.a_ready(nxt);
;             if constexpr (SP2) {
;             PG8_LDB(B0, 0, 0); PG8_LDB(B1, 0, 1); PG8_SCHED; PG8_LDA(At, 0, 0); PG8_STAGE(PG8_SA(1, 1), a1 + hstep, voffA);
;             PG8_WAIT_V(8); PG8_WAIT_L(0); PG8_BAR; PG8_MMA(0, 0, At, B0); PG8_MMA(0, 1, At, B1); PG8_BAR; PG8_SCHED;
;             PG8_LDA(At, 0, 1); PG8_STAGE(PG8_SB(0, 0), b2, voffB); PG8_STAGE(PG8_SB(0, 1), b2 + hstep, voffB); PG8_STAGE(PG8_SA(0, 0), a2, voffA);
;             PG8_WAIT_V(8); PG8_WAIT_L(0); PG8_BAR; PG8_MMA(1, 0, At, B0); PG8_MMA(1, 1, At, B1); PG8_BAR; PG8_SCHED;
.LBB0_634:
	s_ashr_i32 s15, s14, 31
	s_lshl_b64 s[18:19], s[14:15], 20
	s_add_u32 s18, s45, s18
	s_addc_u32 s19, s46, s19
	s_and_b64 s[30:31], s[0:1], exec
	s_cselect_b32 s15, s19, s37
	s_cselect_b32 s61, s18, s36
	s_ashr_i32 s13, s12, 31
	s_lshl_b64 s[30:31], s[12:13], 20
	s_add_u32 s30, s34, s30
	s_addc_u32 s31, s44, s31
	s_and_b64 s[42:43], s[0:1], exec
	s_cselect_b32 s13, s31, s39
	s_cselect_b32 s62, s30, s38
	s_add_u32 s36, s36, 0x80080
	s_addc_u32 s37, s37, 0
	s_add_u32 s63, s38, 0x100
	s_addc_u32 s64, s39, 0
	s_mov_b32 s65, -2
	s_waitcnt lgkmcnt(0)
	v_lshl_add_u64 v[168:169], s[36:37], 0, v[160:161]
	s_add_i32 m0, s2, 0xc000
	global_load_lds_dwordx4 v[168:169], off
	s_add_i32 m0, s2, 0xe000
	v_lshl_add_u64 v[168:169], s[36:37], 0, v[162:163]
	global_load_lds_dwordx4 v[168:169], off
	s_add_u32 s24, s36, 0xfff80080
	s_addc_u32 s25, s37, -1
	s_add_i32 s33, 0, 0x10000
	s_cmp_eq_u32 s65, 28
	s_cselect_b32 s43, s15, s25
	s_cselect_b32 s42, s61, s24
	s_cselect_b32 s39, s13, s64
	s_cselect_b32 s38, s62, s63
	s_add_i32 s24, 0, 0x14000
	s_waitcnt vmcnt(8)
	s_waitcnt lgkmcnt(0)
	s_barrier
	s_setprio 1
	s_waitcnt lgkmcnt(0)
	v_mfma_f32_16x16x32_bf16 v[124:127], v[128:131], v[178:181], 0
	v_mfma_f32_16x16x32_bf16 v[120:123], v[136:139], v[178:181], 0
	v_mfma_f32_16x16x32_bf16 v[108:111], v[128:131], v[186:189], 0
	v_mfma_f32_16x16x32_bf16 v[104:107], v[136:139], v[186:189], 0
	v_mfma_f32_16x16x32_bf16 v[92:95], v[128:131], v[202:205], 0
	v_mfma_f32_16x16x32_bf16 v[88:91], v[136:139], v[202:205], 0
	v_mfma_f32_16x16x32_bf16 v[76:79], v[128:131], v[210:213], 0
	v_mfma_f32_16x16x32_bf16 v[72:75], v[136:139], v[210:213], 0
	v_mfma_f32_16x16x32_bf16 v[124:127], v[132:135], v[182:185], v[124:127]
	v_mfma_f32_16x16x32_bf16 v[120:123], v[140:143], v[182:185], v[120:123]
	v_mfma_f32_16x16x32_bf16 v[108:111], v[132:135], v[194:197], v[108:111]
	v_mfma_f32_16x16x32_bf16 v[104:107], v[140:143], v[194:197], v[104:107]
	v_mfma_f32_16x16x32_bf16 v[92:95], v[132:135], v[206:209], v[92:95]
	v_mfma_f32_16x16x32_bf16 v[88:91], v[140:143], v[206:209], v[88:91]
	v_mfma_f32_16x16x32_bf16 v[76:79], v[132:135], v[214:217], v[76:79]
	v_mfma_f32_16x16x32_bf16 v[72:75], v[140:143], v[214:217], v[72:75]
	s_setprio 0
	s_setprio 1
	v_mfma_f32_16x16x32_bf16 v[116:119], v[144:147], v[178:181], 0
	v_mfma_f32_16x16x32_bf16 v[112:115], v[164:167], v[178:181], 0
	v_mfma_f32_16x16x32_bf16 v[100:103], v[144:147], v[186:189], 0
	v_mfma_f32_16x16x32_bf16 v[96:99], v[164:167], v[186:189], 0
	v_mfma_f32_16x16x32_bf16 v[84:87], v[144:147], v[202:205], 0
	v_mfma_f32_16x16x32_bf16 v[80:83], v[164:167], v[202:205], 0
	v_mfma_f32_16x16x32_bf16 v[68:71], v[144:147], v[210:213], 0
	v_mfma_f32_16x16x32_bf16 v[64:67], v[164:167], v[210:213], 0
	v_mfma_f32_16x16x32_bf16 v[116:119], v[148:151], v[182:185], v[116:119]
	v_mfma_f32_16x16x32_bf16 v[112:115], v[174:177], v[182:185], v[112:115]
	v_mfma_f32_16x16x32_bf16 v[100:103], v[148:151], v[194:197], v[100:103]
	v_mfma_f32_16x16x32_bf16 v[96:99], v[174:177], v[194:197], v[96:99]
	v_mfma_f32_16x16x32_bf16 v[84:87], v[148:151], v[206:209], v[84:87]
	v_mfma_f32_16x16x32_bf16 v[80:83], v[174:177], v[206:209], v[80:83]
	v_mfma_f32_16x16x32_bf16 v[68:71], v[148:151], v[214:217], v[68:71]
	v_mfma_f32_16x16x32_bf16 v[64:67], v[174:177], v[214:217], v[64:67]
	s_setprio 0
	s_barrier
	s_add_i32 s25, s33, s47
	v_lshl_add_u64 v[168:169], s[38:39], 0, v[156:157]
	s_mov_b32 m0, s25
	ds_read_b128 v[178:181], v173 offset:16384
	ds_read_b128 v[182:185], v173 offset:17408
	ds_read_b128 v[186:189], v173 offset:18432
	ds_read_b128 v[194:197], v173 offset:19456
	ds_read_b128 v[202:205], v173 offset:20480
	ds_read_b128 v[206:209], v173 offset:21504
	ds_read_b128 v[210:213], v173 offset:22528
	ds_read_b128 v[214:217], v173 offset:23552
	global_load_lds_dwordx4 v[168:169], off
	s_add_i32 m0, s25, 0x2000
	s_add_u32 s66, s38, 0x80000
	v_lshl_add_u64 v[190:191], s[38:39], 0, v[152:153]
	s_addc_u32 s67, s39, 0
	s_add_i32 s24, s24, s47
	global_load_lds_dwordx4 v[190:191], off
	v_lshl_add_u64 v[218:219], s[66:67], 0, v[156:157]
	s_mov_b32 m0, s24
	v_lshl_add_u64 v[220:221], s[42:43], 0, v[154:155]
	global_load_lds_dwordx4 v[218:219], off
	s_add_i32 m0, s24, 0x2000
	v_lshl_add_u64 v[218:219], s[66:67], 0, v[152:153]
	global_load_lds_dwordx4 v[218:219], off
	s_mov_b32 m0, s2
	v_lshl_add_u64 v[218:219], s[42:43], 0, v[158:159]
	global_load_lds_dwordx4 v[218:219], off
	s_mov_b32 m0, s48
	s_nop 0
	global_load_lds_dwordx4 v[220:221], off
	s_waitcnt vmcnt(8)
	s_waitcnt lgkmcnt(0)
	s_barrier
	s_setprio 1
	s_waitcnt lgkmcnt(0)
	v_mfma_f32_16x16x32_bf16 v[60:63], v[128:131], v[178:181], 0
	v_mfma_f32_16x16x32_bf16 v[56:59], v[136:139], v[178:181], 0
	v_mfma_f32_16x16x32_bf16 v[44:47], v[128:131], v[186:189], 0
	v_mfma_f32_16x16x32_bf16 v[40:43], v[136:139], v[186:189], 0
	v_mfma_f32_16x16x32_bf16 v[28:31], v[128:131], v[202:205], 0
	v_mfma_f32_16x16x32_bf16 v[24:27], v[136:139], v[202:205], 0
	v_mfma_f32_16x16x32_bf16 v[12:15], v[128:131], v[210:213], 0
	v_mfma_f32_16x16x32_bf16 v[8:11], v[136:139], v[210:213], 0
	v_mfma_f32_16x16x32_bf16 v[60:63], v[132:135], v[182:185], v[60:63]
	v_mfma_f32_16x16x32_bf16 v[56:59], v[140:143], v[182:185], v[56:59]
	v_mfma_f32_16x16x32_bf16 v[44:47], v[132:135], v[194:197], v[44:47]
	v_mfma_f32_16x16x32_bf16 v[40:43], v[140:143], v[194:197], v[40:43]
	v_mfma_f32_16x16x32_bf16 v[28:31], v[132:135], v[206:209], v[28:31]
	v_mfma_f32_16x16x32_bf16 v[24:27], v[140:143], v[206:209], v[24:27]
	v_mfma_f32_16x16x32_bf16 v[12:15], v[132:135], v[214:217], v[12:15]
	v_mfma_f32_16x16x32_bf16 v[8:11], v[140:143], v[214:217], v[8:11]
	s_setprio 0
	s_setprio 1
	v_mfma_f32_16x16x32_bf16 v[52:55], v[144:147], v[178:181], 0
	v_mfma_f32_16x16x32_bf16 v[48:51], v[164:167], v[178:181], 0
	v_mfma_f32_16x16x32_bf16 v[36:39], v[144:147], v[186:189], 0
	v_mfma_f32_16x16x32_bf16 v[32:35], v[164:167], v[186:189], 0
	v_mfma_f32_16x16x32_bf16 v[20:23], v[144:147], v[202:205], 0
	v_mfma_f32_16x16x32_bf16 v[16:19], v[164:167], v[202:205], 0
	v_mfma_f32_16x16x32_bf16 v[4:7], v[144:147], v[210:213], 0
	v_mfma_f32_16x16x32_bf16 v[0:3], v[164:167], v[210:213], 0
	v_mfma_f32_16x16x32_bf16 v[52:55], v[148:151], v[182:185], v[52:55]
	v_mfma_f32_16x16x32_bf16 v[48:51], v[174:177], v[182:185], v[48:51]
	v_mfma_f32_16x16x32_bf16 v[36:39], v[148:151], v[194:197], v[36:39]
	v_mfma_f32_16x16x32_bf16 v[32:35], v[174:177], v[194:197], v[32:35]
	v_mfma_f32_16x16x32_bf16 v[20:23], v[148:151], v[206:209], v[20:23]
	v_mfma_f32_16x16x32_bf16 v[16:19], v[174:177], v[206:209], v[16:19]
	v_mfma_f32_16x16x32_bf16 v[4:7], v[148:151], v[214:217], v[4:7]
	v_mfma_f32_16x16x32_bf16 v[0:3], v[174:177], v[214:217], v[0:3]
	s_setprio 0
	s_barrier
; #define PG8_STAGE(bufoff, gbase, voff) do { _Pragma("unroll") for (int _i = 0; _i < 2; ++_i) \
;         __builtin_amdgcn_global_load_lds((const unsigned*)((const char*)(gbase) + (voff)[_i]), (PG8_LAS unsigned*)(lds + (bufoff) + ldsw + _i * 8192), 16, 0, 0); } while (0)
; #define PG8_LDA(dst, b, h) do { _Pragma("unroll") for (int m = 0; m < 4; ++m) _Pragma("unroll") for (int k = 0; k < 2; ++k) dst[m][k] = *(const PG8_LAS bf16x8*)(lds + PG8_SA(b, h) + aoff + m * 2048 + k * 1024); } while (0)
; #define PG8_LDB(dst, b, h) do { _Pragma("unroll") for (int n = 0; n < 2; ++n) _Pragma("unroll") for (int k = 0; k < 2; ++k) dst[n][k] = *(const PG8_LAS bf16x8*)(lds + PG8_SB(b, h) + boff + n * 2048 + k * 1024); } while (0)
; #define PG8_MMA(ai, bj, At, Bt) do { __builtin_amdgcn_s_setprio(1); _Pragma("unroll") for (int m = 0; m < 4; ++m) _Pragma("unroll") for (int n = 0; n < 2; ++n) _Pragma("unroll") for (int k = 0; k < 2; ++k) \
;         acc[ai][bj][m][n] = __builtin_amdgcn_mfma_f32_16x16x32_bf16(Bt[n][k], At[m][k], acc[ai][bj][m][n], 0, 0, 0); __builtin_amdgcn_s_setprio(0); } while (0)
; #define PG8_WAIT_V(n) asm volatile("s_waitcnt vmcnt(" #n ")" ::: "memory")
; #define PG8_WAIT_L(n) asm volatile("s_waitcnt lgkmcnt(" #n ")" ::: "memory")
; #define PG8_BAR __builtin_amdgcn_s_barrier()
; #define PG8_SCHED __builtin_amdgcn_sched_barrier(0)
; template <class Epi, class Sched, bool ALIGN_EPI = false, bool SP2 = false>
; __device__ __forceinline__ void gemm_phase(PG8_LAS unsigned char* lds, const Gemm g, const Sched& S, const Epi& E) {
;     ...
;             PG8_LDB(B0, 1, 0); PG8_LDB(B1, 1, 1); PG8_SCHED; PG8_LDA(At, 1, 0); PG8_STAGE(PG8_SA(0, 1), a2 + hstep, voffA);
;             PG8_WAIT_V(8); PG8_WAIT_L(0); PG8_BAR; PG8_MMA(0, 0, At, B0); PG8_MMA(0, 1, At, B1); PG8_BAR; PG8_SCHED;
;             PG8_LDA(At, 1, 1); PG8_STAGE(PG8_SB(1, 0), b3, voffB); PG8_STAGE(PG8_SB(1, 1), b3 + hstep, voffB); PG8_STAGE(PG8_SA(1, 0), a3, voffA);
;             PG8_WAIT_V(8); PG8_WAIT_L(0); PG8_BAR; PG8_MMA(1, 0, At, B0); PG8_MMA(1, 1, At, B1); PG8_BAR; PG8_SCHED;
	s_add_i32 s24, 0, 0x18000
	s_add_i32 s25, 0, 0x1c000
	v_add_u32_e32 v140, 0x18000, v172
	v_add_u32_e32 v174, 0x1c000, v172
	ds_read_b128 v[128:131], v140
	ds_read_b128 v[132:135], v140 offset:1024
	ds_read_b128 v[136:139], v140 offset:2048
	ds_read_b128 v[140:143], v140 offset:3072
	ds_read_b128 v[144:147], v174
	ds_read_b128 v[148:151], v174 offset:1024
	ds_read_b128 v[164:167], v174 offset:2048
	ds_read_b128 v[174:177], v174 offset:3072
	s_add_u32 s42, s42, 0x80000
	s_addc_u32 s43, s43, 0
	s_mov_b32 m0, s49
	v_lshl_add_u64 v[230:231], s[42:43], 0, v[158:159]
	ds_read_b128 v[178:181], v173 offset:32768
	ds_read_b128 v[182:185], v173 offset:33792
	ds_read_b128 v[186:189], v173 offset:34816
	ds_read_b128 v[194:197], v173 offset:35840
	ds_read_b128 v[202:205], v173 offset:36864
	ds_read_b128 v[206:209], v173 offset:37888
	ds_read_b128 v[210:213], v173 offset:38912
	ds_read_b128 v[214:217], v173 offset:39936
	global_load_lds_dwordx4 v[230:231], off
	s_mov_b32 m0, s50
	v_lshl_add_u64 v[230:231], s[42:43], 0, v[154:155]
	global_load_lds_dwordx4 v[230:231], off
	s_waitcnt vmcnt(8)
	s_waitcnt lgkmcnt(0)
	s_barrier
	s_setprio 1
	s_waitcnt lgkmcnt(0)
	v_mfma_f32_16x16x32_bf16 v[124:127], v[128:131], v[178:181], v[124:127]
	v_mfma_f32_16x16x32_bf16 v[120:123], v[136:139], v[178:181], v[120:123]
	v_mfma_f32_16x16x32_bf16 v[108:111], v[128:131], v[186:189], v[108:111]
	v_mfma_f32_16x16x32_bf16 v[104:107], v[136:139], v[186:189], v[104:107]
	v_mfma_f32_16x16x32_bf16 v[92:95], v[128:131], v[202:205], v[92:95]
	v_mfma_f32_16x16x32_bf16 v[88:91], v[136:139], v[202:205], v[88:91]
	v_mfma_f32_16x16x32_bf16 v[76:79], v[128:131], v[210:213], v[76:79]
	v_mfma_f32_16x16x32_bf16 v[72:75], v[136:139], v[210:213], v[72:75]
	v_mfma_f32_16x16x32_bf16 v[124:127], v[132:135], v[182:185], v[124:127]
	v_mfma_f32_16x16x32_bf16 v[120:123], v[140:143], v[182:185], v[120:123]
	v_mfma_f32_16x16x32_bf16 v[108:111], v[132:135], v[194:197], v[108:111]
	v_mfma_f32_16x16x32_bf16 v[104:107], v[140:143], v[194:197], v[104:107]
	v_mfma_f32_16x16x32_bf16 v[92:95], v[132:135], v[206:209], v[92:95]
	v_mfma_f32_16x16x32_bf16 v[88:91], v[140:143], v[206:209], v[88:91]
	v_mfma_f32_16x16x32_bf16 v[76:79], v[132:135], v[214:217], v[76:79]
	v_mfma_f32_16x16x32_bf16 v[72:75], v[140:143], v[214:217], v[72:75]
	s_setprio 0
	s_setprio 1
	v_mfma_f32_16x16x32_bf16 v[116:119], v[144:147], v[178:181], v[116:119]
	v_mfma_f32_16x16x32_bf16 v[112:115], v[164:167], v[178:181], v[112:115]
	v_mfma_f32_16x16x32_bf16 v[100:103], v[144:147], v[186:189], v[100:103]
	v_mfma_f32_16x16x32_bf16 v[96:99], v[164:167], v[186:189], v[96:99]
	v_mfma_f32_16x16x32_bf16 v[84:87], v[144:147], v[202:205], v[84:87]
	v_mfma_f32_16x16x32_bf16 v[80:83], v[164:167], v[202:205], v[80:83]
	v_mfma_f32_16x16x32_bf16 v[68:71], v[144:147], v[210:213], v[68:71]
	v_mfma_f32_16x16x32_bf16 v[64:67], v[164:167], v[210:213], v[64:67]
	v_mfma_f32_16x16x32_bf16 v[116:119], v[148:151], v[182:185], v[116:119]
	v_mfma_f32_16x16x32_bf16 v[112:115], v[174:177], v[182:185], v[112:115]
	v_mfma_f32_16x16x32_bf16 v[100:103], v[148:151], v[194:197], v[100:103]
	v_mfma_f32_16x16x32_bf16 v[96:99], v[174:177], v[194:197], v[96:99]
	v_mfma_f32_16x16x32_bf16 v[84:87], v[148:151], v[206:209], v[84:87]
	v_mfma_f32_16x16x32_bf16 v[80:83], v[174:177], v[206:209], v[80:83]
	v_mfma_f32_16x16x32_bf16 v[68:71], v[148:151], v[214:217], v[68:71]
	v_mfma_f32_16x16x32_bf16 v[64:67], v[174:177], v[214:217], v[64:67]
	s_setprio 0
	s_barrier
	s_add_i32 s24, s24, s47
	v_lshl_add_u64 v[168:169], v[168:169], 0, s[16:17]
	s_mov_b32 m0, s24
	ds_read_b128 v[178:181], v173 offset:49152
	ds_read_b128 v[182:185], v173 offset:50176
	ds_read_b128 v[186:189], v173 offset:51200
	ds_read_b128 v[194:197], v173 offset:52224
	ds_read_b128 v[202:205], v173 offset:53248
	ds_read_b128 v[206:209], v173 offset:54272
	ds_read_b128 v[210:213], v173 offset:55296
	ds_read_b128 v[214:217], v173 offset:56320
	global_load_lds_dwordx4 v[168:169], off
	s_add_i32 m0, s24, 0x2000
	s_add_u32 s38, s38, 0x80080
	v_lshl_add_u64 v[168:169], v[190:191], 0, s[16:17]
	s_addc_u32 s39, s39, 0
	s_add_i32 s24, s25, s47
	global_load_lds_dwordx4 v[168:169], off
	s_mov_b32 m0, s24
	v_lshl_add_u64 v[168:169], s[38:39], 0, v[156:157]
	global_load_lds_dwordx4 v[168:169], off
	s_add_i32 m0, s24, 0x2000
	v_lshl_add_u64 v[168:169], s[38:39], 0, v[152:153]
	global_load_lds_dwordx4 v[168:169], off
	s_mov_b32 m0, s55
	v_lshl_add_u64 v[168:169], v[218:219], 0, s[16:17]
	global_load_lds_dwordx4 v[168:169], off
	s_mov_b32 m0, s56
	v_lshl_add_u64 v[168:169], v[220:221], 0, s[16:17]
	global_load_lds_dwordx4 v[168:169], off
	s_waitcnt vmcnt(8)
	s_waitcnt lgkmcnt(0)
	s_barrier
; #define PG8_STAGE(bufoff, gbase, voff) do { _Pragma("unroll") for (int _i = 0; _i < 2; ++_i) \
;         __builtin_amdgcn_global_load_lds((const unsigned*)((const char*)(gbase) + (voff)[_i]), (PG8_LAS unsigned*)(lds + (bufoff) + ldsw + _i * 8192), 16, 0, 0); } while (0)
; #define PG8_LDA(dst, b, h) do { _Pragma("unroll") for (int m = 0; m < 4; ++m) _Pragma("unroll") for (int k = 0; k < 2; ++k) dst[m][k] = *(const PG8_LAS bf16x8*)(lds + PG8_SA(b, h) + aoff + m * 2048 + k * 1024); } while (0)
; #define PG8_LDB(dst, b, h) do { _Pragma("unroll") for (int n = 0; n < 2; ++n) _Pragma("unroll") for (int k = 0; k < 2; ++k) dst[n][k] = *(const PG8_LAS bf16x8*)(lds + PG8_SB(b, h) + boff + n * 2048 + k * 1024); } while (0)
; #define PG8_MMA(ai, bj, At, Bt) do { __builtin_amdgcn_s_setprio(1); _Pragma("unroll") for (int m = 0; m < 4; ++m) _Pragma("unroll") for (int n = 0; n < 2; ++n) _Pragma("unroll") for (int k = 0; k < 2; ++k) \
;         acc[ai][bj][m][n] = __builtin_amdgcn_mfma_f32_16x16x32_bf16(Bt[n][k], At[m][k], acc[ai][bj][m][n], 0, 0, 0); __builtin_amdgcn_s_setprio(0); } while (0)
; #define PG8_WAIT_V(n) asm volatile("s_waitcnt vmcnt(" #n ")" ::: "memory")
; template <class Epi, class Sched, bool ALIGN_EPI = false, bool SP2 = false>
; __device__ __forceinline__ void gemm_phase(PG8_LAS unsigned char* lds, const Gemm g, const Sched& S, const Epi& E) {
;     ...
;             PG8_LDB(B0, 0, 0); PG8_LDB(B1, 0, 1); PG8_SCHED; PG8_LDA(At, 0, 0); PG8_STAGE(PG8_SA(1, 1), a1 + hstep, voffA);
;             PG8_WAIT_V(8); PG8_WAIT_L(0); PG8_BAR; PG8_MMA(0, 0, At, B0); PG8_MMA(0, 1, At, B1); PG8_BAR; PG8_SCHED;
;             PG8_LDA(At, 0, 1); PG8_STAGE(PG8_SB(0, 0), b2, voffB); PG8_STAGE(PG8_SB(0, 1), b2 + hstep, voffB); PG8_STAGE(PG8_SA(0, 0), a2, voffA);
;             PG8_WAIT_V(8); PG8_WAIT_L(0); PG8_BAR; PG8_MMA(1, 0, At, B0); PG8_MMA(1, 1, At, B1); PG8_BAR; PG8_SCHED;
;             PG8_LDB(B0, 1, 0); PG8_LDB(B1, 1, 1); PG8_SCHED; PG8_LDA(At, 1, 0); PG8_STAGE(PG8_SA(0, 1), a2 + hstep, voffA);
;             PG8_WAIT_V(8); PG8_WAIT_L(0); PG8_BAR; PG8_MMA(0, 0, At, B0); PG8_MMA(0, 1, At, B1); PG8_BAR; PG8_SCHED;
;             PG8_LDA(At, 1, 1); PG8_STAGE(PG8_SB(1, 0), b3, voffB); PG8_STAGE(PG8_SB(1, 1), b3 + hstep, voffB); PG8_STAGE(PG8_SA(1, 0), a3, voffA);
;             PG8_WAIT_V(8); PG8_WAIT_L(0); PG8_BAR; PG8_MMA(1, 0, At, B0); PG8_MMA(1, 1, At, B1); PG8_BAR; PG8_SCHED;
	s_setprio 1
	s_waitcnt lgkmcnt(0)
	v_mfma_f32_16x16x32_bf16 v[60:63], v[128:131], v[178:181], v[60:63]
	v_mfma_f32_16x16x32_bf16 v[56:59], v[136:139], v[178:181], v[56:59]
	v_mfma_f32_16x16x32_bf16 v[44:47], v[128:131], v[186:189], v[44:47]
	v_mfma_f32_16x16x32_bf16 v[40:43], v[136:139], v[186:189], v[40:43]
	v_mfma_f32_16x16x32_bf16 v[28:31], v[128:131], v[202:205], v[28:31]
	v_mfma_f32_16x16x32_bf16 v[24:27], v[136:139], v[202:205], v[24:27]
	v_mfma_f32_16x16x32_bf16 v[12:15], v[128:131], v[210:213], v[12:15]
	v_mfma_f32_16x16x32_bf16 v[8:11], v[136:139], v[210:213], v[8:11]
	v_mfma_f32_16x16x32_bf16 v[60:63], v[132:135], v[182:185], v[60:63]
	v_mfma_f32_16x16x32_bf16 v[56:59], v[140:143], v[182:185], v[56:59]
	v_mfma_f32_16x16x32_bf16 v[44:47], v[132:135], v[194:197], v[44:47]
	v_mfma_f32_16x16x32_bf16 v[40:43], v[140:143], v[194:197], v[40:43]
	v_mfma_f32_16x16x32_bf16 v[28:31], v[132:135], v[206:209], v[28:31]
	v_mfma_f32_16x16x32_bf16 v[24:27], v[140:143], v[206:209], v[24:27]
	v_mfma_f32_16x16x32_bf16 v[12:15], v[132:135], v[214:217], v[12:15]
	v_mfma_f32_16x16x32_bf16 v[8:11], v[140:143], v[214:217], v[8:11]
	s_setprio 0
	s_setprio 1
	v_mfma_f32_16x16x32_bf16 v[52:55], v[144:147], v[178:181], v[52:55]
	v_mfma_f32_16x16x32_bf16 v[48:51], v[164:167], v[178:181], v[48:51]
	v_mfma_f32_16x16x32_bf16 v[36:39], v[144:147], v[186:189], v[36:39]
	v_mfma_f32_16x16x32_bf16 v[32:35], v[164:167], v[186:189], v[32:35]
	v_mfma_f32_16x16x32_bf16 v[20:23], v[144:147], v[202:205], v[20:23]
	v_mfma_f32_16x16x32_bf16 v[16:19], v[164:167], v[202:205], v[16:19]
	v_mfma_f32_16x16x32_bf16 v[4:7], v[144:147], v[210:213], v[4:7]
	v_mfma_f32_16x16x32_bf16 v[0:3], v[164:167], v[210:213], v[0:3]
	v_mfma_f32_16x16x32_bf16 v[52:55], v[148:151], v[182:185], v[52:55]
	v_mfma_f32_16x16x32_bf16 v[48:51], v[174:177], v[182:185], v[48:51]
	v_mfma_f32_16x16x32_bf16 v[36:39], v[148:151], v[194:197], v[36:39]
	v_mfma_f32_16x16x32_bf16 v[32:35], v[174:177], v[194:197], v[32:35]
	v_mfma_f32_16x16x32_bf16 v[20:23], v[148:151], v[206:209], v[20:23]
	v_mfma_f32_16x16x32_bf16 v[16:19], v[174:177], v[206:209], v[16:19]
	v_mfma_f32_16x16x32_bf16 v[4:7], v[148:151], v[214:217], v[4:7]
	v_mfma_f32_16x16x32_bf16 v[0:3], v[174:177], v[214:217], v[0:3]
	s_setprio 0
	s_add_i32 s65, s65, 2
	s_add_u32 s36, s36, 0x100
	s_addc_u32 s37, s37, 0
	s_add_u32 s63, s63, 0x100
	s_addc_u32 s64, s64, 0
	s_cmp_gt_u32 s65, 29
	s_barrier
.LBB0_635:
	v_add_u32_e32 v140, 0x10000, v172
	v_add_u32_e32 v168, 0x14000, v172
	ds_read_b128 v[128:131], v140
	ds_read_b128 v[132:135], v140 offset:1024
	ds_read_b128 v[136:139], v140 offset:2048
	ds_read_b128 v[140:143], v140 offset:3072
	ds_read_b128 v[144:147], v168
	ds_read_b128 v[148:151], v168 offset:1024
	ds_read_b128 v[164:167], v168 offset:2048
	ds_read_b128 v[174:177], v168 offset:3072
	v_lshl_add_u64 v[168:169], s[36:37], 0, v[160:161]
	s_add_i32 m0, s2, 0xc000
	ds_read_b128 v[178:181], v173
	ds_read_b128 v[182:185], v173 offset:1024
	ds_read_b128 v[186:189], v173 offset:2048
	ds_read_b128 v[194:197], v173 offset:3072
	ds_read_b128 v[202:205], v173 offset:4096
	ds_read_b128 v[206:209], v173 offset:5120
	ds_read_b128 v[210:213], v173 offset:6144
	ds_read_b128 v[214:217], v173 offset:7168
	global_load_lds_dwordx4 v[168:169], off
	s_add_i32 m0, s2, 0xe000
	v_lshl_add_u64 v[168:169], s[36:37], 0, v[162:163]
	global_load_lds_dwordx4 v[168:169], off
	s_add_u32 s24, s36, 0xfff80080
	s_addc_u32 s25, s37, -1
	s_add_i32 s33, 0, 0x10000
	s_cmp_eq_u32 s65, 28
	s_cselect_b32 s43, s15, s25
	s_cselect_b32 s42, s61, s24
	s_cselect_b32 s39, s13, s64
	s_cselect_b32 s38, s62, s63
	s_add_i32 s24, 0, 0x14000
	s_waitcnt vmcnt(8)
	s_waitcnt lgkmcnt(0)
	s_barrier
	s_setprio 1
	s_waitcnt lgkmcnt(0)
	v_mfma_f32_16x16x32_bf16 v[124:127], v[128:131], v[178:181], v[124:127]
	v_mfma_f32_16x16x32_bf16 v[120:123], v[136:139], v[178:181], v[120:123]
	v_mfma_f32_16x16x32_bf16 v[108:111], v[128:131], v[186:189], v[108:111]
	v_mfma_f32_16x16x32_bf16 v[104:107], v[136:139], v[186:189], v[104:107]
	v_mfma_f32_16x16x32_bf16 v[92:95], v[128:131], v[202:205], v[92:95]
	v_mfma_f32_16x16x32_bf16 v[88:91], v[136:139], v[202:205], v[88:91]
	v_mfma_f32_16x16x32_bf16 v[76:79], v[128:131], v[210:213], v[76:79]
	v_mfma_f32_16x16x32_bf16 v[72:75], v[136:139], v[210:213], v[72:75]
	v_mfma_f32_16x16x32_bf16 v[124:127], v[132:135], v[182:185], v[124:127]
	v_mfma_f32_16x16x32_bf16 v[120:123], v[140:143], v[182:185], v[120:123]
	v_mfma_f32_16x16x32_bf16 v[108:111], v[132:135], v[194:197], v[108:111]
	v_mfma_f32_16x16x32_bf16 v[104:107], v[140:143], v[194:197], v[104:107]
	v_mfma_f32_16x16x32_bf16 v[92:95], v[132:135], v[206:209], v[92:95]
	v_mfma_f32_16x16x32_bf16 v[88:91], v[140:143], v[206:209], v[88:91]
	v_mfma_f32_16x16x32_bf16 v[76:79], v[132:135], v[214:217], v[76:79]
	v_mfma_f32_16x16x32_bf16 v[72:75], v[140:143], v[214:217], v[72:75]
	s_setprio 0
	s_setprio 1
	v_mfma_f32_16x16x32_bf16 v[116:119], v[144:147], v[178:181], v[116:119]
	v_mfma_f32_16x16x32_bf16 v[112:115], v[164:167], v[178:181], v[112:115]
	v_mfma_f32_16x16x32_bf16 v[100:103], v[144:147], v[186:189], v[100:103]
	v_mfma_f32_16x16x32_bf16 v[96:99], v[164:167], v[186:189], v[96:99]
	v_mfma_f32_16x16x32_bf16 v[84:87], v[144:147], v[202:205], v[84:87]
	v_mfma_f32_16x16x32_bf16 v[80:83], v[164:167], v[202:205], v[80:83]
	v_mfma_f32_16x16x32_bf16 v[68:71], v[144:147], v[210:213], v[68:71]
	v_mfma_f32_16x16x32_bf16 v[64:67], v[164:167], v[210:213], v[64:67]
	v_mfma_f32_16x16x32_bf16 v[116:119], v[148:151], v[182:185], v[116:119]
	v_mfma_f32_16x16x32_bf16 v[112:115], v[174:177], v[182:185], v[112:115]
	v_mfma_f32_16x16x32_bf16 v[100:103], v[148:151], v[194:197], v[100:103]
	v_mfma_f32_16x16x32_bf16 v[96:99], v[174:177], v[194:197], v[96:99]
	v_mfma_f32_16x16x32_bf16 v[84:87], v[148:151], v[206:209], v[84:87]
	v_mfma_f32_16x16x32_bf16 v[80:83], v[174:177], v[206:209], v[80:83]
	v_mfma_f32_16x16x32_bf16 v[68:71], v[148:151], v[214:217], v[68:71]
	v_mfma_f32_16x16x32_bf16 v[64:67], v[174:177], v[214:217], v[64:67]
	s_setprio 0
	s_barrier
; #define PG8_STAGE(bufoff, gbase, voff) do { _Pragma("unroll") for (int _i = 0; _i < 2; ++_i) \
;         __builtin_amdgcn_global_load_lds((const unsigned*)((const char*)(gbase) + (voff)[_i]), (PG8_LAS unsigned*)(lds + (bufoff) + ldsw + _i * 8192), 16, 0, 0); } while (0)
; #define PG8_LDA(dst, b, h) do { _Pragma("unroll") for (int m = 0; m < 4; ++m) _Pragma("unroll") for (int k = 0; k < 2; ++k) dst[m][k] = *(const PG8_LAS bf16x8*)(lds + PG8_SA(b, h) + aoff + m * 2048 + k * 1024); } while (0)
; #define PG8_LDB(dst, b, h) do { _Pragma("unroll") for (int n = 0; n < 2; ++n) _Pragma("unroll") for (int k = 0; k < 2; ++k) dst[n][k] = *(const PG8_LAS bf16x8*)(lds + PG8_SB(b, h) + boff + n * 2048 + k * 1024); } while (0)
; #define PG8_MMA(ai, bj, At, Bt) do { __builtin_amdgcn_s_setprio(1); _Pragma("unroll") for (int m = 0; m < 4; ++m) _Pragma("unroll") for (int n = 0; n < 2; ++n) _Pragma("unroll") for (int k = 0; k < 2; ++k) \
;         acc[ai][bj][m][n] = __builtin_amdgcn_mfma_f32_16x16x32_bf16(Bt[n][k], At[m][k], acc[ai][bj][m][n], 0, 0, 0); __builtin_amdgcn_s_setprio(0); } while (0)
; #define PG8_WAIT_V(n) asm volatile("s_waitcnt vmcnt(" #n ")" ::: "memory")
; #define PG8_WAIT_L(n) asm volatile("s_waitcnt lgkmcnt(" #n ")" ::: "memory")
; #define PG8_BAR __builtin_amdgcn_s_barrier()
; #define PG8_SCHED __builtin_amdgcn_sched_barrier(0)
; template <class Epi, class Sched, bool ALIGN_EPI = false, bool SP2 = false>
; __device__ __forceinline__ void gemm_phase(PG8_LAS unsigned char* lds, const Gemm g, const Sched& S, const Epi& E) {
;     ...
;             PG8_LDA(At, 0, 1); PG8_STAGE(PG8_SB(0, 0), b2, voffB); PG8_STAGE(PG8_SB(0, 1), b2 + hstep, voffB); PG8_STAGE(PG8_SA(0, 0), a2, voffA);
;             PG8_WAIT_V(8); PG8_WAIT_L(0); PG8_BAR; PG8_MMA(1, 0, At, B0); PG8_MMA(1, 1, At, B1); PG8_BAR; PG8_SCHED;
;             PG8_LDB(B0, 1, 0); PG8_LDB(B1, 1, 1); PG8_SCHED; PG8_LDA(At, 1, 0); PG8_STAGE(PG8_SA(0, 1), a2 + hstep, voffA);
;             PG8_WAIT_V(8); PG8_WAIT_L(0); PG8_BAR; PG8_MMA(0, 0, At, B0); PG8_MMA(0, 1, At, B1); PG8_BAR; PG8_SCHED;
	s_add_i32 s25, s33, s47
	v_lshl_add_u64 v[168:169], s[38:39], 0, v[156:157]
	s_mov_b32 m0, s25
	ds_read_b128 v[178:181], v173 offset:16384
	ds_read_b128 v[182:185], v173 offset:17408
	ds_read_b128 v[186:189], v173 offset:18432
	ds_read_b128 v[194:197], v173 offset:19456
	ds_read_b128 v[202:205], v173 offset:20480
	ds_read_b128 v[206:209], v173 offset:21504
	ds_read_b128 v[210:213], v173 offset:22528
	ds_read_b128 v[214:217], v173 offset:23552
	global_load_lds_dwordx4 v[168:169], off
	s_add_i32 m0, s25, 0x2000
	s_add_u32 s66, s38, 0x80000
	v_lshl_add_u64 v[190:191], s[38:39], 0, v[152:153]
	s_addc_u32 s67, s39, 0
	s_add_i32 s24, s24, s47
	global_load_lds_dwordx4 v[190:191], off
	v_lshl_add_u64 v[218:219], s[66:67], 0, v[156:157]
	s_mov_b32 m0, s24
	v_lshl_add_u64 v[220:221], s[42:43], 0, v[154:155]
	global_load_lds_dwordx4 v[218:219], off
	s_add_i32 m0, s24, 0x2000
	v_lshl_add_u64 v[218:219], s[66:67], 0, v[152:153]
	global_load_lds_dwordx4 v[218:219], off
	s_mov_b32 m0, s2
	v_lshl_add_u64 v[218:219], s[42:43], 0, v[158:159]
	global_load_lds_dwordx4 v[218:219], off
	s_mov_b32 m0, s48
	s_nop 0
	global_load_lds_dwordx4 v[220:221], off
	s_waitcnt vmcnt(8)
	s_waitcnt lgkmcnt(0)
	s_barrier
	s_setprio 1
	s_waitcnt lgkmcnt(0)
	v_mfma_f32_16x16x32_bf16 v[60:63], v[128:131], v[178:181], v[60:63]
	v_mfma_f32_16x16x32_bf16 v[56:59], v[136:139], v[178:181], v[56:59]
	v_mfma_f32_16x16x32_bf16 v[44:47], v[128:131], v[186:189], v[44:47]
	v_mfma_f32_16x16x32_bf16 v[40:43], v[136:139], v[186:189], v[40:43]
	v_mfma_f32_16x16x32_bf16 v[28:31], v[128:131], v[202:205], v[28:31]
	v_mfma_f32_16x16x32_bf16 v[24:27], v[136:139], v[202:205], v[24:27]
	v_mfma_f32_16x16x32_bf16 v[12:15], v[128:131], v[210:213], v[12:15]
	v_mfma_f32_16x16x32_bf16 v[8:11], v[136:139], v[210:213], v[8:11]
	v_mfma_f32_16x16x32_bf16 v[60:63], v[132:135], v[182:185], v[60:63]
	v_mfma_f32_16x16x32_bf16 v[56:59], v[140:143], v[182:185], v[56:59]
	v_mfma_f32_16x16x32_bf16 v[44:47], v[132:135], v[194:197], v[44:47]
	v_mfma_f32_16x16x32_bf16 v[40:43], v[140:143], v[194:197], v[40:43]
	v_mfma_f32_16x16x32_bf16 v[28:31], v[132:135], v[206:209], v[28:31]
	v_mfma_f32_16x16x32_bf16 v[24:27], v[140:143], v[206:209], v[24:27]
	v_mfma_f32_16x16x32_bf16 v[12:15], v[132:135], v[214:217], v[12:15]
	v_mfma_f32_16x16x32_bf16 v[8:11], v[140:143], v[214:217], v[8:11]
	s_setprio 0
	s_setprio 1
	v_mfma_f32_16x16x32_bf16 v[52:55], v[144:147], v[178:181], v[52:55]
	v_mfma_f32_16x16x32_bf16 v[48:51], v[164:167], v[178:181], v[48:51]
	v_mfma_f32_16x16x32_bf16 v[36:39], v[144:147], v[186:189], v[36:39]
	v_mfma_f32_16x16x32_bf16 v[32:35], v[164:167], v[186:189], v[32:35]
	v_mfma_f32_16x16x32_bf16 v[20:23], v[144:147], v[202:205], v[20:23]
	v_mfma_f32_16x16x32_bf16 v[16:19], v[164:167], v[202:205], v[16:19]
	v_mfma_f32_16x16x32_bf16 v[4:7], v[144:147], v[210:213], v[4:7]
	v_mfma_f32_16x16x32_bf16 v[0:3], v[164:167], v[210:213], v[0:3]
	v_mfma_f32_16x16x32_bf16 v[52:55], v[148:151], v[182:185], v[52:55]
	v_mfma_f32_16x16x32_bf16 v[48:51], v[174:177], v[182:185], v[48:51]
	v_mfma_f32_16x16x32_bf16 v[36:39], v[148:151], v[194:197], v[36:39]
	v_mfma_f32_16x16x32_bf16 v[32:35], v[174:177], v[194:197], v[32:35]
	v_mfma_f32_16x16x32_bf16 v[20:23], v[148:151], v[206:209], v[20:23]
	v_mfma_f32_16x16x32_bf16 v[16:19], v[174:177], v[206:209], v[16:19]
	v_mfma_f32_16x16x32_bf16 v[4:7], v[148:151], v[214:217], v[4:7]
	v_mfma_f32_16x16x32_bf16 v[0:3], v[174:177], v[214:217], v[0:3]
	s_setprio 0
	s_barrier
	s_add_i32 s24, 0, 0x18000
	s_add_i32 s25, 0, 0x1c000
	v_add_u32_e32 v140, 0x18000, v172
	v_add_u32_e32 v174, 0x1c000, v172
	ds_read_b128 v[128:131], v140
	ds_read_b128 v[132:135], v140 offset:1024
	ds_read_b128 v[136:139], v140 offset:2048
	ds_read_b128 v[140:143], v140 offset:3072
	ds_read_b128 v[144:147], v174
	ds_read_b128 v[148:151], v174 offset:1024
	ds_read_b128 v[164:167], v174 offset:2048
	ds_read_b128 v[174:177], v174 offset:3072
	s_add_u32 s42, s42, 0x80000
	s_addc_u32 s43, s43, 0
	s_mov_b32 m0, s49
	v_lshl_add_u64 v[230:231], s[42:43], 0, v[158:159]
	ds_read_b128 v[178:181], v173 offset:32768
	ds_read_b128 v[182:185], v173 offset:33792
	ds_read_b128 v[186:189], v173 offset:34816
	ds_read_b128 v[194:197], v173 offset:35840
	ds_read_b128 v[202:205], v173 offset:36864
	ds_read_b128 v[206:209], v173 offset:37888
	ds_read_b128 v[210:213], v173 offset:38912
	ds_read_b128 v[214:217], v173 offset:39936
	global_load_lds_dwordx4 v[230:231], off
	s_mov_b32 m0, s50
	v_lshl_add_u64 v[230:231], s[42:43], 0, v[154:155]
	global_load_lds_dwordx4 v[230:231], off
	s_waitcnt vmcnt(8)
	s_waitcnt lgkmcnt(0)
	s_barrier
; #define PG8_STAGE(bufoff, gbase, voff) do { _Pragma("unroll") for (int _i = 0; _i < 2; ++_i) \
;         __builtin_amdgcn_global_load_lds((const unsigned*)((const char*)(gbase) + (voff)[_i]), (PG8_LAS unsigned*)(lds + (bufoff) + ldsw + _i * 8192), 16, 0, 0); } while (0)
; #define PG8_LDA(dst, b, h) do { _Pragma("unroll") for (int m = 0; m < 4; ++m) _Pragma("unroll") for (int k = 0; k < 2; ++k) dst[m][k] = *(const PG8_LAS bf16x8*)(lds + PG8_SA(b, h) + aoff + m * 2048 + k * 1024); } while (0)
; #define PG8_MMA(ai, bj, At, Bt) do { __builtin_amdgcn_s_setprio(1); _Pragma("unroll") for (int m = 0; m < 4; ++m) _Pragma("unroll") for (int n = 0; n < 2; ++n) _Pragma("unroll") for (int k = 0; k < 2; ++k) \
;         acc[ai][bj][m][n] = __builtin_amdgcn_mfma_f32_16x16x32_bf16(Bt[n][k], At[m][k], acc[ai][bj][m][n], 0, 0, 0); __builtin_amdgcn_s_setprio(0); } while (0)
; #define PG8_WAIT_V(n) asm volatile("s_waitcnt vmcnt(" #n ")" ::: "memory")
; #define PG8_WAIT_L(n) asm volatile("s_waitcnt lgkmcnt(" #n ")" ::: "memory")
; #define PG8_BAR __builtin_amdgcn_s_barrier()
; #define PG8_SCHED __builtin_amdgcn_sched_barrier(0)
; template <class Epi, class Sched, bool ALIGN_EPI = false, bool SP2 = false>
; __device__ __forceinline__ void gemm_phase(PG8_LAS unsigned char* lds, const Gemm g, const Sched& S, const Epi& E) {
;     ...
;             PG8_WAIT_V(8); PG8_WAIT_L(0); PG8_BAR; PG8_MMA(0, 0, At, B0); PG8_MMA(0, 1, At, B1); PG8_BAR; PG8_SCHED;
;             PG8_LDA(At, 1, 1); PG8_STAGE(PG8_SB(1, 0), b3, voffB); PG8_STAGE(PG8_SB(1, 1), b3 + hstep, voffB); PG8_STAGE(PG8_SA(1, 0), a3, voffA);
;             PG8_WAIT_V(8); PG8_WAIT_L(0); PG8_BAR; PG8_MMA(1, 0, At, B0); PG8_MMA(1, 1, At, B1); PG8_BAR; PG8_SCHED;
	s_setprio 1
	s_waitcnt lgkmcnt(0)
	v_mfma_f32_16x16x32_bf16 v[124:127], v[128:131], v[178:181], v[124:127]
	v_mfma_f32_16x16x32_bf16 v[120:123], v[136:139], v[178:181], v[120:123]
	v_mfma_f32_16x16x32_bf16 v[108:111], v[128:131], v[186:189], v[108:111]
	v_mfma_f32_16x16x32_bf16 v[104:107], v[136:139], v[186:189], v[104:107]
	v_mfma_f32_16x16x32_bf16 v[92:95], v[128:131], v[202:205], v[92:95]
	v_mfma_f32_16x16x32_bf16 v[88:91], v[136:139], v[202:205], v[88:91]
	v_mfma_f32_16x16x32_bf16 v[76:79], v[128:131], v[210:213], v[76:79]
	v_mfma_f32_16x16x32_bf16 v[72:75], v[136:139], v[210:213], v[72:75]
	v_mfma_f32_16x16x32_bf16 v[124:127], v[132:135], v[182:185], v[124:127]
	v_mfma_f32_16x16x32_bf16 v[120:123], v[140:143], v[182:185], v[120:123]
	v_mfma_f32_16x16x32_bf16 v[108:111], v[132:135], v[194:197], v[108:111]
	v_mfma_f32_16x16x32_bf16 v[104:107], v[140:143], v[194:197], v[104:107]
	v_mfma_f32_16x16x32_bf16 v[92:95], v[132:135], v[206:209], v[92:95]
	v_mfma_f32_16x16x32_bf16 v[88:91], v[140:143], v[206:209], v[88:91]
	v_mfma_f32_16x16x32_bf16 v[76:79], v[132:135], v[214:217], v[76:79]
	v_mfma_f32_16x16x32_bf16 v[72:75], v[140:143], v[214:217], v[72:75]
	s_setprio 0
	s_setprio 1
	v_mfma_f32_16x16x32_bf16 v[116:119], v[144:147], v[178:181], v[116:119]
	v_mfma_f32_16x16x32_bf16 v[112:115], v[164:167], v[178:181], v[112:115]
	v_mfma_f32_16x16x32_bf16 v[100:103], v[144:147], v[186:189], v[100:103]
	v_mfma_f32_16x16x32_bf16 v[96:99], v[164:167], v[186:189], v[96:99]
	v_mfma_f32_16x16x32_bf16 v[84:87], v[144:147], v[202:205], v[84:87]
	v_mfma_f32_16x16x32_bf16 v[80:83], v[164:167], v[202:205], v[80:83]
	v_mfma_f32_16x16x32_bf16 v[68:71], v[144:147], v[210:213], v[68:71]
	v_mfma_f32_16x16x32_bf16 v[64:67], v[164:167], v[210:213], v[64:67]
	v_mfma_f32_16x16x32_bf16 v[116:119], v[148:151], v[182:185], v[116:119]
	v_mfma_f32_16x16x32_bf16 v[112:115], v[174:177], v[182:185], v[112:115]
	v_mfma_f32_16x16x32_bf16 v[100:103], v[148:151], v[194:197], v[100:103]
	v_mfma_f32_16x16x32_bf16 v[96:99], v[174:177], v[194:197], v[96:99]
	v_mfma_f32_16x16x32_bf16 v[84:87], v[148:151], v[206:209], v[84:87]
	v_mfma_f32_16x16x32_bf16 v[80:83], v[174:177], v[206:209], v[80:83]
	v_mfma_f32_16x16x32_bf16 v[68:71], v[148:151], v[214:217], v[68:71]
	v_mfma_f32_16x16x32_bf16 v[64:67], v[174:177], v[214:217], v[64:67]
	s_setprio 0
	s_barrier
	s_add_i32 s24, s24, s47
	v_lshl_add_u64 v[168:169], v[168:169], 0, s[16:17]
	s_mov_b32 m0, s24
	ds_read_b128 v[178:181], v173 offset:49152
	ds_read_b128 v[182:185], v173 offset:50176
	ds_read_b128 v[186:189], v173 offset:51200
	ds_read_b128 v[194:197], v173 offset:52224
	ds_read_b128 v[202:205], v173 offset:53248
	ds_read_b128 v[206:209], v173 offset:54272
	ds_read_b128 v[210:213], v173 offset:55296
	ds_read_b128 v[214:217], v173 offset:56320
	global_load_lds_dwordx4 v[168:169], off
	s_add_i32 m0, s24, 0x2000
	s_add_u32 s38, s38, 0x80080
	v_lshl_add_u64 v[168:169], v[190:191], 0, s[16:17]
	s_addc_u32 s39, s39, 0
	s_add_i32 s24, s25, s47
	global_load_lds_dwordx4 v[168:169], off
	s_mov_b32 m0, s24
	v_lshl_add_u64 v[168:169], s[38:39], 0, v[156:157]
	global_load_lds_dwordx4 v[168:169], off
	s_add_i32 m0, s24, 0x2000
	v_lshl_add_u64 v[168:169], s[38:39], 0, v[152:153]
	global_load_lds_dwordx4 v[168:169], off
	s_mov_b32 m0, s55
	v_lshl_add_u64 v[168:169], v[218:219], 0, s[16:17]
	global_load_lds_dwordx4 v[168:169], off
	s_mov_b32 m0, s56
	v_lshl_add_u64 v[168:169], v[220:221], 0, s[16:17]
	global_load_lds_dwordx4 v[168:169], off
	s_waitcnt vmcnt(8)
	s_waitcnt lgkmcnt(0)
	s_barrier
	s_setprio 1
	s_waitcnt lgkmcnt(0)
	v_mfma_f32_16x16x32_bf16 v[60:63], v[128:131], v[178:181], v[60:63]
	v_mfma_f32_16x16x32_bf16 v[56:59], v[136:139], v[178:181], v[56:59]
	v_mfma_f32_16x16x32_bf16 v[44:47], v[128:131], v[186:189], v[44:47]
	v_mfma_f32_16x16x32_bf16 v[40:43], v[136:139], v[186:189], v[40:43]
	v_mfma_f32_16x16x32_bf16 v[28:31], v[128:131], v[202:205], v[28:31]
	v_mfma_f32_16x16x32_bf16 v[24:27], v[136:139], v[202:205], v[24:27]
	v_mfma_f32_16x16x32_bf16 v[12:15], v[128:131], v[210:213], v[12:15]
	v_mfma_f32_16x16x32_bf16 v[8:11], v[136:139], v[210:213], v[8:11]
	v_mfma_f32_16x16x32_bf16 v[60:63], v[132:135], v[182:185], v[60:63]
	v_mfma_f32_16x16x32_bf16 v[56:59], v[140:143], v[182:185], v[56:59]
	v_mfma_f32_16x16x32_bf16 v[44:47], v[132:135], v[194:197], v[44:47]
	v_mfma_f32_16x16x32_bf16 v[40:43], v[140:143], v[194:197], v[40:43]
	v_mfma_f32_16x16x32_bf16 v[28:31], v[132:135], v[206:209], v[28:31]
	v_mfma_f32_16x16x32_bf16 v[24:27], v[140:143], v[206:209], v[24:27]
	v_mfma_f32_16x16x32_bf16 v[12:15], v[132:135], v[214:217], v[12:15]
	v_mfma_f32_16x16x32_bf16 v[8:11], v[140:143], v[214:217], v[8:11]
	s_setprio 0
	s_setprio 1
	v_mfma_f32_16x16x32_bf16 v[52:55], v[144:147], v[178:181], v[52:55]
	v_mfma_f32_16x16x32_bf16 v[48:51], v[164:167], v[178:181], v[48:51]
	v_mfma_f32_16x16x32_bf16 v[36:39], v[144:147], v[186:189], v[36:39]
	v_mfma_f32_16x16x32_bf16 v[32:35], v[164:167], v[186:189], v[32:35]
	v_mfma_f32_16x16x32_bf16 v[20:23], v[144:147], v[202:205], v[20:23]
	v_mfma_f32_16x16x32_bf16 v[16:19], v[164:167], v[202:205], v[16:19]
	v_mfma_f32_16x16x32_bf16 v[4:7], v[144:147], v[210:213], v[4:7]
	v_mfma_f32_16x16x32_bf16 v[0:3], v[164:167], v[210:213], v[0:3]
	v_mfma_f32_16x16x32_bf16 v[52:55], v[148:151], v[182:185], v[52:55]
	v_mfma_f32_16x16x32_bf16 v[48:51], v[174:177], v[182:185], v[48:51]
	v_mfma_f32_16x16x32_bf16 v[36:39], v[148:151], v[194:197], v[36:39]
	v_mfma_f32_16x16x32_bf16 v[32:35], v[174:177], v[194:197], v[32:35]
	v_mfma_f32_16x16x32_bf16 v[20:23], v[148:151], v[206:209], v[20:23]
	v_mfma_f32_16x16x32_bf16 v[16:19], v[174:177], v[206:209], v[16:19]
	v_mfma_f32_16x16x32_bf16 v[4:7], v[148:151], v[214:217], v[4:7]
	v_mfma_f32_16x16x32_bf16 v[0:3], v[174:177], v[214:217], v[0:3]
	s_setprio 0
	s_add_i32 s65, s65, 2
	s_add_u32 s36, s36, 0x100
	s_addc_u32 s37, s37, 0
	s_add_u32 s63, s63, 0x100
	s_addc_u32 s64, s64, 0
	s_cmp_gt_u32 s65, 29
	s_barrier
	s_cbranch_scc0 .LBB0_635
	s_and_b64 vcc, exec, s[10:11]
	s_cbranch_vccz .LBB0_638
	s_barrier

; #define PG8_STAGE(bufoff, gbase, voff) do { _Pragma("unroll") for (int _i = 0; _i < 2; ++_i) \
;         __builtin_amdgcn_global_load_lds((const unsigned*)((const char*)(gbase) + (voff)[_i]), (PG8_LAS unsigned*)(lds + (bufoff) + ldsw + _i * 8192), 16, 0, 0); } while (0)
; #define PG8_LDA(dst, b, h) do { _Pragma("unroll") for (int m = 0; m < 4; ++m) _Pragma("unroll") for (int k = 0; k < 2; ++k) dst[m][k] = *(const PG8_LAS bf16x8*)(lds + PG8_SA(b, h) + aoff + m * 2048 + k * 1024); } while (0)
; #define PG8_LDB(dst, b, h) do { _Pragma("unroll") for (int n = 0; n < 2; ++n) _Pragma("unroll") for (int k = 0; k < 2; ++k) dst[n][k] = *(const PG8_LAS bf16x8*)(lds + PG8_SB(b, h) + boff + n * 2048 + k * 1024); } while (0)
; #define PG8_WAIT_V(n) asm volatile("s_waitcnt vmcnt(" #n ")" ::: "memory")
; #define PG8_WAIT_L(n) asm volatile("s_waitcnt lgkmcnt(" #n ")" ::: "memory")
; #define PG8_BAR __builtin_amdgcn_s_barrier()
; #define PG8_SCHED __builtin_amdgcn_sched_barrier(0)
; template <class Epi, class Sched, bool ALIGN_EPI = false, bool SP2 = false>
; __device__ __forceinline__ void gemm_phase(PG8_LAS unsigned char* lds, const Gemm g, const Sched& S, const Epi& E) {
;     ...
;         const char* nA = has_next ? (const char*)g.A + (size_t)nxt.pm * tstep : cA; const char* nB = has_next ? (const char*)g.Bt + (size_t)nxt.pn * tstep : cB;
;         for (int t = 0; t < nt; t += 2) {
;             if constexpr (Epi::MID_HOOK) { if (t == Epi::MID_T) E.mid(acc, cur, wr, wc, fr, fq); }
;             const bool last = (t == nt - 2);
;             const char* a1 = cA + (size_t)(t + 1) * kstep;
;             const char* a2 = last ? nA : cA + (size_t)(t + 2) * kstep; const char* b2 = last ? nB : cB + (size_t)(t + 2) * kstep;
;             const char* a3 = a2 + kstep; const char* b3 = b2 + kstep;
;             if (last && has_next) S.a_ready(nxt);
;             if constexpr (SP2) {
;             PG8_LDB(B0, 0, 0); PG8_LDB(B1, 0, 1); PG8_SCHED; PG8_LDA(At, 0, 0); PG8_STAGE(PG8_SA(1, 1), a1 + hstep, voffA);
;             PG8_WAIT_V(8); PG8_WAIT_L(0); PG8_BAR; PG8_MMA(0, 0, At, B0); PG8_MMA(0, 1, At, B1); PG8_BAR; PG8_SCHED;
;             PG8_LDA(At, 0, 1); PG8_STAGE(PG8_SB(0, 0), b2, voffB); PG8_STAGE(PG8_SB(0, 1), b2 + hstep, voffB); PG8_STAGE(PG8_SA(0, 0), a2, voffA);
;             PG8_WAIT_V(8); PG8_WAIT_L(0); PG8_BAR; PG8_MMA(1, 0, At, B0); PG8_MMA(1, 1, At, B1); PG8_BAR; PG8_SCHED;
.LBB0_729:
	s_ashr_i32 s49, s48, 31
	s_lshl_b64 s[12:13], s[48:49], 20
	s_add_u32 s50, s18, s12
	s_addc_u32 s51, s19, s13
	s_and_b64 s[12:13], s[42:43], exec
	s_cselect_b32 s49, s51, s1
	s_cselect_b32 s60, s50, s0
	s_ashr_i32 s47, s46, 31
	s_lshl_b64 s[12:13], s[46:47], 20
	s_add_u32 s52, s14, s12
	s_addc_u32 s53, s15, s13
	s_and_b64 s[12:13], s[42:43], exec
	s_cselect_b32 s47, s53, s11
	s_cselect_b32 s61, s52, s10
	s_add_u32 s0, s0, 0x80080
	s_addc_u32 s1, s1, 0
	s_add_u32 s62, s10, 0x100
	s_addc_u32 s63, s11, 0
	s_mov_b32 s64, -2
	v_lshl_add_u64 v[190:191], s[0:1], 0, v[136:137]
	s_add_i32 m0, s31, 0xc000
	global_load_lds_dwordx4 v[190:191], off
	s_add_i32 m0, s31, 0xe000
	v_lshl_add_u64 v[190:191], s[0:1], 0, v[138:139]
	global_load_lds_dwordx4 v[190:191], off
	s_add_u32 s10, s0, 0xfff80080
	s_addc_u32 s11, s1, -1
	s_add_i32 s24, 0, 0x10000
	s_cmp_eq_u32 s64, 28
	s_cselect_b32 s13, s49, s11
	s_cselect_b32 s12, s60, s10
	s_cselect_b32 s11, s47, s63
	s_cselect_b32 s10, s61, s62
	s_add_i32 s25, 0, 0x14000
	s_waitcnt vmcnt(8)
	s_waitcnt lgkmcnt(0)
	s_barrier
	s_setprio 1
	s_waitcnt lgkmcnt(0)
	v_mfma_f32_16x16x32_bf16 v[124:127], v[140:143], v[178:181], 0
	v_mfma_f32_16x16x32_bf16 v[112:115], v[154:157], v[178:181], 0
	v_mfma_f32_16x16x32_bf16 v[108:111], v[140:143], v[186:189], 0
	v_mfma_f32_16x16x32_bf16 v[100:103], v[154:157], v[186:189], 0
	v_mfma_f32_16x16x32_bf16 v[92:95], v[140:143], v[202:205], 0
	v_mfma_f32_16x16x32_bf16 v[84:87], v[154:157], v[202:205], 0
	v_mfma_f32_16x16x32_bf16 v[76:79], v[140:143], v[210:213], 0
	v_mfma_f32_16x16x32_bf16 v[68:71], v[154:157], v[210:213], 0
	v_mfma_f32_16x16x32_bf16 v[124:127], v[144:147], v[182:185], v[124:127]
	v_mfma_f32_16x16x32_bf16 v[112:115], v[158:161], v[182:185], v[112:115]
	v_mfma_f32_16x16x32_bf16 v[108:111], v[144:147], v[194:197], v[108:111]
	v_mfma_f32_16x16x32_bf16 v[100:103], v[158:161], v[194:197], v[100:103]
	v_mfma_f32_16x16x32_bf16 v[92:95], v[144:147], v[206:209], v[92:95]
	v_mfma_f32_16x16x32_bf16 v[84:87], v[158:161], v[206:209], v[84:87]
	v_mfma_f32_16x16x32_bf16 v[76:79], v[144:147], v[214:217], v[76:79]
	v_mfma_f32_16x16x32_bf16 v[68:71], v[158:161], v[214:217], v[68:71]
	s_setprio 0
	s_setprio 1
	v_mfma_f32_16x16x32_bf16 v[120:123], v[162:165], v[178:181], 0
	v_mfma_f32_16x16x32_bf16 v[116:119], v[170:173], v[178:181], 0
	v_mfma_f32_16x16x32_bf16 v[104:107], v[162:165], v[186:189], 0
	v_mfma_f32_16x16x32_bf16 v[96:99], v[170:173], v[186:189], 0
	v_mfma_f32_16x16x32_bf16 v[88:91], v[162:165], v[202:205], 0
	v_mfma_f32_16x16x32_bf16 v[80:83], v[170:173], v[202:205], 0
	v_mfma_f32_16x16x32_bf16 v[72:75], v[162:165], v[210:213], 0
	v_mfma_f32_16x16x32_bf16 v[64:67], v[170:173], v[210:213], 0
	v_mfma_f32_16x16x32_bf16 v[120:123], v[166:169], v[182:185], v[120:123]
	v_mfma_f32_16x16x32_bf16 v[116:119], v[174:177], v[182:185], v[116:119]
	v_mfma_f32_16x16x32_bf16 v[104:107], v[166:169], v[194:197], v[104:107]
	v_mfma_f32_16x16x32_bf16 v[96:99], v[174:177], v[194:197], v[96:99]
	v_mfma_f32_16x16x32_bf16 v[88:91], v[166:169], v[206:209], v[88:91]
	v_mfma_f32_16x16x32_bf16 v[80:83], v[174:177], v[206:209], v[80:83]
	v_mfma_f32_16x16x32_bf16 v[72:75], v[166:169], v[214:217], v[72:75]
	v_mfma_f32_16x16x32_bf16 v[64:67], v[174:177], v[214:217], v[64:67]
	s_setprio 0
	s_barrier
	s_add_i32 s24, s24, s30
	v_lshl_add_u64 v[190:191], s[10:11], 0, v[132:133]
	s_mov_b32 m0, s24
	ds_read_b128 v[178:181], v152 offset:16384
	ds_read_b128 v[182:185], v152 offset:17408
	ds_read_b128 v[186:189], v152 offset:18432
	ds_read_b128 v[194:197], v152 offset:19456
	ds_read_b128 v[202:205], v152 offset:20480
	ds_read_b128 v[206:209], v152 offset:21504
	ds_read_b128 v[210:213], v152 offset:22528
	ds_read_b128 v[214:217], v152 offset:23552
	global_load_lds_dwordx4 v[190:191], off
	s_add_i32 m0, s24, 0x2000
	s_add_u32 s66, s10, 0x80000
	v_lshl_add_u64 v[218:219], s[10:11], 0, v[128:129]
	s_addc_u32 s67, s11, 0
	s_add_i32 s24, s25, s30
	global_load_lds_dwordx4 v[218:219], off
	v_lshl_add_u64 v[220:221], s[66:67], 0, v[132:133]
	s_mov_b32 m0, s24
	v_lshl_add_u64 v[230:231], s[12:13], 0, v[130:131]
	global_load_lds_dwordx4 v[220:221], off
	s_add_i32 m0, s24, 0x2000
	v_lshl_add_u64 v[220:221], s[66:67], 0, v[128:129]
	global_load_lds_dwordx4 v[220:221], off
	s_mov_b32 m0, s31
	v_lshl_add_u64 v[220:221], s[12:13], 0, v[134:135]
	global_load_lds_dwordx4 v[220:221], off
	s_mov_b32 m0, s34
	s_nop 0
	global_load_lds_dwordx4 v[230:231], off
	s_waitcnt vmcnt(8)
	s_waitcnt lgkmcnt(0)
	s_barrier
	s_setprio 1
	s_waitcnt lgkmcnt(0)
	v_mfma_f32_16x16x32_bf16 v[60:63], v[140:143], v[178:181], 0
	v_mfma_f32_16x16x32_bf16 v[52:55], v[154:157], v[178:181], 0
	v_mfma_f32_16x16x32_bf16 v[44:47], v[140:143], v[186:189], 0
	v_mfma_f32_16x16x32_bf16 v[36:39], v[154:157], v[186:189], 0
	v_mfma_f32_16x16x32_bf16 v[28:31], v[140:143], v[202:205], 0
	v_mfma_f32_16x16x32_bf16 v[20:23], v[154:157], v[202:205], 0
	v_mfma_f32_16x16x32_bf16 v[12:15], v[140:143], v[210:213], 0
	v_mfma_f32_16x16x32_bf16 v[4:7], v[154:157], v[210:213], 0
	v_mfma_f32_16x16x32_bf16 v[60:63], v[144:147], v[182:185], v[60:63]
	v_mfma_f32_16x16x32_bf16 v[52:55], v[158:161], v[182:185], v[52:55]
	v_mfma_f32_16x16x32_bf16 v[44:47], v[144:147], v[194:197], v[44:47]
	v_mfma_f32_16x16x32_bf16 v[36:39], v[158:161], v[194:197], v[36:39]
	v_mfma_f32_16x16x32_bf16 v[28:31], v[144:147], v[206:209], v[28:31]
	v_mfma_f32_16x16x32_bf16 v[20:23], v[158:161], v[206:209], v[20:23]
	v_mfma_f32_16x16x32_bf16 v[12:15], v[144:147], v[214:217], v[12:15]
	v_mfma_f32_16x16x32_bf16 v[4:7], v[158:161], v[214:217], v[4:7]
	s_setprio 0
	s_setprio 1
	v_mfma_f32_16x16x32_bf16 v[56:59], v[162:165], v[178:181], 0
	v_mfma_f32_16x16x32_bf16 v[48:51], v[170:173], v[178:181], 0
	v_mfma_f32_16x16x32_bf16 v[40:43], v[162:165], v[186:189], 0
	v_mfma_f32_16x16x32_bf16 v[32:35], v[170:173], v[186:189], 0
	v_mfma_f32_16x16x32_bf16 v[24:27], v[162:165], v[202:205], 0
	v_mfma_f32_16x16x32_bf16 v[16:19], v[170:173], v[202:205], 0
	v_mfma_f32_16x16x32_bf16 v[8:11], v[162:165], v[210:213], 0
	v_mfma_f32_16x16x32_bf16 v[0:3], v[170:173], v[210:213], 0
	v_mfma_f32_16x16x32_bf16 v[56:59], v[166:169], v[182:185], v[56:59]
	v_mfma_f32_16x16x32_bf16 v[48:51], v[174:177], v[182:185], v[48:51]
	v_mfma_f32_16x16x32_bf16 v[40:43], v[166:169], v[194:197], v[40:43]
	v_mfma_f32_16x16x32_bf16 v[32:35], v[174:177], v[194:197], v[32:35]
	v_mfma_f32_16x16x32_bf16 v[24:27], v[166:169], v[206:209], v[24:27]
	v_mfma_f32_16x16x32_bf16 v[16:19], v[174:177], v[206:209], v[16:19]
	v_mfma_f32_16x16x32_bf16 v[8:11], v[166:169], v[214:217], v[8:11]
	v_mfma_f32_16x16x32_bf16 v[0:3], v[174:177], v[214:217], v[0:3]
	s_setprio 0
	s_barrier
; #define PG8_STAGE(bufoff, gbase, voff) do { _Pragma("unroll") for (int _i = 0; _i < 2; ++_i) \
;         __builtin_amdgcn_global_load_lds((const unsigned*)((const char*)(gbase) + (voff)[_i]), (PG8_LAS unsigned*)(lds + (bufoff) + ldsw + _i * 8192), 16, 0, 0); } while (0)
; #define PG8_LDA(dst, b, h) do { _Pragma("unroll") for (int m = 0; m < 4; ++m) _Pragma("unroll") for (int k = 0; k < 2; ++k) dst[m][k] = *(const PG8_LAS bf16x8*)(lds + PG8_SA(b, h) + aoff + m * 2048 + k * 1024); } while (0)
; #define PG8_LDB(dst, b, h) do { _Pragma("unroll") for (int n = 0; n < 2; ++n) _Pragma("unroll") for (int k = 0; k < 2; ++k) dst[n][k] = *(const PG8_LAS bf16x8*)(lds + PG8_SB(b, h) + boff + n * 2048 + k * 1024); } while (0)
; #define PG8_MMA(ai, bj, At, Bt) do { __builtin_amdgcn_s_setprio(1); _Pragma("unroll") for (int m = 0; m < 4; ++m) _Pragma("unroll") for (int n = 0; n < 2; ++n) _Pragma("unroll") for (int k = 0; k < 2; ++k) \
;         acc[ai][bj][m][n] = __builtin_amdgcn_mfma_f32_16x16x32_bf16(Bt[n][k], At[m][k], acc[ai][bj][m][n], 0, 0, 0); __builtin_amdgcn_s_setprio(0); } while (0)
; #define PG8_WAIT_V(n) asm volatile("s_waitcnt vmcnt(" #n ")" ::: "memory")
; #define PG8_WAIT_L(n) asm volatile("s_waitcnt lgkmcnt(" #n ")" ::: "memory")
; #define PG8_BAR __builtin_amdgcn_s_barrier()
; #define PG8_SCHED __builtin_amdgcn_sched_barrier(0)
; template <class Epi, class Sched, bool ALIGN_EPI = false, bool SP2 = false>
; __device__ __forceinline__ void gemm_phase(PG8_LAS unsigned char* lds, const Gemm g, const Sched& S, const Epi& E) {
;     ...
;             PG8_LDB(B0, 1, 0); PG8_LDB(B1, 1, 1); PG8_SCHED; PG8_LDA(At, 1, 0); PG8_STAGE(PG8_SA(0, 1), a2 + hstep, voffA);
;             PG8_WAIT_V(8); PG8_WAIT_L(0); PG8_BAR; PG8_MMA(0, 0, At, B0); PG8_MMA(0, 1, At, B1); PG8_BAR; PG8_SCHED;
;             PG8_LDA(At, 1, 1); PG8_STAGE(PG8_SB(1, 0), b3, voffB); PG8_STAGE(PG8_SB(1, 1), b3 + hstep, voffB); PG8_STAGE(PG8_SA(1, 0), a3, voffA);
;             PG8_WAIT_V(8); PG8_WAIT_L(0); PG8_BAR; PG8_MMA(1, 0, At, B0); PG8_MMA(1, 1, At, B1); PG8_BAR; PG8_SCHED;
	s_add_i32 s24, 0, 0x18000
	v_add_u32_e32 v148, 0x18000, v151
	s_add_i32 s25, 0, 0x1c000
	ds_read_b128 v[140:143], v148
	ds_read_b128 v[144:147], v148 offset:1024
	ds_read_b128 v[154:157], v148 offset:2048
	ds_read_b128 v[158:161], v148 offset:3072
	v_add_u32_e32 v148, 0x1c000, v151
	ds_read_b128 v[162:165], v148
	ds_read_b128 v[166:169], v148 offset:1024
	ds_read_b128 v[170:173], v148 offset:2048
	ds_read_b128 v[174:177], v148 offset:3072
	s_add_u32 s12, s12, 0x80000
	s_addc_u32 s13, s13, 0
	s_mov_b32 m0, s36
	v_lshl_add_u64 v[232:233], s[12:13], 0, v[134:135]
	ds_read_b128 v[178:181], v152 offset:32768
	ds_read_b128 v[182:185], v152 offset:33792
	ds_read_b128 v[186:189], v152 offset:34816
	ds_read_b128 v[194:197], v152 offset:35840
	ds_read_b128 v[202:205], v152 offset:36864
	ds_read_b128 v[206:209], v152 offset:37888
	ds_read_b128 v[210:213], v152 offset:38912
	ds_read_b128 v[214:217], v152 offset:39936
	global_load_lds_dwordx4 v[232:233], off
	s_mov_b32 m0, s37
	v_lshl_add_u64 v[232:233], s[12:13], 0, v[130:131]
	global_load_lds_dwordx4 v[232:233], off
	s_waitcnt vmcnt(8)
	s_waitcnt lgkmcnt(0)
	s_barrier
	s_setprio 1
	s_waitcnt lgkmcnt(0)
	v_mfma_f32_16x16x32_bf16 v[124:127], v[140:143], v[178:181], v[124:127]
	v_mfma_f32_16x16x32_bf16 v[112:115], v[154:157], v[178:181], v[112:115]
	v_mfma_f32_16x16x32_bf16 v[108:111], v[140:143], v[186:189], v[108:111]
	v_mfma_f32_16x16x32_bf16 v[100:103], v[154:157], v[186:189], v[100:103]
	v_mfma_f32_16x16x32_bf16 v[92:95], v[140:143], v[202:205], v[92:95]
	v_mfma_f32_16x16x32_bf16 v[84:87], v[154:157], v[202:205], v[84:87]
	v_mfma_f32_16x16x32_bf16 v[76:79], v[140:143], v[210:213], v[76:79]
	v_mfma_f32_16x16x32_bf16 v[68:71], v[154:157], v[210:213], v[68:71]
	v_mfma_f32_16x16x32_bf16 v[124:127], v[144:147], v[182:185], v[124:127]
	v_mfma_f32_16x16x32_bf16 v[112:115], v[158:161], v[182:185], v[112:115]
	v_mfma_f32_16x16x32_bf16 v[108:111], v[144:147], v[194:197], v[108:111]
	v_mfma_f32_16x16x32_bf16 v[100:103], v[158:161], v[194:197], v[100:103]
	v_mfma_f32_16x16x32_bf16 v[92:95], v[144:147], v[206:209], v[92:95]
	v_mfma_f32_16x16x32_bf16 v[84:87], v[158:161], v[206:209], v[84:87]
	v_mfma_f32_16x16x32_bf16 v[76:79], v[144:147], v[214:217], v[76:79]
	v_mfma_f32_16x16x32_bf16 v[68:71], v[158:161], v[214:217], v[68:71]
	s_setprio 0
	s_setprio 1
	v_mfma_f32_16x16x32_bf16 v[120:123], v[162:165], v[178:181], v[120:123]
	v_mfma_f32_16x16x32_bf16 v[116:119], v[170:173], v[178:181], v[116:119]
	v_mfma_f32_16x16x32_bf16 v[104:107], v[162:165], v[186:189], v[104:107]
	v_mfma_f32_16x16x32_bf16 v[96:99], v[170:173], v[186:189], v[96:99]
	v_mfma_f32_16x16x32_bf16 v[88:91], v[162:165], v[202:205], v[88:91]
	v_mfma_f32_16x16x32_bf16 v[80:83], v[170:173], v[202:205], v[80:83]
	v_mfma_f32_16x16x32_bf16 v[72:75], v[162:165], v[210:213], v[72:75]
	v_mfma_f32_16x16x32_bf16 v[64:67], v[170:173], v[210:213], v[64:67]
	v_mfma_f32_16x16x32_bf16 v[120:123], v[166:169], v[182:185], v[120:123]
	v_mfma_f32_16x16x32_bf16 v[116:119], v[174:177], v[182:185], v[116:119]
	v_mfma_f32_16x16x32_bf16 v[104:107], v[166:169], v[194:197], v[104:107]
	v_mfma_f32_16x16x32_bf16 v[96:99], v[174:177], v[194:197], v[96:99]
	v_mfma_f32_16x16x32_bf16 v[88:91], v[166:169], v[206:209], v[88:91]
	v_mfma_f32_16x16x32_bf16 v[80:83], v[174:177], v[206:209], v[80:83]
	v_mfma_f32_16x16x32_bf16 v[72:75], v[166:169], v[214:217], v[72:75]
	v_mfma_f32_16x16x32_bf16 v[64:67], v[174:177], v[214:217], v[64:67]
	s_setprio 0
	s_barrier
	s_add_i32 s12, s24, s30
	v_lshl_add_u64 v[190:191], v[190:191], 0, s[16:17]
	s_mov_b32 m0, s12
	ds_read_b128 v[178:181], v152 offset:49152
	ds_read_b128 v[182:185], v152 offset:50176
	ds_read_b128 v[186:189], v152 offset:51200
	ds_read_b128 v[194:197], v152 offset:52224
	ds_read_b128 v[202:205], v152 offset:53248
	ds_read_b128 v[206:209], v152 offset:54272
	ds_read_b128 v[210:213], v152 offset:55296
	ds_read_b128 v[214:217], v152 offset:56320
	global_load_lds_dwordx4 v[190:191], off
	s_add_i32 m0, s12, 0x2000
	s_add_u32 s10, s10, 0x80080
	v_lshl_add_u64 v[190:191], v[218:219], 0, s[16:17]
	s_addc_u32 s11, s11, 0
	s_add_i32 s12, s25, s30
	global_load_lds_dwordx4 v[190:191], off
	s_mov_b32 m0, s12
	v_lshl_add_u64 v[190:191], s[10:11], 0, v[132:133]
	global_load_lds_dwordx4 v[190:191], off
	s_add_i32 m0, s12, 0x2000
	v_lshl_add_u64 v[190:191], s[10:11], 0, v[128:129]
	global_load_lds_dwordx4 v[190:191], off
	s_mov_b32 m0, s56
	v_lshl_add_u64 v[190:191], v[220:221], 0, s[16:17]
	global_load_lds_dwordx4 v[190:191], off
	s_mov_b32 m0, s57
	v_lshl_add_u64 v[190:191], v[230:231], 0, s[16:17]
	global_load_lds_dwordx4 v[190:191], off
	s_waitcnt vmcnt(8)
	s_waitcnt lgkmcnt(0)
	s_barrier
; #define PG8_STAGE(bufoff, gbase, voff) do { _Pragma("unroll") for (int _i = 0; _i < 2; ++_i) \
;         __builtin_amdgcn_global_load_lds((const unsigned*)((const char*)(gbase) + (voff)[_i]), (PG8_LAS unsigned*)(lds + (bufoff) + ldsw + _i * 8192), 16, 0, 0); } while (0)
; #define PG8_LDA(dst, b, h) do { _Pragma("unroll") for (int m = 0; m < 4; ++m) _Pragma("unroll") for (int k = 0; k < 2; ++k) dst[m][k] = *(const PG8_LAS bf16x8*)(lds + PG8_SA(b, h) + aoff + m * 2048 + k * 1024); } while (0)
; #define PG8_LDB(dst, b, h) do { _Pragma("unroll") for (int n = 0; n < 2; ++n) _Pragma("unroll") for (int k = 0; k < 2; ++k) dst[n][k] = *(const PG8_LAS bf16x8*)(lds + PG8_SB(b, h) + boff + n * 2048 + k * 1024); } while (0)
; #define PG8_MMA(ai, bj, At, Bt) do { __builtin_amdgcn_s_setprio(1); _Pragma("unroll") for (int m = 0; m < 4; ++m) _Pragma("unroll") for (int n = 0; n < 2; ++n) _Pragma("unroll") for (int k = 0; k < 2; ++k) \
;         acc[ai][bj][m][n] = __builtin_amdgcn_mfma_f32_16x16x32_bf16(Bt[n][k], At[m][k], acc[ai][bj][m][n], 0, 0, 0); __builtin_amdgcn_s_setprio(0); } while (0)
; #define PG8_WAIT_V(n) asm volatile("s_waitcnt vmcnt(" #n ")" ::: "memory")
; template <class Epi, class Sched, bool ALIGN_EPI = false, bool SP2 = false>
; __device__ __forceinline__ void gemm_phase(PG8_LAS unsigned char* lds, const Gemm g, const Sched& S, const Epi& E) {
;     ...
;             PG8_LDB(B0, 0, 0); PG8_LDB(B1, 0, 1); PG8_SCHED; PG8_LDA(At, 0, 0); PG8_STAGE(PG8_SA(1, 1), a1 + hstep, voffA);
;             PG8_WAIT_V(8); PG8_WAIT_L(0); PG8_BAR; PG8_MMA(0, 0, At, B0); PG8_MMA(0, 1, At, B1); PG8_BAR; PG8_SCHED;
;             PG8_LDA(At, 0, 1); PG8_STAGE(PG8_SB(0, 0), b2, voffB); PG8_STAGE(PG8_SB(0, 1), b2 + hstep, voffB); PG8_STAGE(PG8_SA(0, 0), a2, voffA);
;             PG8_WAIT_V(8); PG8_WAIT_L(0); PG8_BAR; PG8_MMA(1, 0, At, B0); PG8_MMA(1, 1, At, B1); PG8_BAR; PG8_SCHED;
;             PG8_LDB(B0, 1, 0); PG8_LDB(B1, 1, 1); PG8_SCHED; PG8_LDA(At, 1, 0); PG8_STAGE(PG8_SA(0, 1), a2 + hstep, voffA);
;             PG8_WAIT_V(8); PG8_WAIT_L(0); PG8_BAR; PG8_MMA(0, 0, At, B0); PG8_MMA(0, 1, At, B1); PG8_BAR; PG8_SCHED;
;             PG8_LDA(At, 1, 1); PG8_STAGE(PG8_SB(1, 0), b3, voffB); PG8_STAGE(PG8_SB(1, 1), b3 + hstep, voffB); PG8_STAGE(PG8_SA(1, 0), a3, voffA);
;             PG8_WAIT_V(8); PG8_WAIT_L(0); PG8_BAR; PG8_MMA(1, 0, At, B0); PG8_MMA(1, 1, At, B1); PG8_BAR; PG8_SCHED;
	s_setprio 1
	s_waitcnt lgkmcnt(0)
	v_mfma_f32_16x16x32_bf16 v[60:63], v[140:143], v[178:181], v[60:63]
	v_mfma_f32_16x16x32_bf16 v[52:55], v[154:157], v[178:181], v[52:55]
	v_mfma_f32_16x16x32_bf16 v[44:47], v[140:143], v[186:189], v[44:47]
	v_mfma_f32_16x16x32_bf16 v[36:39], v[154:157], v[186:189], v[36:39]
	v_mfma_f32_16x16x32_bf16 v[28:31], v[140:143], v[202:205], v[28:31]
	v_mfma_f32_16x16x32_bf16 v[20:23], v[154:157], v[202:205], v[20:23]
	v_mfma_f32_16x16x32_bf16 v[12:15], v[140:143], v[210:213], v[12:15]
	v_mfma_f32_16x16x32_bf16 v[4:7], v[154:157], v[210:213], v[4:7]
	v_mfma_f32_16x16x32_bf16 v[60:63], v[144:147], v[182:185], v[60:63]
	v_mfma_f32_16x16x32_bf16 v[52:55], v[158:161], v[182:185], v[52:55]
	v_mfma_f32_16x16x32_bf16 v[44:47], v[144:147], v[194:197], v[44:47]
	v_mfma_f32_16x16x32_bf16 v[36:39], v[158:161], v[194:197], v[36:39]
	v_mfma_f32_16x16x32_bf16 v[28:31], v[144:147], v[206:209], v[28:31]
	v_mfma_f32_16x16x32_bf16 v[20:23], v[158:161], v[206:209], v[20:23]
	v_mfma_f32_16x16x32_bf16 v[12:15], v[144:147], v[214:217], v[12:15]
	v_mfma_f32_16x16x32_bf16 v[4:7], v[158:161], v[214:217], v[4:7]
	s_setprio 0
	s_setprio 1
	v_mfma_f32_16x16x32_bf16 v[56:59], v[162:165], v[178:181], v[56:59]
	v_mfma_f32_16x16x32_bf16 v[48:51], v[170:173], v[178:181], v[48:51]
	v_mfma_f32_16x16x32_bf16 v[40:43], v[162:165], v[186:189], v[40:43]
	v_mfma_f32_16x16x32_bf16 v[32:35], v[170:173], v[186:189], v[32:35]
	v_mfma_f32_16x16x32_bf16 v[24:27], v[162:165], v[202:205], v[24:27]
	v_mfma_f32_16x16x32_bf16 v[16:19], v[170:173], v[202:205], v[16:19]
	v_mfma_f32_16x16x32_bf16 v[8:11], v[162:165], v[210:213], v[8:11]
	v_mfma_f32_16x16x32_bf16 v[0:3], v[170:173], v[210:213], v[0:3]
	v_mfma_f32_16x16x32_bf16 v[56:59], v[166:169], v[182:185], v[56:59]
	v_mfma_f32_16x16x32_bf16 v[48:51], v[174:177], v[182:185], v[48:51]
	v_mfma_f32_16x16x32_bf16 v[40:43], v[166:169], v[194:197], v[40:43]
	v_mfma_f32_16x16x32_bf16 v[32:35], v[174:177], v[194:197], v[32:35]
	v_mfma_f32_16x16x32_bf16 v[24:27], v[166:169], v[206:209], v[24:27]
	v_mfma_f32_16x16x32_bf16 v[16:19], v[174:177], v[206:209], v[16:19]
	v_mfma_f32_16x16x32_bf16 v[8:11], v[166:169], v[214:217], v[8:11]
	v_mfma_f32_16x16x32_bf16 v[0:3], v[174:177], v[214:217], v[0:3]
	s_setprio 0
	s_add_i32 s64, s64, 2
	s_add_u32 s0, s0, 0x100
	s_addc_u32 s1, s1, 0
	s_add_u32 s62, s62, 0x100
	s_addc_u32 s63, s63, 0
	s_cmp_gt_u32 s64, 29
	s_barrier
.LBB0_730:
	v_add_u32_e32 v148, 0x10000, v151
	ds_read_b128 v[140:143], v148
	ds_read_b128 v[144:147], v148 offset:1024
	ds_read_b128 v[154:157], v148 offset:2048
	ds_read_b128 v[158:161], v148 offset:3072
	v_add_u32_e32 v148, 0x14000, v151
	ds_read_b128 v[162:165], v148
	ds_read_b128 v[166:169], v148 offset:1024
	ds_read_b128 v[170:173], v148 offset:2048
	ds_read_b128 v[174:177], v148 offset:3072
	v_lshl_add_u64 v[190:191], s[0:1], 0, v[136:137]
	s_add_i32 m0, s31, 0xc000
	ds_read_b128 v[178:181], v152
	ds_read_b128 v[182:185], v152 offset:1024
	ds_read_b128 v[186:189], v152 offset:2048
	ds_read_b128 v[194:197], v152 offset:3072
	ds_read_b128 v[202:205], v152 offset:4096
	ds_read_b128 v[206:209], v152 offset:5120
	ds_read_b128 v[210:213], v152 offset:6144
	ds_read_b128 v[214:217], v152 offset:7168
	global_load_lds_dwordx4 v[190:191], off
	s_add_i32 m0, s31, 0xe000
	v_lshl_add_u64 v[190:191], s[0:1], 0, v[138:139]
	global_load_lds_dwordx4 v[190:191], off
	s_add_u32 s10, s0, 0xfff80080
	s_addc_u32 s11, s1, -1
	s_add_i32 s24, 0, 0x10000
	s_cmp_eq_u32 s64, 28
	s_cselect_b32 s13, s49, s11
	s_cselect_b32 s12, s60, s10
	s_cselect_b32 s11, s47, s63
	s_cselect_b32 s10, s61, s62
	s_add_i32 s25, 0, 0x14000
	s_waitcnt vmcnt(8)
	s_waitcnt lgkmcnt(0)
	s_barrier
	s_setprio 1
	s_waitcnt lgkmcnt(0)
	v_mfma_f32_16x16x32_bf16 v[124:127], v[140:143], v[178:181], v[124:127]
	v_mfma_f32_16x16x32_bf16 v[112:115], v[154:157], v[178:181], v[112:115]
	v_mfma_f32_16x16x32_bf16 v[108:111], v[140:143], v[186:189], v[108:111]
	v_mfma_f32_16x16x32_bf16 v[100:103], v[154:157], v[186:189], v[100:103]
	v_mfma_f32_16x16x32_bf16 v[92:95], v[140:143], v[202:205], v[92:95]
	v_mfma_f32_16x16x32_bf16 v[84:87], v[154:157], v[202:205], v[84:87]
	v_mfma_f32_16x16x32_bf16 v[76:79], v[140:143], v[210:213], v[76:79]
	v_mfma_f32_16x16x32_bf16 v[68:71], v[154:157], v[210:213], v[68:71]
	v_mfma_f32_16x16x32_bf16 v[124:127], v[144:147], v[182:185], v[124:127]
	v_mfma_f32_16x16x32_bf16 v[112:115], v[158:161], v[182:185], v[112:115]
	v_mfma_f32_16x16x32_bf16 v[108:111], v[144:147], v[194:197], v[108:111]
	v_mfma_f32_16x16x32_bf16 v[100:103], v[158:161], v[194:197], v[100:103]
	v_mfma_f32_16x16x32_bf16 v[92:95], v[144:147], v[206:209], v[92:95]
	v_mfma_f32_16x16x32_bf16 v[84:87], v[158:161], v[206:209], v[84:87]
	v_mfma_f32_16x16x32_bf16 v[76:79], v[144:147], v[214:217], v[76:79]
	v_mfma_f32_16x16x32_bf16 v[68:71], v[158:161], v[214:217], v[68:71]
	s_setprio 0
	s_setprio 1
	v_mfma_f32_16x16x32_bf16 v[120:123], v[162:165], v[178:181], v[120:123]
	v_mfma_f32_16x16x32_bf16 v[116:119], v[170:173], v[178:181], v[116:119]
	v_mfma_f32_16x16x32_bf16 v[104:107], v[162:165], v[186:189], v[104:107]
	v_mfma_f32_16x16x32_bf16 v[96:99], v[170:173], v[186:189], v[96:99]
	v_mfma_f32_16x16x32_bf16 v[88:91], v[162:165], v[202:205], v[88:91]
	v_mfma_f32_16x16x32_bf16 v[80:83], v[170:173], v[202:205], v[80:83]
	v_mfma_f32_16x16x32_bf16 v[72:75], v[162:165], v[210:213], v[72:75]
	v_mfma_f32_16x16x32_bf16 v[64:67], v[170:173], v[210:213], v[64:67]
	v_mfma_f32_16x16x32_bf16 v[120:123], v[166:169], v[182:185], v[120:123]
	v_mfma_f32_16x16x32_bf16 v[116:119], v[174:177], v[182:185], v[116:119]
	v_mfma_f32_16x16x32_bf16 v[104:107], v[166:169], v[194:197], v[104:107]
	v_mfma_f32_16x16x32_bf16 v[96:99], v[174:177], v[194:197], v[96:99]
	v_mfma_f32_16x16x32_bf16 v[88:91], v[166:169], v[206:209], v[88:91]
	v_mfma_f32_16x16x32_bf16 v[80:83], v[174:177], v[206:209], v[80:83]
	v_mfma_f32_16x16x32_bf16 v[72:75], v[166:169], v[214:217], v[72:75]
	v_mfma_f32_16x16x32_bf16 v[64:67], v[174:177], v[214:217], v[64:67]
	s_setprio 0
	s_barrier
; #define PG8_STAGE(bufoff, gbase, voff) do { _Pragma("unroll") for (int _i = 0; _i < 2; ++_i) \
;         __builtin_amdgcn_global_load_lds((const unsigned*)((const char*)(gbase) + (voff)[_i]), (PG8_LAS unsigned*)(lds + (bufoff) + ldsw + _i * 8192), 16, 0, 0); } while (0)
; #define PG8_LDA(dst, b, h) do { _Pragma("unroll") for (int m = 0; m < 4; ++m) _Pragma("unroll") for (int k = 0; k < 2; ++k) dst[m][k] = *(const PG8_LAS bf16x8*)(lds + PG8_SA(b, h) + aoff + m * 2048 + k * 1024); } while (0)
; #define PG8_LDB(dst, b, h) do { _Pragma("unroll") for (int n = 0; n < 2; ++n) _Pragma("unroll") for (int k = 0; k < 2; ++k) dst[n][k] = *(const PG8_LAS bf16x8*)(lds + PG8_SB(b, h) + boff + n * 2048 + k * 1024); } while (0)
; #define PG8_MMA(ai, bj, At, Bt) do { __builtin_amdgcn_s_setprio(1); _Pragma("unroll") for (int m = 0; m < 4; ++m) _Pragma("unroll") for (int n = 0; n < 2; ++n) _Pragma("unroll") for (int k = 0; k < 2; ++k) \
;         acc[ai][bj][m][n] = __builtin_amdgcn_mfma_f32_16x16x32_bf16(Bt[n][k], At[m][k], acc[ai][bj][m][n], 0, 0, 0); __builtin_amdgcn_s_setprio(0); } while (0)
; #define PG8_WAIT_V(n) asm volatile("s_waitcnt vmcnt(" #n ")" ::: "memory")
; #define PG8_WAIT_L(n) asm volatile("s_waitcnt lgkmcnt(" #n ")" ::: "memory")
; #define PG8_BAR __builtin_amdgcn_s_barrier()
; #define PG8_SCHED __builtin_amdgcn_sched_barrier(0)
; template <class Epi, class Sched, bool ALIGN_EPI = false, bool SP2 = false>
; __device__ __forceinline__ void gemm_phase(PG8_LAS unsigned char* lds, const Gemm g, const Sched& S, const Epi& E) {
;     ...
;             PG8_LDA(At, 0, 1); PG8_STAGE(PG8_SB(0, 0), b2, voffB); PG8_STAGE(PG8_SB(0, 1), b2 + hstep, voffB); PG8_STAGE(PG8_SA(0, 0), a2, voffA);
;             PG8_WAIT_V(8); PG8_WAIT_L(0); PG8_BAR; PG8_MMA(1, 0, At, B0); PG8_MMA(1, 1, At, B1); PG8_BAR; PG8_SCHED;
;             PG8_LDB(B0, 1, 0); PG8_LDB(B1, 1, 1); PG8_SCHED; PG8_LDA(At, 1, 0); PG8_STAGE(PG8_SA(0, 1), a2 + hstep, voffA);
;             PG8_WAIT_V(8); PG8_WAIT_L(0); PG8_BAR; PG8_MMA(0, 0, At, B0); PG8_MMA(0, 1, At, B1); PG8_BAR; PG8_SCHED;
	s_add_i32 s24, s24, s30
	v_lshl_add_u64 v[190:191], s[10:11], 0, v[132:133]
	s_mov_b32 m0, s24
	ds_read_b128 v[178:181], v152 offset:16384
	ds_read_b128 v[182:185], v152 offset:17408
	ds_read_b128 v[186:189], v152 offset:18432
	ds_read_b128 v[194:197], v152 offset:19456
	ds_read_b128 v[202:205], v152 offset:20480
	ds_read_b128 v[206:209], v152 offset:21504
	ds_read_b128 v[210:213], v152 offset:22528
	ds_read_b128 v[214:217], v152 offset:23552
	global_load_lds_dwordx4 v[190:191], off
	s_add_i32 m0, s24, 0x2000
	s_add_u32 s66, s10, 0x80000
	v_lshl_add_u64 v[218:219], s[10:11], 0, v[128:129]
	s_addc_u32 s67, s11, 0
	s_add_i32 s24, s25, s30
	global_load_lds_dwordx4 v[218:219], off
	v_lshl_add_u64 v[220:221], s[66:67], 0, v[132:133]
	s_mov_b32 m0, s24
	v_lshl_add_u64 v[230:231], s[12:13], 0, v[130:131]
	global_load_lds_dwordx4 v[220:221], off
	s_add_i32 m0, s24, 0x2000
	v_lshl_add_u64 v[220:221], s[66:67], 0, v[128:129]
	global_load_lds_dwordx4 v[220:221], off
	s_mov_b32 m0, s31
	v_lshl_add_u64 v[220:221], s[12:13], 0, v[134:135]
	global_load_lds_dwordx4 v[220:221], off
	s_mov_b32 m0, s34
	s_nop 0
	global_load_lds_dwordx4 v[230:231], off
	s_waitcnt vmcnt(8)
	s_waitcnt lgkmcnt(0)
	s_barrier
	s_setprio 1
	s_waitcnt lgkmcnt(0)
	v_mfma_f32_16x16x32_bf16 v[60:63], v[140:143], v[178:181], v[60:63]
	v_mfma_f32_16x16x32_bf16 v[52:55], v[154:157], v[178:181], v[52:55]
	v_mfma_f32_16x16x32_bf16 v[44:47], v[140:143], v[186:189], v[44:47]
	v_mfma_f32_16x16x32_bf16 v[36:39], v[154:157], v[186:189], v[36:39]
	v_mfma_f32_16x16x32_bf16 v[28:31], v[140:143], v[202:205], v[28:31]
	v_mfma_f32_16x16x32_bf16 v[20:23], v[154:157], v[202:205], v[20:23]
	v_mfma_f32_16x16x32_bf16 v[12:15], v[140:143], v[210:213], v[12:15]
	v_mfma_f32_16x16x32_bf16 v[4:7], v[154:157], v[210:213], v[4:7]
	v_mfma_f32_16x16x32_bf16 v[60:63], v[144:147], v[182:185], v[60:63]
	v_mfma_f32_16x16x32_bf16 v[52:55], v[158:161], v[182:185], v[52:55]
	v_mfma_f32_16x16x32_bf16 v[44:47], v[144:147], v[194:197], v[44:47]
	v_mfma_f32_16x16x32_bf16 v[36:39], v[158:161], v[194:197], v[36:39]
	v_mfma_f32_16x16x32_bf16 v[28:31], v[144:147], v[206:209], v[28:31]
	v_mfma_f32_16x16x32_bf16 v[20:23], v[158:161], v[206:209], v[20:23]
	v_mfma_f32_16x16x32_bf16 v[12:15], v[144:147], v[214:217], v[12:15]
	v_mfma_f32_16x16x32_bf16 v[4:7], v[158:161], v[214:217], v[4:7]
	s_setprio 0
	s_setprio 1
	v_mfma_f32_16x16x32_bf16 v[56:59], v[162:165], v[178:181], v[56:59]
	v_mfma_f32_16x16x32_bf16 v[48:51], v[170:173], v[178:181], v[48:51]
	v_mfma_f32_16x16x32_bf16 v[40:43], v[162:165], v[186:189], v[40:43]
	v_mfma_f32_16x16x32_bf16 v[32:35], v[170:173], v[186:189], v[32:35]
	v_mfma_f32_16x16x32_bf16 v[24:27], v[162:165], v[202:205], v[24:27]
	v_mfma_f32_16x16x32_bf16 v[16:19], v[170:173], v[202:205], v[16:19]
	v_mfma_f32_16x16x32_bf16 v[8:11], v[162:165], v[210:213], v[8:11]
	v_mfma_f32_16x16x32_bf16 v[0:3], v[170:173], v[210:213], v[0:3]
	v_mfma_f32_16x16x32_bf16 v[56:59], v[166:169], v[182:185], v[56:59]
	v_mfma_f32_16x16x32_bf16 v[48:51], v[174:177], v[182:185], v[48:51]
	v_mfma_f32_16x16x32_bf16 v[40:43], v[166:169], v[194:197], v[40:43]
	v_mfma_f32_16x16x32_bf16 v[32:35], v[174:177], v[194:197], v[32:35]
	v_mfma_f32_16x16x32_bf16 v[24:27], v[166:169], v[206:209], v[24:27]
	v_mfma_f32_16x16x32_bf16 v[16:19], v[174:177], v[206:209], v[16:19]
	v_mfma_f32_16x16x32_bf16 v[8:11], v[166:169], v[214:217], v[8:11]
	v_mfma_f32_16x16x32_bf16 v[0:3], v[174:177], v[214:217], v[0:3]
	s_setprio 0
	s_barrier
	s_add_i32 s24, 0, 0x18000
	v_add_u32_e32 v148, 0x18000, v151
	s_add_i32 s25, 0, 0x1c000
	ds_read_b128 v[140:143], v148
	ds_read_b128 v[144:147], v148 offset:1024
	ds_read_b128 v[154:157], v148 offset:2048
	ds_read_b128 v[158:161], v148 offset:3072
	v_add_u32_e32 v148, 0x1c000, v151
	ds_read_b128 v[162:165], v148
	ds_read_b128 v[166:169], v148 offset:1024
	ds_read_b128 v[170:173], v148 offset:2048
	ds_read_b128 v[174:177], v148 offset:3072
	s_add_u32 s12, s12, 0x80000
	s_addc_u32 s13, s13, 0
	s_mov_b32 m0, s36
	v_lshl_add_u64 v[232:233], s[12:13], 0, v[134:135]
	ds_read_b128 v[178:181], v152 offset:32768
	ds_read_b128 v[182:185], v152 offset:33792
	ds_read_b128 v[186:189], v152 offset:34816
	ds_read_b128 v[194:197], v152 offset:35840
	ds_read_b128 v[202:205], v152 offset:36864
	ds_read_b128 v[206:209], v152 offset:37888
	ds_read_b128 v[210:213], v152 offset:38912
	ds_read_b128 v[214:217], v152 offset:39936
	global_load_lds_dwordx4 v[232:233], off
	s_mov_b32 m0, s37
	v_lshl_add_u64 v[232:233], s[12:13], 0, v[130:131]
	global_load_lds_dwordx4 v[232:233], off
	s_waitcnt vmcnt(8)
	s_waitcnt lgkmcnt(0)
	s_barrier
; #define PG8_STAGE(bufoff, gbase, voff) do { _Pragma("unroll") for (int _i = 0; _i < 2; ++_i) \
;         __builtin_amdgcn_global_load_lds((const unsigned*)((const char*)(gbase) + (voff)[_i]), (PG8_LAS unsigned*)(lds + (bufoff) + ldsw + _i * 8192), 16, 0, 0); } while (0)
; #define PG8_LDA(dst, b, h) do { _Pragma("unroll") for (int m = 0; m < 4; ++m) _Pragma("unroll") for (int k = 0; k < 2; ++k) dst[m][k] = *(const PG8_LAS bf16x8*)(lds + PG8_SA(b, h) + aoff + m * 2048 + k * 1024); } while (0)
; #define PG8_MMA(ai, bj, At, Bt) do { __builtin_amdgcn_s_setprio(1); _Pragma("unroll") for (int m = 0; m < 4; ++m) _Pragma("unroll") for (int n = 0; n < 2; ++n) _Pragma("unroll") for (int k = 0; k < 2; ++k) \
;         acc[ai][bj][m][n] = __builtin_amdgcn_mfma_f32_16x16x32_bf16(Bt[n][k], At[m][k], acc[ai][bj][m][n], 0, 0, 0); __builtin_amdgcn_s_setprio(0); } while (0)
; #define PG8_WAIT_V(n) asm volatile("s_waitcnt vmcnt(" #n ")" ::: "memory")
; #define PG8_WAIT_L(n) asm volatile("s_waitcnt lgkmcnt(" #n ")" ::: "memory")
; #define PG8_BAR __builtin_amdgcn_s_barrier()
; #define PG8_SCHED __builtin_amdgcn_sched_barrier(0)
; template <class Epi, class Sched, bool ALIGN_EPI = false, bool SP2 = false>
; __device__ __forceinline__ void gemm_phase(PG8_LAS unsigned char* lds, const Gemm g, const Sched& S, const Epi& E) {
;     ...
;             PG8_WAIT_V(8); PG8_WAIT_L(0); PG8_BAR; PG8_MMA(0, 0, At, B0); PG8_MMA(0, 1, At, B1); PG8_BAR; PG8_SCHED;
;             PG8_LDA(At, 1, 1); PG8_STAGE(PG8_SB(1, 0), b3, voffB); PG8_STAGE(PG8_SB(1, 1), b3 + hstep, voffB); PG8_STAGE(PG8_SA(1, 0), a3, voffA);
;             PG8_WAIT_V(8); PG8_WAIT_L(0); PG8_BAR; PG8_MMA(1, 0, At, B0); PG8_MMA(1, 1, At, B1); PG8_BAR; PG8_SCHED;
	s_setprio 1
	s_waitcnt lgkmcnt(0)
	v_mfma_f32_16x16x32_bf16 v[124:127], v[140:143], v[178:181], v[124:127]
	v_mfma_f32_16x16x32_bf16 v[112:115], v[154:157], v[178:181], v[112:115]
	v_mfma_f32_16x16x32_bf16 v[108:111], v[140:143], v[186:189], v[108:111]
	v_mfma_f32_16x16x32_bf16 v[100:103], v[154:157], v[186:189], v[100:103]
	v_mfma_f32_16x16x32_bf16 v[92:95], v[140:143], v[202:205], v[92:95]
	v_mfma_f32_16x16x32_bf16 v[84:87], v[154:157], v[202:205], v[84:87]
	v_mfma_f32_16x16x32_bf16 v[76:79], v[140:143], v[210:213], v[76:79]
	v_mfma_f32_16x16x32_bf16 v[68:71], v[154:157], v[210:213], v[68:71]
	v_mfma_f32_16x16x32_bf16 v[124:127], v[144:147], v[182:185], v[124:127]
	v_mfma_f32_16x16x32_bf16 v[112:115], v[158:161], v[182:185], v[112:115]
	v_mfma_f32_16x16x32_bf16 v[108:111], v[144:147], v[194:197], v[108:111]
	v_mfma_f32_16x16x32_bf16 v[100:103], v[158:161], v[194:197], v[100:103]
	v_mfma_f32_16x16x32_bf16 v[92:95], v[144:147], v[206:209], v[92:95]
	v_mfma_f32_16x16x32_bf16 v[84:87], v[158:161], v[206:209], v[84:87]
	v_mfma_f32_16x16x32_bf16 v[76:79], v[144:147], v[214:217], v[76:79]
	v_mfma_f32_16x16x32_bf16 v[68:71], v[158:161], v[214:217], v[68:71]
	s_setprio 0
	s_setprio 1
	v_mfma_f32_16x16x32_bf16 v[120:123], v[162:165], v[178:181], v[120:123]
	v_mfma_f32_16x16x32_bf16 v[116:119], v[170:173], v[178:181], v[116:119]
	v_mfma_f32_16x16x32_bf16 v[104:107], v[162:165], v[186:189], v[104:107]
	v_mfma_f32_16x16x32_bf16 v[96:99], v[170:173], v[186:189], v[96:99]
	v_mfma_f32_16x16x32_bf16 v[88:91], v[162:165], v[202:205], v[88:91]
	v_mfma_f32_16x16x32_bf16 v[80:83], v[170:173], v[202:205], v[80:83]
	v_mfma_f32_16x16x32_bf16 v[72:75], v[162:165], v[210:213], v[72:75]
	v_mfma_f32_16x16x32_bf16 v[64:67], v[170:173], v[210:213], v[64:67]
	v_mfma_f32_16x16x32_bf16 v[120:123], v[166:169], v[182:185], v[120:123]
	v_mfma_f32_16x16x32_bf16 v[116:119], v[174:177], v[182:185], v[116:119]
	v_mfma_f32_16x16x32_bf16 v[104:107], v[166:169], v[194:197], v[104:107]
	v_mfma_f32_16x16x32_bf16 v[96:99], v[174:177], v[194:197], v[96:99]
	v_mfma_f32_16x16x32_bf16 v[88:91], v[166:169], v[206:209], v[88:91]
	v_mfma_f32_16x16x32_bf16 v[80:83], v[174:177], v[206:209], v[80:83]
	v_mfma_f32_16x16x32_bf16 v[72:75], v[166:169], v[214:217], v[72:75]
	v_mfma_f32_16x16x32_bf16 v[64:67], v[174:177], v[214:217], v[64:67]
	s_setprio 0
	s_barrier
	s_add_i32 s12, s24, s30
	v_lshl_add_u64 v[190:191], v[190:191], 0, s[16:17]
	s_mov_b32 m0, s12
	ds_read_b128 v[178:181], v152 offset:49152
	ds_read_b128 v[182:185], v152 offset:50176
	ds_read_b128 v[186:189], v152 offset:51200
	ds_read_b128 v[194:197], v152 offset:52224
	ds_read_b128 v[202:205], v152 offset:53248
	ds_read_b128 v[206:209], v152 offset:54272
	ds_read_b128 v[210:213], v152 offset:55296
	ds_read_b128 v[214:217], v152 offset:56320
	global_load_lds_dwordx4 v[190:191], off
	s_add_i32 m0, s12, 0x2000
	s_add_u32 s10, s10, 0x80080
	v_lshl_add_u64 v[190:191], v[218:219], 0, s[16:17]
	s_addc_u32 s11, s11, 0
	s_add_i32 s12, s25, s30
	global_load_lds_dwordx4 v[190:191], off
	s_mov_b32 m0, s12
	v_lshl_add_u64 v[190:191], s[10:11], 0, v[132:133]
	global_load_lds_dwordx4 v[190:191], off
	s_add_i32 m0, s12, 0x2000
	v_lshl_add_u64 v[190:191], s[10:11], 0, v[128:129]
	global_load_lds_dwordx4 v[190:191], off
	s_mov_b32 m0, s56
	v_lshl_add_u64 v[190:191], v[220:221], 0, s[16:17]
	global_load_lds_dwordx4 v[190:191], off
	s_mov_b32 m0, s57
	v_lshl_add_u64 v[190:191], v[230:231], 0, s[16:17]
	global_load_lds_dwordx4 v[190:191], off
	s_waitcnt vmcnt(8)
	s_waitcnt lgkmcnt(0)
	s_barrier
	s_setprio 1
	s_waitcnt lgkmcnt(0)
	v_mfma_f32_16x16x32_bf16 v[60:63], v[140:143], v[178:181], v[60:63]
	v_mfma_f32_16x16x32_bf16 v[52:55], v[154:157], v[178:181], v[52:55]
	v_mfma_f32_16x16x32_bf16 v[44:47], v[140:143], v[186:189], v[44:47]
	v_mfma_f32_16x16x32_bf16 v[36:39], v[154:157], v[186:189], v[36:39]
	v_mfma_f32_16x16x32_bf16 v[28:31], v[140:143], v[202:205], v[28:31]
	v_mfma_f32_16x16x32_bf16 v[20:23], v[154:157], v[202:205], v[20:23]
	v_mfma_f32_16x16x32_bf16 v[12:15], v[140:143], v[210:213], v[12:15]
	v_mfma_f32_16x16x32_bf16 v[4:7], v[154:157], v[210:213], v[4:7]
	v_mfma_f32_16x16x32_bf16 v[60:63], v[144:147], v[182:185], v[60:63]
	v_mfma_f32_16x16x32_bf16 v[52:55], v[158:161], v[182:185], v[52:55]
	v_mfma_f32_16x16x32_bf16 v[44:47], v[144:147], v[194:197], v[44:47]
	v_mfma_f32_16x16x32_bf16 v[36:39], v[158:161], v[194:197], v[36:39]
	v_mfma_f32_16x16x32_bf16 v[28:31], v[144:147], v[206:209], v[28:31]
	v_mfma_f32_16x16x32_bf16 v[20:23], v[158:161], v[206:209], v[20:23]
	v_mfma_f32_16x16x32_bf16 v[12:15], v[144:147], v[214:217], v[12:15]
	v_mfma_f32_16x16x32_bf16 v[4:7], v[158:161], v[214:217], v[4:7]
	s_setprio 0
	s_setprio 1
	v_mfma_f32_16x16x32_bf16 v[56:59], v[162:165], v[178:181], v[56:59]
	v_mfma_f32_16x16x32_bf16 v[48:51], v[170:173], v[178:181], v[48:51]
	v_mfma_f32_16x16x32_bf16 v[40:43], v[162:165], v[186:189], v[40:43]
	v_mfma_f32_16x16x32_bf16 v[32:35], v[170:173], v[186:189], v[32:35]
	v_mfma_f32_16x16x32_bf16 v[24:27], v[162:165], v[202:205], v[24:27]
	v_mfma_f32_16x16x32_bf16 v[16:19], v[170:173], v[202:205], v[16:19]
	v_mfma_f32_16x16x32_bf16 v[8:11], v[162:165], v[210:213], v[8:11]
	v_mfma_f32_16x16x32_bf16 v[0:3], v[170:173], v[210:213], v[0:3]
	v_mfma_f32_16x16x32_bf16 v[56:59], v[166:169], v[182:185], v[56:59]
	v_mfma_f32_16x16x32_bf16 v[48:51], v[174:177], v[182:185], v[48:51]
	v_mfma_f32_16x16x32_bf16 v[40:43], v[166:169], v[194:197], v[40:43]
	v_mfma_f32_16x16x32_bf16 v[32:35], v[174:177], v[194:197], v[32:35]
	v_mfma_f32_16x16x32_bf16 v[24:27], v[166:169], v[206:209], v[24:27]
	v_mfma_f32_16x16x32_bf16 v[16:19], v[174:177], v[206:209], v[16:19]
	v_mfma_f32_16x16x32_bf16 v[8:11], v[166:169], v[214:217], v[8:11]
	v_mfma_f32_16x16x32_bf16 v[0:3], v[174:177], v[214:217], v[0:3]
	s_setprio 0
	s_add_i32 s64, s64, 2
	s_add_u32 s0, s0, 0x100
	s_addc_u32 s1, s1, 0
	s_add_u32 s62, s62, 0x100
	s_addc_u32 s63, s63, 0
	s_cmp_gt_u32 s64, 29
	s_barrier
	s_cbranch_scc0 .LBB0_730
	s_and_b64 vcc, exec, s[44:45]
	s_cbranch_vccz .LBB0_733
	s_barrier

; #define PG8_STAGE(bufoff, gbase, voff) do { _Pragma("unroll") for (int _i = 0; _i < 2; ++_i) \
;         __builtin_amdgcn_global_load_lds((const unsigned*)((const char*)(gbase) + (voff)[_i]), (PG8_LAS unsigned*)(lds + (bufoff) + ldsw + _i * 8192), 16, 0, 0); } while (0)
; #define PG8_LDA(dst, b, h) do { _Pragma("unroll") for (int m = 0; m < 4; ++m) _Pragma("unroll") for (int k = 0; k < 2; ++k) dst[m][k] = *(const PG8_LAS bf16x8*)(lds + PG8_SA(b, h) + aoff + m * 2048 + k * 1024); } while (0)
; #define PG8_LDB(dst, b, h) do { _Pragma("unroll") for (int n = 0; n < 2; ++n) _Pragma("unroll") for (int k = 0; k < 2; ++k) dst[n][k] = *(const PG8_LAS bf16x8*)(lds + PG8_SB(b, h) + boff + n * 2048 + k * 1024); } while (0)
; #define PG8_MMA(ai, bj, At, Bt) do { __builtin_amdgcn_s_setprio(1); _Pragma("unroll") for (int m = 0; m < 4; ++m) _Pragma("unroll") for (int n = 0; n < 2; ++n) _Pragma("unroll") for (int k = 0; k < 2; ++k) \
;         acc[ai][bj][m][n] = __builtin_amdgcn_mfma_f32_16x16x32_bf16(Bt[n][k], At[m][k], acc[ai][bj][m][n], 0, 0, 0); __builtin_amdgcn_s_setprio(0); } while (0)
; #define PG8_WAIT_V(n) asm volatile("s_waitcnt vmcnt(" #n ")" ::: "memory")
; #define PG8_WAIT_L(n) asm volatile("s_waitcnt lgkmcnt(" #n ")" ::: "memory")
; template <class Epi, class Sched, bool ALIGN_EPI = false, bool SP2 = false>
; __device__ __forceinline__ void gemm_phase(PG8_LAS unsigned char* lds, const Gemm g, const Sched& S, const Epi& E) {
;     ...
;             const bool last = (t == nt - 2);
;             const char* a1 = cA + (size_t)(t + 1) * kstep;
;             const char* a2 = last ? nA : cA + (size_t)(t + 2) * kstep; const char* b2 = last ? nB : cB + (size_t)(t + 2) * kstep;
;             const char* a3 = a2 + kstep; const char* b3 = b2 + kstep;
;             if (last && has_next) S.a_ready(nxt);
;             if constexpr (SP2) {
;             PG8_LDB(B0, 0, 0); PG8_LDB(B1, 0, 1); PG8_SCHED; PG8_LDA(At, 0, 0); PG8_STAGE(PG8_SA(1, 1), a1 + hstep, voffA);
;             PG8_WAIT_V(8); PG8_WAIT_L(0); PG8_BAR; PG8_MMA(0, 0, At, B0); PG8_MMA(0, 1, At, B1); PG8_BAR; PG8_SCHED;
;             PG8_LDA(At, 0, 1); PG8_STAGE(PG8_SB(0, 0), b2, voffB); PG8_STAGE(PG8_SB(0, 1), b2 + hstep, voffB); PG8_STAGE(PG8_SA(0, 0), a2, voffA);
;             PG8_WAIT_V(8); PG8_WAIT_L(0); PG8_BAR; PG8_MMA(1, 0, At, B0); PG8_MMA(1, 1, At, B1); PG8_BAR; PG8_SCHED;
.LBB0_816:
	s_add_u32 s59, s30, 0x100
	s_addc_u32 s60, s31, 0
	s_mov_b32 s61, -2
	s_waitcnt lgkmcnt(0)
	v_lshl_add_u64 v[168:169], s[18:19], 0, v[160:161]
	s_add_i32 m0, s2, 0xc000
	global_load_lds_dwordx4 v[168:169], off
	s_add_i32 m0, s2, 0xe000
	v_lshl_add_u64 v[168:169], s[18:19], 0, v[162:163]
	global_load_lds_dwordx4 v[168:169], off
	s_add_u32 s30, s18, 0x100
	s_addc_u32 s31, s19, 0
	s_add_i32 s24, 0, 0x10000
	s_cmpk_eq_i32 s61, 0x54
	s_cselect_b32 s39, s5, s31
	s_cselect_b32 s38, s4, s30
	s_cselect_b32 s37, s15, s60
	s_cselect_b32 s36, s14, s59
	s_add_i32 s25, 0, 0x14000
	s_waitcnt vmcnt(8)
	s_waitcnt lgkmcnt(0)
	s_barrier
	s_setprio 1
	s_waitcnt lgkmcnt(0)
	v_mfma_f32_16x16x32_bf16 v[124:127], v[128:131], v[178:181], 0
	v_mfma_f32_16x16x32_bf16 v[120:123], v[136:139], v[178:181], 0
	v_mfma_f32_16x16x32_bf16 v[108:111], v[128:131], v[186:189], 0
	v_mfma_f32_16x16x32_bf16 v[104:107], v[136:139], v[186:189], 0
	v_mfma_f32_16x16x32_bf16 v[92:95], v[128:131], v[202:205], 0
	v_mfma_f32_16x16x32_bf16 v[88:91], v[136:139], v[202:205], 0
	v_mfma_f32_16x16x32_bf16 v[76:79], v[128:131], v[210:213], 0
	v_mfma_f32_16x16x32_bf16 v[72:75], v[136:139], v[210:213], 0
	v_mfma_f32_16x16x32_bf16 v[124:127], v[132:135], v[182:185], v[124:127]
	v_mfma_f32_16x16x32_bf16 v[120:123], v[140:143], v[182:185], v[120:123]
	v_mfma_f32_16x16x32_bf16 v[108:111], v[132:135], v[194:197], v[108:111]
	v_mfma_f32_16x16x32_bf16 v[104:107], v[140:143], v[194:197], v[104:107]
	v_mfma_f32_16x16x32_bf16 v[92:95], v[132:135], v[206:209], v[92:95]
	v_mfma_f32_16x16x32_bf16 v[88:91], v[140:143], v[206:209], v[88:91]
	v_mfma_f32_16x16x32_bf16 v[76:79], v[132:135], v[214:217], v[76:79]
	v_mfma_f32_16x16x32_bf16 v[72:75], v[140:143], v[214:217], v[72:75]
	s_setprio 0
	s_setprio 1
	v_mfma_f32_16x16x32_bf16 v[116:119], v[144:147], v[178:181], 0
	v_mfma_f32_16x16x32_bf16 v[112:115], v[164:167], v[178:181], 0
	v_mfma_f32_16x16x32_bf16 v[100:103], v[144:147], v[186:189], 0
	v_mfma_f32_16x16x32_bf16 v[96:99], v[164:167], v[186:189], 0
	v_mfma_f32_16x16x32_bf16 v[84:87], v[144:147], v[202:205], 0
	v_mfma_f32_16x16x32_bf16 v[80:83], v[164:167], v[202:205], 0
	v_mfma_f32_16x16x32_bf16 v[68:71], v[144:147], v[210:213], 0
	v_mfma_f32_16x16x32_bf16 v[64:67], v[164:167], v[210:213], 0
	v_mfma_f32_16x16x32_bf16 v[116:119], v[148:151], v[182:185], v[116:119]
	v_mfma_f32_16x16x32_bf16 v[112:115], v[174:177], v[182:185], v[112:115]
	v_mfma_f32_16x16x32_bf16 v[100:103], v[148:151], v[194:197], v[100:103]
	v_mfma_f32_16x16x32_bf16 v[96:99], v[174:177], v[194:197], v[96:99]
	v_mfma_f32_16x16x32_bf16 v[84:87], v[148:151], v[206:209], v[84:87]
	v_mfma_f32_16x16x32_bf16 v[80:83], v[174:177], v[206:209], v[80:83]
	v_mfma_f32_16x16x32_bf16 v[68:71], v[148:151], v[214:217], v[68:71]
	v_mfma_f32_16x16x32_bf16 v[64:67], v[174:177], v[214:217], v[64:67]
	s_setprio 0
	s_barrier
	s_add_i32 s18, s24, s43
	v_lshl_add_u64 v[168:169], s[36:37], 0, v[156:157]
	s_mov_b32 m0, s18
	ds_read_b128 v[178:181], v173 offset:16384
	ds_read_b128 v[182:185], v173 offset:17408
	ds_read_b128 v[186:189], v173 offset:18432
	ds_read_b128 v[194:197], v173 offset:19456
	ds_read_b128 v[202:205], v173 offset:20480
	ds_read_b128 v[206:209], v173 offset:21504
	ds_read_b128 v[210:213], v173 offset:22528
	ds_read_b128 v[214:217], v173 offset:23552
	global_load_lds_dwordx4 v[168:169], off
	s_add_i32 m0, s18, 0x2000
	s_add_u32 s18, s36, 0x160000
	v_lshl_add_u64 v[190:191], s[36:37], 0, v[152:153]
	s_addc_u32 s19, s37, 0
	s_add_i32 s24, s25, s43
	global_load_lds_dwordx4 v[190:191], off
	v_lshl_add_u64 v[218:219], s[18:19], 0, v[156:157]
	s_mov_b32 m0, s24
	v_lshl_add_u64 v[220:221], s[38:39], 0, v[154:155]
	global_load_lds_dwordx4 v[218:219], off
	s_add_i32 m0, s24, 0x2000
	v_lshl_add_u64 v[218:219], s[18:19], 0, v[152:153]
	global_load_lds_dwordx4 v[218:219], off
	s_mov_b32 m0, s2
	v_lshl_add_u64 v[218:219], s[38:39], 0, v[158:159]
	global_load_lds_dwordx4 v[218:219], off
	s_mov_b32 m0, s44
	s_nop 0
	global_load_lds_dwordx4 v[220:221], off
	s_waitcnt vmcnt(8)
	s_waitcnt lgkmcnt(0)
	s_barrier
	s_setprio 1
	s_waitcnt lgkmcnt(0)
	v_mfma_f32_16x16x32_bf16 v[60:63], v[128:131], v[178:181], 0
	v_mfma_f32_16x16x32_bf16 v[56:59], v[136:139], v[178:181], 0
	v_mfma_f32_16x16x32_bf16 v[44:47], v[128:131], v[186:189], 0
	v_mfma_f32_16x16x32_bf16 v[40:43], v[136:139], v[186:189], 0
	v_mfma_f32_16x16x32_bf16 v[28:31], v[128:131], v[202:205], 0
	v_mfma_f32_16x16x32_bf16 v[24:27], v[136:139], v[202:205], 0
	v_mfma_f32_16x16x32_bf16 v[12:15], v[128:131], v[210:213], 0
	v_mfma_f32_16x16x32_bf16 v[8:11], v[136:139], v[210:213], 0
	v_mfma_f32_16x16x32_bf16 v[60:63], v[132:135], v[182:185], v[60:63]
	v_mfma_f32_16x16x32_bf16 v[56:59], v[140:143], v[182:185], v[56:59]
	v_mfma_f32_16x16x32_bf16 v[44:47], v[132:135], v[194:197], v[44:47]
	v_mfma_f32_16x16x32_bf16 v[40:43], v[140:143], v[194:197], v[40:43]
	v_mfma_f32_16x16x32_bf16 v[28:31], v[132:135], v[206:209], v[28:31]
	v_mfma_f32_16x16x32_bf16 v[24:27], v[140:143], v[206:209], v[24:27]
	v_mfma_f32_16x16x32_bf16 v[12:15], v[132:135], v[214:217], v[12:15]
	v_mfma_f32_16x16x32_bf16 v[8:11], v[140:143], v[214:217], v[8:11]
	s_setprio 0
	s_setprio 1
	v_mfma_f32_16x16x32_bf16 v[52:55], v[144:147], v[178:181], 0
	v_mfma_f32_16x16x32_bf16 v[48:51], v[164:167], v[178:181], 0
	v_mfma_f32_16x16x32_bf16 v[36:39], v[144:147], v[186:189], 0
	v_mfma_f32_16x16x32_bf16 v[32:35], v[164:167], v[186:189], 0
	v_mfma_f32_16x16x32_bf16 v[20:23], v[144:147], v[202:205], 0
	v_mfma_f32_16x16x32_bf16 v[16:19], v[164:167], v[202:205], 0
	v_mfma_f32_16x16x32_bf16 v[4:7], v[144:147], v[210:213], 0
	v_mfma_f32_16x16x32_bf16 v[0:3], v[164:167], v[210:213], 0
	v_mfma_f32_16x16x32_bf16 v[52:55], v[148:151], v[182:185], v[52:55]
	v_mfma_f32_16x16x32_bf16 v[48:51], v[174:177], v[182:185], v[48:51]
	v_mfma_f32_16x16x32_bf16 v[36:39], v[148:151], v[194:197], v[36:39]
	v_mfma_f32_16x16x32_bf16 v[32:35], v[174:177], v[194:197], v[32:35]
	v_mfma_f32_16x16x32_bf16 v[20:23], v[148:151], v[206:209], v[20:23]
	v_mfma_f32_16x16x32_bf16 v[16:19], v[174:177], v[206:209], v[16:19]
	v_mfma_f32_16x16x32_bf16 v[4:7], v[148:151], v[214:217], v[4:7]
	v_mfma_f32_16x16x32_bf16 v[0:3], v[174:177], v[214:217], v[0:3]
	s_setprio 0
	s_barrier
; #define PG8_STAGE(bufoff, gbase, voff) do { _Pragma("unroll") for (int _i = 0; _i < 2; ++_i) \
;         __builtin_amdgcn_global_load_lds((const unsigned*)((const char*)(gbase) + (voff)[_i]), (PG8_LAS unsigned*)(lds + (bufoff) + ldsw + _i * 8192), 16, 0, 0); } while (0)
; #define PG8_LDA(dst, b, h) do { _Pragma("unroll") for (int m = 0; m < 4; ++m) _Pragma("unroll") for (int k = 0; k < 2; ++k) dst[m][k] = *(const PG8_LAS bf16x8*)(lds + PG8_SA(b, h) + aoff + m * 2048 + k * 1024); } while (0)
; #define PG8_LDB(dst, b, h) do { _Pragma("unroll") for (int n = 0; n < 2; ++n) _Pragma("unroll") for (int k = 0; k < 2; ++k) dst[n][k] = *(const PG8_LAS bf16x8*)(lds + PG8_SB(b, h) + boff + n * 2048 + k * 1024); } while (0)
; #define PG8_MMA(ai, bj, At, Bt) do { __builtin_amdgcn_s_setprio(1); _Pragma("unroll") for (int m = 0; m < 4; ++m) _Pragma("unroll") for (int n = 0; n < 2; ++n) _Pragma("unroll") for (int k = 0; k < 2; ++k) \
;         acc[ai][bj][m][n] = __builtin_amdgcn_mfma_f32_16x16x32_bf16(Bt[n][k], At[m][k], acc[ai][bj][m][n], 0, 0, 0); __builtin_amdgcn_s_setprio(0); } while (0)
; #define PG8_WAIT_V(n) asm volatile("s_waitcnt vmcnt(" #n ")" ::: "memory")
; #define PG8_WAIT_L(n) asm volatile("s_waitcnt lgkmcnt(" #n ")" ::: "memory")
; #define PG8_BAR __builtin_amdgcn_s_barrier()
; #define PG8_SCHED __builtin_amdgcn_sched_barrier(0)
; template <class Epi, class Sched, bool ALIGN_EPI = false, bool SP2 = false>
; __device__ __forceinline__ void gemm_phase(PG8_LAS unsigned char* lds, const Gemm g, const Sched& S, const Epi& E) {
;     ...
;             PG8_LDB(B0, 1, 0); PG8_LDB(B1, 1, 1); PG8_SCHED; PG8_LDA(At, 1, 0); PG8_STAGE(PG8_SA(0, 1), a2 + hstep, voffA);
;             PG8_WAIT_V(8); PG8_WAIT_L(0); PG8_BAR; PG8_MMA(0, 0, At, B0); PG8_MMA(0, 1, At, B1); PG8_BAR; PG8_SCHED;
;             PG8_LDA(At, 1, 1); PG8_STAGE(PG8_SB(1, 0), b3, voffB); PG8_STAGE(PG8_SB(1, 1), b3 + hstep, voffB); PG8_STAGE(PG8_SA(1, 0), a3, voffA);
	s_add_i32 s24, 0, 0x18000
	s_add_i32 s25, 0, 0x1c000
	v_add_u32_e32 v140, 0x18000, v172
	v_add_u32_e32 v174, 0x1c000, v172
	ds_read_b128 v[128:131], v140
	ds_read_b128 v[132:135], v140 offset:1024
	ds_read_b128 v[136:139], v140 offset:2048
	ds_read_b128 v[140:143], v140 offset:3072
	ds_read_b128 v[144:147], v174
	ds_read_b128 v[148:151], v174 offset:1024
	ds_read_b128 v[164:167], v174 offset:2048
	ds_read_b128 v[174:177], v174 offset:3072
	s_add_u32 s18, s38, 0x160000
	s_addc_u32 s19, s39, 0
	s_mov_b32 m0, s45
	v_lshl_add_u64 v[230:231], s[18:19], 0, v[158:159]
	ds_read_b128 v[178:181], v173 offset:32768
	ds_read_b128 v[182:185], v173 offset:33792
	ds_read_b128 v[186:189], v173 offset:34816
	ds_read_b128 v[194:197], v173 offset:35840
	ds_read_b128 v[202:205], v173 offset:36864
	ds_read_b128 v[206:209], v173 offset:37888
	ds_read_b128 v[210:213], v173 offset:38912
	ds_read_b128 v[214:217], v173 offset:39936
	global_load_lds_dwordx4 v[230:231], off
	s_mov_b32 m0, s46
	v_lshl_add_u64 v[230:231], s[18:19], 0, v[154:155]
	global_load_lds_dwordx4 v[230:231], off
	s_waitcnt vmcnt(8)
	s_waitcnt lgkmcnt(0)
	s_barrier
	s_setprio 1
	s_waitcnt lgkmcnt(0)
	v_mfma_f32_16x16x32_bf16 v[124:127], v[128:131], v[178:181], v[124:127]
	v_mfma_f32_16x16x32_bf16 v[120:123], v[136:139], v[178:181], v[120:123]
	v_mfma_f32_16x16x32_bf16 v[108:111], v[128:131], v[186:189], v[108:111]
	v_mfma_f32_16x16x32_bf16 v[104:107], v[136:139], v[186:189], v[104:107]
	v_mfma_f32_16x16x32_bf16 v[92:95], v[128:131], v[202:205], v[92:95]
	v_mfma_f32_16x16x32_bf16 v[88:91], v[136:139], v[202:205], v[88:91]
	v_mfma_f32_16x16x32_bf16 v[76:79], v[128:131], v[210:213], v[76:79]
	v_mfma_f32_16x16x32_bf16 v[72:75], v[136:139], v[210:213], v[72:75]
	v_mfma_f32_16x16x32_bf16 v[124:127], v[132:135], v[182:185], v[124:127]
	v_mfma_f32_16x16x32_bf16 v[120:123], v[140:143], v[182:185], v[120:123]
	v_mfma_f32_16x16x32_bf16 v[108:111], v[132:135], v[194:197], v[108:111]
	v_mfma_f32_16x16x32_bf16 v[104:107], v[140:143], v[194:197], v[104:107]
	v_mfma_f32_16x16x32_bf16 v[92:95], v[132:135], v[206:209], v[92:95]
	v_mfma_f32_16x16x32_bf16 v[88:91], v[140:143], v[206:209], v[88:91]
	v_mfma_f32_16x16x32_bf16 v[76:79], v[132:135], v[214:217], v[76:79]
	v_mfma_f32_16x16x32_bf16 v[72:75], v[140:143], v[214:217], v[72:75]
	s_setprio 0
	s_setprio 1
	v_mfma_f32_16x16x32_bf16 v[116:119], v[144:147], v[178:181], v[116:119]
	v_mfma_f32_16x16x32_bf16 v[112:115], v[164:167], v[178:181], v[112:115]
	v_mfma_f32_16x16x32_bf16 v[100:103], v[144:147], v[186:189], v[100:103]
	v_mfma_f32_16x16x32_bf16 v[96:99], v[164:167], v[186:189], v[96:99]
	v_mfma_f32_16x16x32_bf16 v[84:87], v[144:147], v[202:205], v[84:87]
	v_mfma_f32_16x16x32_bf16 v[80:83], v[164:167], v[202:205], v[80:83]
	v_mfma_f32_16x16x32_bf16 v[68:71], v[144:147], v[210:213], v[68:71]
	v_mfma_f32_16x16x32_bf16 v[64:67], v[164:167], v[210:213], v[64:67]
	v_mfma_f32_16x16x32_bf16 v[116:119], v[148:151], v[182:185], v[116:119]
	v_mfma_f32_16x16x32_bf16 v[112:115], v[174:177], v[182:185], v[112:115]
	v_mfma_f32_16x16x32_bf16 v[100:103], v[148:151], v[194:197], v[100:103]
	v_mfma_f32_16x16x32_bf16 v[96:99], v[174:177], v[194:197], v[96:99]
	v_mfma_f32_16x16x32_bf16 v[84:87], v[148:151], v[206:209], v[84:87]
	v_mfma_f32_16x16x32_bf16 v[80:83], v[174:177], v[206:209], v[80:83]
	v_mfma_f32_16x16x32_bf16 v[68:71], v[148:151], v[214:217], v[68:71]
	v_mfma_f32_16x16x32_bf16 v[64:67], v[174:177], v[214:217], v[64:67]
	s_setprio 0
	s_barrier
	s_add_i32 s18, s24, s43
	v_lshl_add_u64 v[168:169], v[168:169], 0, s[16:17]
	s_mov_b32 m0, s18
	ds_read_b128 v[178:181], v173 offset:49152
	ds_read_b128 v[182:185], v173 offset:50176
	ds_read_b128 v[186:189], v173 offset:51200
	ds_read_b128 v[194:197], v173 offset:52224
	ds_read_b128 v[202:205], v173 offset:53248
	ds_read_b128 v[206:209], v173 offset:54272
	ds_read_b128 v[210:213], v173 offset:55296
	ds_read_b128 v[214:217], v173 offset:56320
	global_load_lds_dwordx4 v[168:169], off
	s_add_i32 m0, s18, 0x2000
	s_add_u32 s18, s36, 0x160080
	v_lshl_add_u64 v[168:169], v[190:191], 0, s[16:17]
	s_addc_u32 s19, s37, 0
	s_add_i32 s24, s25, s43
	global_load_lds_dwordx4 v[168:169], off
	s_mov_b32 m0, s24
	v_lshl_add_u64 v[168:169], s[18:19], 0, v[156:157]
	global_load_lds_dwordx4 v[168:169], off
	s_add_i32 m0, s24, 0x2000
	v_lshl_add_u64 v[168:169], s[18:19], 0, v[152:153]
	global_load_lds_dwordx4 v[168:169], off
	s_mov_b32 m0, s51
	v_lshl_add_u64 v[168:169], v[218:219], 0, s[16:17]
	global_load_lds_dwordx4 v[168:169], off
	s_mov_b32 m0, s52
	v_lshl_add_u64 v[168:169], v[220:221], 0, s[16:17]
	global_load_lds_dwordx4 v[168:169], off
	s_waitcnt vmcnt(8)
	s_waitcnt lgkmcnt(0)
	s_barrier
; #define PG8_STAGE(bufoff, gbase, voff) do { _Pragma("unroll") for (int _i = 0; _i < 2; ++_i) \
;         __builtin_amdgcn_global_load_lds((const unsigned*)((const char*)(gbase) + (voff)[_i]), (PG8_LAS unsigned*)(lds + (bufoff) + ldsw + _i * 8192), 16, 0, 0); } while (0)
; #define PG8_LDA(dst, b, h) do { _Pragma("unroll") for (int m = 0; m < 4; ++m) _Pragma("unroll") for (int k = 0; k < 2; ++k) dst[m][k] = *(const PG8_LAS bf16x8*)(lds + PG8_SA(b, h) + aoff + m * 2048 + k * 1024); } while (0)
; #define PG8_LDB(dst, b, h) do { _Pragma("unroll") for (int n = 0; n < 2; ++n) _Pragma("unroll") for (int k = 0; k < 2; ++k) dst[n][k] = *(const PG8_LAS bf16x8*)(lds + PG8_SB(b, h) + boff + n * 2048 + k * 1024); } while (0)
; #define PG8_MMA(ai, bj, At, Bt) do { __builtin_amdgcn_s_setprio(1); _Pragma("unroll") for (int m = 0; m < 4; ++m) _Pragma("unroll") for (int n = 0; n < 2; ++n) _Pragma("unroll") for (int k = 0; k < 2; ++k) \
;         acc[ai][bj][m][n] = __builtin_amdgcn_mfma_f32_16x16x32_bf16(Bt[n][k], At[m][k], acc[ai][bj][m][n], 0, 0, 0); __builtin_amdgcn_s_setprio(0); } while (0)
; #define PG8_WAIT_V(n) asm volatile("s_waitcnt vmcnt(" #n ")" ::: "memory")
; #define PG8_WAIT_L(n) asm volatile("s_waitcnt lgkmcnt(" #n ")" ::: "memory")
; #define PG8_BAR __builtin_amdgcn_s_barrier()
; #define PG8_SCHED __builtin_amdgcn_sched_barrier(0)
; template <class Epi, class Sched, bool ALIGN_EPI = false, bool SP2 = false>
; __device__ __forceinline__ void gemm_phase(PG8_LAS unsigned char* lds, const Gemm g, const Sched& S, const Epi& E) {
;     ...
;         for (int t = 0; t < nt; t += 2) {
;     ...
;             PG8_LDB(B0, 0, 0); PG8_LDB(B1, 0, 1); PG8_SCHED; PG8_LDA(At, 0, 0); PG8_STAGE(PG8_SA(1, 1), a1 + hstep, voffA);
;             PG8_WAIT_V(8); PG8_WAIT_L(0); PG8_BAR; PG8_MMA(0, 0, At, B0); PG8_MMA(0, 1, At, B1); PG8_BAR; PG8_SCHED;
;     ...
;             PG8_WAIT_V(8); PG8_WAIT_L(0); PG8_BAR; PG8_MMA(1, 0, At, B0); PG8_MMA(1, 1, At, B1); PG8_BAR; PG8_SCHED;
	s_setprio 1
	s_waitcnt lgkmcnt(0)
	v_mfma_f32_16x16x32_bf16 v[60:63], v[128:131], v[178:181], v[60:63]
	v_mfma_f32_16x16x32_bf16 v[56:59], v[136:139], v[178:181], v[56:59]
	v_mfma_f32_16x16x32_bf16 v[44:47], v[128:131], v[186:189], v[44:47]
	v_mfma_f32_16x16x32_bf16 v[40:43], v[136:139], v[186:189], v[40:43]
	v_mfma_f32_16x16x32_bf16 v[28:31], v[128:131], v[202:205], v[28:31]
	v_mfma_f32_16x16x32_bf16 v[24:27], v[136:139], v[202:205], v[24:27]
	v_mfma_f32_16x16x32_bf16 v[12:15], v[128:131], v[210:213], v[12:15]
	v_mfma_f32_16x16x32_bf16 v[8:11], v[136:139], v[210:213], v[8:11]
	v_mfma_f32_16x16x32_bf16 v[60:63], v[132:135], v[182:185], v[60:63]
	v_mfma_f32_16x16x32_bf16 v[56:59], v[140:143], v[182:185], v[56:59]
	v_mfma_f32_16x16x32_bf16 v[44:47], v[132:135], v[194:197], v[44:47]
	v_mfma_f32_16x16x32_bf16 v[40:43], v[140:143], v[194:197], v[40:43]
	v_mfma_f32_16x16x32_bf16 v[28:31], v[132:135], v[206:209], v[28:31]
	v_mfma_f32_16x16x32_bf16 v[24:27], v[140:143], v[206:209], v[24:27]
	v_mfma_f32_16x16x32_bf16 v[12:15], v[132:135], v[214:217], v[12:15]
	v_mfma_f32_16x16x32_bf16 v[8:11], v[140:143], v[214:217], v[8:11]
	s_setprio 0
	s_setprio 1
	v_mfma_f32_16x16x32_bf16 v[52:55], v[144:147], v[178:181], v[52:55]
	v_mfma_f32_16x16x32_bf16 v[48:51], v[164:167], v[178:181], v[48:51]
	v_mfma_f32_16x16x32_bf16 v[36:39], v[144:147], v[186:189], v[36:39]
	v_mfma_f32_16x16x32_bf16 v[32:35], v[164:167], v[186:189], v[32:35]
	v_mfma_f32_16x16x32_bf16 v[20:23], v[144:147], v[202:205], v[20:23]
	v_mfma_f32_16x16x32_bf16 v[16:19], v[164:167], v[202:205], v[16:19]
	v_mfma_f32_16x16x32_bf16 v[4:7], v[144:147], v[210:213], v[4:7]
	v_mfma_f32_16x16x32_bf16 v[0:3], v[164:167], v[210:213], v[0:3]
	v_mfma_f32_16x16x32_bf16 v[52:55], v[148:151], v[182:185], v[52:55]
	v_mfma_f32_16x16x32_bf16 v[48:51], v[174:177], v[182:185], v[48:51]
	v_mfma_f32_16x16x32_bf16 v[36:39], v[148:151], v[194:197], v[36:39]
	v_mfma_f32_16x16x32_bf16 v[32:35], v[174:177], v[194:197], v[32:35]
	v_mfma_f32_16x16x32_bf16 v[20:23], v[148:151], v[206:209], v[20:23]
	v_mfma_f32_16x16x32_bf16 v[16:19], v[174:177], v[206:209], v[16:19]
	v_mfma_f32_16x16x32_bf16 v[4:7], v[148:151], v[214:217], v[4:7]
	v_mfma_f32_16x16x32_bf16 v[0:3], v[174:177], v[214:217], v[0:3]
	s_setprio 0
	s_add_i32 s61, s61, 2
	s_add_u32 s59, s59, 0x100
	s_addc_u32 s60, s60, 0
	s_cmpk_gt_u32 s61, 0x55
	s_mov_b64 s[18:19], s[30:31]
	s_barrier
.LBB0_817:
	v_add_u32_e32 v140, 0x10000, v172
	v_add_u32_e32 v168, 0x14000, v172
	ds_read_b128 v[128:131], v140
	ds_read_b128 v[132:135], v140 offset:1024
	ds_read_b128 v[136:139], v140 offset:2048
	ds_read_b128 v[140:143], v140 offset:3072
	ds_read_b128 v[144:147], v168
	ds_read_b128 v[148:151], v168 offset:1024
	ds_read_b128 v[164:167], v168 offset:2048
	ds_read_b128 v[174:177], v168 offset:3072
	v_lshl_add_u64 v[168:169], s[18:19], 0, v[160:161]
	s_add_i32 m0, s2, 0xc000
	ds_read_b128 v[178:181], v173
	ds_read_b128 v[182:185], v173 offset:1024
	ds_read_b128 v[186:189], v173 offset:2048
	ds_read_b128 v[194:197], v173 offset:3072
	ds_read_b128 v[202:205], v173 offset:4096
	ds_read_b128 v[206:209], v173 offset:5120
	ds_read_b128 v[210:213], v173 offset:6144
	ds_read_b128 v[214:217], v173 offset:7168
	global_load_lds_dwordx4 v[168:169], off
	s_add_i32 m0, s2, 0xe000
	v_lshl_add_u64 v[168:169], s[18:19], 0, v[162:163]
	global_load_lds_dwordx4 v[168:169], off
	s_add_u32 s30, s18, 0x100
	s_addc_u32 s31, s19, 0
	s_add_i32 s24, 0, 0x10000
	s_cmpk_eq_i32 s61, 0x54
	s_cselect_b32 s39, s5, s31
	s_cselect_b32 s38, s4, s30
	s_cselect_b32 s37, s15, s60
	s_cselect_b32 s36, s14, s59
	s_add_i32 s25, 0, 0x14000
	s_waitcnt vmcnt(8)
	s_waitcnt lgkmcnt(0)
	s_barrier
	s_setprio 1
	s_waitcnt lgkmcnt(0)
	v_mfma_f32_16x16x32_bf16 v[124:127], v[128:131], v[178:181], v[124:127]
	v_mfma_f32_16x16x32_bf16 v[120:123], v[136:139], v[178:181], v[120:123]
	v_mfma_f32_16x16x32_bf16 v[108:111], v[128:131], v[186:189], v[108:111]
	v_mfma_f32_16x16x32_bf16 v[104:107], v[136:139], v[186:189], v[104:107]
	v_mfma_f32_16x16x32_bf16 v[92:95], v[128:131], v[202:205], v[92:95]
	v_mfma_f32_16x16x32_bf16 v[88:91], v[136:139], v[202:205], v[88:91]
	v_mfma_f32_16x16x32_bf16 v[76:79], v[128:131], v[210:213], v[76:79]
	v_mfma_f32_16x16x32_bf16 v[72:75], v[136:139], v[210:213], v[72:75]
	v_mfma_f32_16x16x32_bf16 v[124:127], v[132:135], v[182:185], v[124:127]
	v_mfma_f32_16x16x32_bf16 v[120:123], v[140:143], v[182:185], v[120:123]
	v_mfma_f32_16x16x32_bf16 v[108:111], v[132:135], v[194:197], v[108:111]
	v_mfma_f32_16x16x32_bf16 v[104:107], v[140:143], v[194:197], v[104:107]
	v_mfma_f32_16x16x32_bf16 v[92:95], v[132:135], v[206:209], v[92:95]
	v_mfma_f32_16x16x32_bf16 v[88:91], v[140:143], v[206:209], v[88:91]
	v_mfma_f32_16x16x32_bf16 v[76:79], v[132:135], v[214:217], v[76:79]
	v_mfma_f32_16x16x32_bf16 v[72:75], v[140:143], v[214:217], v[72:75]
	s_setprio 0
	s_setprio 1
	v_mfma_f32_16x16x32_bf16 v[116:119], v[144:147], v[178:181], v[116:119]
	v_mfma_f32_16x16x32_bf16 v[112:115], v[164:167], v[178:181], v[112:115]
	v_mfma_f32_16x16x32_bf16 v[100:103], v[144:147], v[186:189], v[100:103]
	v_mfma_f32_16x16x32_bf16 v[96:99], v[164:167], v[186:189], v[96:99]
	v_mfma_f32_16x16x32_bf16 v[84:87], v[144:147], v[202:205], v[84:87]
	v_mfma_f32_16x16x32_bf16 v[80:83], v[164:167], v[202:205], v[80:83]
	v_mfma_f32_16x16x32_bf16 v[68:71], v[144:147], v[210:213], v[68:71]
	v_mfma_f32_16x16x32_bf16 v[64:67], v[164:167], v[210:213], v[64:67]
	v_mfma_f32_16x16x32_bf16 v[116:119], v[148:151], v[182:185], v[116:119]
	v_mfma_f32_16x16x32_bf16 v[112:115], v[174:177], v[182:185], v[112:115]
	v_mfma_f32_16x16x32_bf16 v[100:103], v[148:151], v[194:197], v[100:103]
	v_mfma_f32_16x16x32_bf16 v[96:99], v[174:177], v[194:197], v[96:99]
	v_mfma_f32_16x16x32_bf16 v[84:87], v[148:151], v[206:209], v[84:87]
	v_mfma_f32_16x16x32_bf16 v[80:83], v[174:177], v[206:209], v[80:83]
	v_mfma_f32_16x16x32_bf16 v[68:71], v[148:151], v[214:217], v[68:71]
	v_mfma_f32_16x16x32_bf16 v[64:67], v[174:177], v[214:217], v[64:67]
	s_setprio 0
	s_barrier
; #define PG8_STAGE(bufoff, gbase, voff) do { _Pragma("unroll") for (int _i = 0; _i < 2; ++_i) \
;         __builtin_amdgcn_global_load_lds((const unsigned*)((const char*)(gbase) + (voff)[_i]), (PG8_LAS unsigned*)(lds + (bufoff) + ldsw + _i * 8192), 16, 0, 0); } while (0)
; #define PG8_LDA(dst, b, h) do { _Pragma("unroll") for (int m = 0; m < 4; ++m) _Pragma("unroll") for (int k = 0; k < 2; ++k) dst[m][k] = *(const PG8_LAS bf16x8*)(lds + PG8_SA(b, h) + aoff + m * 2048 + k * 1024); } while (0)
; #define PG8_LDB(dst, b, h) do { _Pragma("unroll") for (int n = 0; n < 2; ++n) _Pragma("unroll") for (int k = 0; k < 2; ++k) dst[n][k] = *(const PG8_LAS bf16x8*)(lds + PG8_SB(b, h) + boff + n * 2048 + k * 1024); } while (0)
; #define PG8_MMA(ai, bj, At, Bt) do { __builtin_amdgcn_s_setprio(1); _Pragma("unroll") for (int m = 0; m < 4; ++m) _Pragma("unroll") for (int n = 0; n < 2; ++n) _Pragma("unroll") for (int k = 0; k < 2; ++k) \
;         acc[ai][bj][m][n] = __builtin_amdgcn_mfma_f32_16x16x32_bf16(Bt[n][k], At[m][k], acc[ai][bj][m][n], 0, 0, 0); __builtin_amdgcn_s_setprio(0); } while (0)
; #define PG8_WAIT_V(n) asm volatile("s_waitcnt vmcnt(" #n ")" ::: "memory")
; #define PG8_WAIT_L(n) asm volatile("s_waitcnt lgkmcnt(" #n ")" ::: "memory")
; #define PG8_BAR __builtin_amdgcn_s_barrier()
; #define PG8_SCHED __builtin_amdgcn_sched_barrier(0)
; template <class Epi, class Sched, bool ALIGN_EPI = false, bool SP2 = false>
; __device__ __forceinline__ void gemm_phase(PG8_LAS unsigned char* lds, const Gemm g, const Sched& S, const Epi& E) {
;     ...
;             PG8_LDA(At, 0, 1); PG8_STAGE(PG8_SB(0, 0), b2, voffB); PG8_STAGE(PG8_SB(0, 1), b2 + hstep, voffB); PG8_STAGE(PG8_SA(0, 0), a2, voffA);
;             PG8_WAIT_V(8); PG8_WAIT_L(0); PG8_BAR; PG8_MMA(1, 0, At, B0); PG8_MMA(1, 1, At, B1); PG8_BAR; PG8_SCHED;
;             PG8_LDB(B0, 1, 0); PG8_LDB(B1, 1, 1); PG8_SCHED; PG8_LDA(At, 1, 0); PG8_STAGE(PG8_SA(0, 1), a2 + hstep, voffA);
	s_add_i32 s18, s24, s43
	v_lshl_add_u64 v[168:169], s[36:37], 0, v[156:157]
	s_mov_b32 m0, s18
	ds_read_b128 v[178:181], v173 offset:16384
	ds_read_b128 v[182:185], v173 offset:17408
	ds_read_b128 v[186:189], v173 offset:18432
	ds_read_b128 v[194:197], v173 offset:19456
	ds_read_b128 v[202:205], v173 offset:20480
	ds_read_b128 v[206:209], v173 offset:21504
	ds_read_b128 v[210:213], v173 offset:22528
	ds_read_b128 v[214:217], v173 offset:23552
	global_load_lds_dwordx4 v[168:169], off
	s_add_i32 m0, s18, 0x2000
	s_add_u32 s18, s36, 0x160000
	v_lshl_add_u64 v[190:191], s[36:37], 0, v[152:153]
	s_addc_u32 s19, s37, 0
	s_add_i32 s24, s25, s43
	global_load_lds_dwordx4 v[190:191], off
	v_lshl_add_u64 v[218:219], s[18:19], 0, v[156:157]
	s_mov_b32 m0, s24
	v_lshl_add_u64 v[220:221], s[38:39], 0, v[154:155]
	global_load_lds_dwordx4 v[218:219], off
	s_add_i32 m0, s24, 0x2000
	v_lshl_add_u64 v[218:219], s[18:19], 0, v[152:153]
	global_load_lds_dwordx4 v[218:219], off
	s_mov_b32 m0, s2
	v_lshl_add_u64 v[218:219], s[38:39], 0, v[158:159]
	global_load_lds_dwordx4 v[218:219], off
	s_mov_b32 m0, s44
	s_nop 0
	global_load_lds_dwordx4 v[220:221], off
	s_waitcnt vmcnt(8)
	s_waitcnt lgkmcnt(0)
	s_barrier
	s_setprio 1
	s_waitcnt lgkmcnt(0)
	v_mfma_f32_16x16x32_bf16 v[60:63], v[128:131], v[178:181], v[60:63]
	v_mfma_f32_16x16x32_bf16 v[56:59], v[136:139], v[178:181], v[56:59]
	v_mfma_f32_16x16x32_bf16 v[44:47], v[128:131], v[186:189], v[44:47]
	v_mfma_f32_16x16x32_bf16 v[40:43], v[136:139], v[186:189], v[40:43]
	v_mfma_f32_16x16x32_bf16 v[28:31], v[128:131], v[202:205], v[28:31]
	v_mfma_f32_16x16x32_bf16 v[24:27], v[136:139], v[202:205], v[24:27]
	v_mfma_f32_16x16x32_bf16 v[12:15], v[128:131], v[210:213], v[12:15]
	v_mfma_f32_16x16x32_bf16 v[8:11], v[136:139], v[210:213], v[8:11]
	v_mfma_f32_16x16x32_bf16 v[60:63], v[132:135], v[182:185], v[60:63]
	v_mfma_f32_16x16x32_bf16 v[56:59], v[140:143], v[182:185], v[56:59]
	v_mfma_f32_16x16x32_bf16 v[44:47], v[132:135], v[194:197], v[44:47]
	v_mfma_f32_16x16x32_bf16 v[40:43], v[140:143], v[194:197], v[40:43]
	v_mfma_f32_16x16x32_bf16 v[28:31], v[132:135], v[206:209], v[28:31]
	v_mfma_f32_16x16x32_bf16 v[24:27], v[140:143], v[206:209], v[24:27]
	v_mfma_f32_16x16x32_bf16 v[12:15], v[132:135], v[214:217], v[12:15]
	v_mfma_f32_16x16x32_bf16 v[8:11], v[140:143], v[214:217], v[8:11]
	s_setprio 0
	s_setprio 1
	v_mfma_f32_16x16x32_bf16 v[52:55], v[144:147], v[178:181], v[52:55]
	v_mfma_f32_16x16x32_bf16 v[48:51], v[164:167], v[178:181], v[48:51]
	v_mfma_f32_16x16x32_bf16 v[36:39], v[144:147], v[186:189], v[36:39]
	v_mfma_f32_16x16x32_bf16 v[32:35], v[164:167], v[186:189], v[32:35]
	v_mfma_f32_16x16x32_bf16 v[20:23], v[144:147], v[202:205], v[20:23]
	v_mfma_f32_16x16x32_bf16 v[16:19], v[164:167], v[202:205], v[16:19]
	v_mfma_f32_16x16x32_bf16 v[4:7], v[144:147], v[210:213], v[4:7]
	v_mfma_f32_16x16x32_bf16 v[0:3], v[164:167], v[210:213], v[0:3]
	v_mfma_f32_16x16x32_bf16 v[52:55], v[148:151], v[182:185], v[52:55]
	v_mfma_f32_16x16x32_bf16 v[48:51], v[174:177], v[182:185], v[48:51]
	v_mfma_f32_16x16x32_bf16 v[36:39], v[148:151], v[194:197], v[36:39]
	v_mfma_f32_16x16x32_bf16 v[32:35], v[174:177], v[194:197], v[32:35]
	v_mfma_f32_16x16x32_bf16 v[20:23], v[148:151], v[206:209], v[20:23]
	v_mfma_f32_16x16x32_bf16 v[16:19], v[174:177], v[206:209], v[16:19]
	v_mfma_f32_16x16x32_bf16 v[4:7], v[148:151], v[214:217], v[4:7]
	v_mfma_f32_16x16x32_bf16 v[0:3], v[174:177], v[214:217], v[0:3]
	s_setprio 0
	s_barrier
	s_add_i32 s24, 0, 0x18000
	s_add_i32 s25, 0, 0x1c000
	v_add_u32_e32 v140, 0x18000, v172
	v_add_u32_e32 v174, 0x1c000, v172
	ds_read_b128 v[128:131], v140
	ds_read_b128 v[132:135], v140 offset:1024
	ds_read_b128 v[136:139], v140 offset:2048
	ds_read_b128 v[140:143], v140 offset:3072
	ds_read_b128 v[144:147], v174
	ds_read_b128 v[148:151], v174 offset:1024
	ds_read_b128 v[164:167], v174 offset:2048
	ds_read_b128 v[174:177], v174 offset:3072
	s_add_u32 s18, s38, 0x160000
	s_addc_u32 s19, s39, 0
	s_mov_b32 m0, s45
	v_lshl_add_u64 v[230:231], s[18:19], 0, v[158:159]
	ds_read_b128 v[178:181], v173 offset:32768
	ds_read_b128 v[182:185], v173 offset:33792
	ds_read_b128 v[186:189], v173 offset:34816
	ds_read_b128 v[194:197], v173 offset:35840
	ds_read_b128 v[202:205], v173 offset:36864
	ds_read_b128 v[206:209], v173 offset:37888
	ds_read_b128 v[210:213], v173 offset:38912
	ds_read_b128 v[214:217], v173 offset:39936
	global_load_lds_dwordx4 v[230:231], off
	s_mov_b32 m0, s46
	v_lshl_add_u64 v[230:231], s[18:19], 0, v[154:155]
	global_load_lds_dwordx4 v[230:231], off
	s_waitcnt vmcnt(8)
	s_waitcnt lgkmcnt(0)
	s_barrier
; #define PG8_STAGE(bufoff, gbase, voff) do { _Pragma("unroll") for (int _i = 0; _i < 2; ++_i) \
;         __builtin_amdgcn_global_load_lds((const unsigned*)((const char*)(gbase) + (voff)[_i]), (PG8_LAS unsigned*)(lds + (bufoff) + ldsw + _i * 8192), 16, 0, 0); } while (0)
; #define PG8_LDA(dst, b, h) do { _Pragma("unroll") for (int m = 0; m < 4; ++m) _Pragma("unroll") for (int k = 0; k < 2; ++k) dst[m][k] = *(const PG8_LAS bf16x8*)(lds + PG8_SA(b, h) + aoff + m * 2048 + k * 1024); } while (0)
; #define PG8_MMA(ai, bj, At, Bt) do { __builtin_amdgcn_s_setprio(1); _Pragma("unroll") for (int m = 0; m < 4; ++m) _Pragma("unroll") for (int n = 0; n < 2; ++n) _Pragma("unroll") for (int k = 0; k < 2; ++k) \
;         acc[ai][bj][m][n] = __builtin_amdgcn_mfma_f32_16x16x32_bf16(Bt[n][k], At[m][k], acc[ai][bj][m][n], 0, 0, 0); __builtin_amdgcn_s_setprio(0); } while (0)
; #define PG8_WAIT_V(n) asm volatile("s_waitcnt vmcnt(" #n ")" ::: "memory")
; #define PG8_WAIT_L(n) asm volatile("s_waitcnt lgkmcnt(" #n ")" ::: "memory")
; #define PG8_BAR __builtin_amdgcn_s_barrier()
; #define PG8_SCHED __builtin_amdgcn_sched_barrier(0)
; template <class Epi, class Sched, bool ALIGN_EPI = false, bool SP2 = false>
; __device__ __forceinline__ void gemm_phase(PG8_LAS unsigned char* lds, const Gemm g, const Sched& S, const Epi& E) {
;     ...
;             PG8_WAIT_V(8); PG8_WAIT_L(0); PG8_BAR; PG8_MMA(0, 0, At, B0); PG8_MMA(0, 1, At, B1); PG8_BAR; PG8_SCHED;
;             PG8_LDA(At, 1, 1); PG8_STAGE(PG8_SB(1, 0), b3, voffB); PG8_STAGE(PG8_SB(1, 1), b3 + hstep, voffB); PG8_STAGE(PG8_SA(1, 0), a3, voffA);
;             PG8_WAIT_V(8); PG8_WAIT_L(0); PG8_BAR; PG8_MMA(1, 0, At, B0); PG8_MMA(1, 1, At, B1); PG8_BAR; PG8_SCHED;
;     ...
;         if constexpr (ALIGN_EPI) { if (wr == 0) PG8_BAR; }
	s_setprio 1
	s_waitcnt lgkmcnt(0)
	v_mfma_f32_16x16x32_bf16 v[124:127], v[128:131], v[178:181], v[124:127]
	v_mfma_f32_16x16x32_bf16 v[120:123], v[136:139], v[178:181], v[120:123]
	v_mfma_f32_16x16x32_bf16 v[108:111], v[128:131], v[186:189], v[108:111]
	v_mfma_f32_16x16x32_bf16 v[104:107], v[136:139], v[186:189], v[104:107]
	v_mfma_f32_16x16x32_bf16 v[92:95], v[128:131], v[202:205], v[92:95]
	v_mfma_f32_16x16x32_bf16 v[88:91], v[136:139], v[202:205], v[88:91]
	v_mfma_f32_16x16x32_bf16 v[76:79], v[128:131], v[210:213], v[76:79]
	v_mfma_f32_16x16x32_bf16 v[72:75], v[136:139], v[210:213], v[72:75]
	v_mfma_f32_16x16x32_bf16 v[124:127], v[132:135], v[182:185], v[124:127]
	v_mfma_f32_16x16x32_bf16 v[120:123], v[140:143], v[182:185], v[120:123]
	v_mfma_f32_16x16x32_bf16 v[108:111], v[132:135], v[194:197], v[108:111]
	v_mfma_f32_16x16x32_bf16 v[104:107], v[140:143], v[194:197], v[104:107]
	v_mfma_f32_16x16x32_bf16 v[92:95], v[132:135], v[206:209], v[92:95]
	v_mfma_f32_16x16x32_bf16 v[88:91], v[140:143], v[206:209], v[88:91]
	v_mfma_f32_16x16x32_bf16 v[76:79], v[132:135], v[214:217], v[76:79]
	v_mfma_f32_16x16x32_bf16 v[72:75], v[140:143], v[214:217], v[72:75]
	s_setprio 0
	s_setprio 1
	v_mfma_f32_16x16x32_bf16 v[116:119], v[144:147], v[178:181], v[116:119]
	v_mfma_f32_16x16x32_bf16 v[112:115], v[164:167], v[178:181], v[112:115]
	v_mfma_f32_16x16x32_bf16 v[100:103], v[144:147], v[186:189], v[100:103]
	v_mfma_f32_16x16x32_bf16 v[96:99], v[164:167], v[186:189], v[96:99]
	v_mfma_f32_16x16x32_bf16 v[84:87], v[144:147], v[202:205], v[84:87]
	v_mfma_f32_16x16x32_bf16 v[80:83], v[164:167], v[202:205], v[80:83]
	v_mfma_f32_16x16x32_bf16 v[68:71], v[144:147], v[210:213], v[68:71]
	v_mfma_f32_16x16x32_bf16 v[64:67], v[164:167], v[210:213], v[64:67]
	v_mfma_f32_16x16x32_bf16 v[116:119], v[148:151], v[182:185], v[116:119]
	v_mfma_f32_16x16x32_bf16 v[112:115], v[174:177], v[182:185], v[112:115]
	v_mfma_f32_16x16x32_bf16 v[100:103], v[148:151], v[194:197], v[100:103]
	v_mfma_f32_16x16x32_bf16 v[96:99], v[174:177], v[194:197], v[96:99]
	v_mfma_f32_16x16x32_bf16 v[84:87], v[148:151], v[206:209], v[84:87]
	v_mfma_f32_16x16x32_bf16 v[80:83], v[174:177], v[206:209], v[80:83]
	v_mfma_f32_16x16x32_bf16 v[68:71], v[148:151], v[214:217], v[68:71]
	v_mfma_f32_16x16x32_bf16 v[64:67], v[174:177], v[214:217], v[64:67]
	s_setprio 0
	s_barrier
	s_add_i32 s18, s24, s43
	v_lshl_add_u64 v[168:169], v[168:169], 0, s[16:17]
	s_mov_b32 m0, s18
	ds_read_b128 v[178:181], v173 offset:49152
	ds_read_b128 v[182:185], v173 offset:50176
	ds_read_b128 v[186:189], v173 offset:51200
	ds_read_b128 v[194:197], v173 offset:52224
	ds_read_b128 v[202:205], v173 offset:53248
	ds_read_b128 v[206:209], v173 offset:54272
	ds_read_b128 v[210:213], v173 offset:55296
	ds_read_b128 v[214:217], v173 offset:56320
	global_load_lds_dwordx4 v[168:169], off
	s_add_i32 m0, s18, 0x2000
	s_add_u32 s18, s36, 0x160080
	v_lshl_add_u64 v[168:169], v[190:191], 0, s[16:17]
	s_addc_u32 s19, s37, 0
	s_add_i32 s24, s25, s43
	global_load_lds_dwordx4 v[168:169], off
	s_mov_b32 m0, s24
	v_lshl_add_u64 v[168:169], s[18:19], 0, v[156:157]
	global_load_lds_dwordx4 v[168:169], off
	s_add_i32 m0, s24, 0x2000
	v_lshl_add_u64 v[168:169], s[18:19], 0, v[152:153]
	global_load_lds_dwordx4 v[168:169], off
	s_mov_b32 m0, s51
	v_lshl_add_u64 v[168:169], v[218:219], 0, s[16:17]
	global_load_lds_dwordx4 v[168:169], off
	s_mov_b32 m0, s52
	v_lshl_add_u64 v[168:169], v[220:221], 0, s[16:17]
	global_load_lds_dwordx4 v[168:169], off
	s_waitcnt vmcnt(8)
	s_waitcnt lgkmcnt(0)
	s_barrier
	s_setprio 1
	s_waitcnt lgkmcnt(0)
	v_mfma_f32_16x16x32_bf16 v[60:63], v[128:131], v[178:181], v[60:63]
	v_mfma_f32_16x16x32_bf16 v[56:59], v[136:139], v[178:181], v[56:59]
	v_mfma_f32_16x16x32_bf16 v[44:47], v[128:131], v[186:189], v[44:47]
	v_mfma_f32_16x16x32_bf16 v[40:43], v[136:139], v[186:189], v[40:43]
	v_mfma_f32_16x16x32_bf16 v[28:31], v[128:131], v[202:205], v[28:31]
	v_mfma_f32_16x16x32_bf16 v[24:27], v[136:139], v[202:205], v[24:27]
	v_mfma_f32_16x16x32_bf16 v[12:15], v[128:131], v[210:213], v[12:15]
	v_mfma_f32_16x16x32_bf16 v[8:11], v[136:139], v[210:213], v[8:11]
	v_mfma_f32_16x16x32_bf16 v[60:63], v[132:135], v[182:185], v[60:63]
	v_mfma_f32_16x16x32_bf16 v[56:59], v[140:143], v[182:185], v[56:59]
	v_mfma_f32_16x16x32_bf16 v[44:47], v[132:135], v[194:197], v[44:47]
	v_mfma_f32_16x16x32_bf16 v[40:43], v[140:143], v[194:197], v[40:43]
	v_mfma_f32_16x16x32_bf16 v[28:31], v[132:135], v[206:209], v[28:31]
	v_mfma_f32_16x16x32_bf16 v[24:27], v[140:143], v[206:209], v[24:27]
	v_mfma_f32_16x16x32_bf16 v[12:15], v[132:135], v[214:217], v[12:15]
	v_mfma_f32_16x16x32_bf16 v[8:11], v[140:143], v[214:217], v[8:11]
	s_setprio 0
	s_setprio 1
	v_mfma_f32_16x16x32_bf16 v[52:55], v[144:147], v[178:181], v[52:55]
	v_mfma_f32_16x16x32_bf16 v[48:51], v[164:167], v[178:181], v[48:51]
	v_mfma_f32_16x16x32_bf16 v[36:39], v[144:147], v[186:189], v[36:39]
	v_mfma_f32_16x16x32_bf16 v[32:35], v[164:167], v[186:189], v[32:35]
	v_mfma_f32_16x16x32_bf16 v[20:23], v[144:147], v[202:205], v[20:23]
	v_mfma_f32_16x16x32_bf16 v[16:19], v[164:167], v[202:205], v[16:19]
	v_mfma_f32_16x16x32_bf16 v[4:7], v[144:147], v[210:213], v[4:7]
	v_mfma_f32_16x16x32_bf16 v[0:3], v[164:167], v[210:213], v[0:3]
	v_mfma_f32_16x16x32_bf16 v[52:55], v[148:151], v[182:185], v[52:55]
	v_mfma_f32_16x16x32_bf16 v[48:51], v[174:177], v[182:185], v[48:51]
	v_mfma_f32_16x16x32_bf16 v[36:39], v[148:151], v[194:197], v[36:39]
	v_mfma_f32_16x16x32_bf16 v[32:35], v[174:177], v[194:197], v[32:35]
	v_mfma_f32_16x16x32_bf16 v[20:23], v[148:151], v[206:209], v[20:23]
	v_mfma_f32_16x16x32_bf16 v[16:19], v[174:177], v[206:209], v[16:19]
	v_mfma_f32_16x16x32_bf16 v[4:7], v[148:151], v[214:217], v[4:7]
	v_mfma_f32_16x16x32_bf16 v[0:3], v[174:177], v[214:217], v[0:3]
	s_setprio 0
	s_add_i32 s61, s61, 2
	s_add_u32 s59, s59, 0x100
	s_addc_u32 s60, s60, 0
	s_cmpk_gt_u32 s61, 0x55
	s_mov_b64 s[18:19], s[30:31]
	s_barrier
	s_cbranch_scc0 .LBB0_817
	s_and_b64 vcc, exec, s[12:13]
	s_cbranch_vccz .LBB0_820
	s_barrier
